# v40 + retout items: 8 Q/K staging loads issued together, LDS writes after one wait
# baseline (speedup 1.0000x reference)
.LBB0_944:
	s_andn2_saveexec_b64 s[2:3], s[2:3]
	s_cbranch_execz .LBB0_946
	v_add_u32_e32 v3, 0xfffff0dc, v2
	v_lshlrev_b32_e32 v0, 5, v3
	v_and_b32_e32 v0, 0x1ff80, v0
	v_mul_u32_u24_e32 v0, 0xea0, v0
	v_lshlrev_b32_e32 v0, 1, v0
	v_and_b32_e32 v2, 3, v2
	v_lshl_add_u64 v[82:83], s[14:15], 0, v[0:1]
	v_lshlrev_b32_e32 v0, 13, v3
	v_mbcnt_lo_u32_b32 v3, -1, 0
	v_mbcnt_hi_u32_b32 v3, -1, v3
	v_readlane_b32 s72, v236, 24
	v_or_b32_e32 v50, s8, v3
	v_lshlrev_b32_e32 v3, 2, v2
	v_readlane_b32 s73, v236, 25
	v_readlane_b32 s74, v236, 26
	v_readlane_b32 s75, v236, 27
	v_ashrrev_i32_e32 v21, 3, v50
	v_lshlrev_b32_e32 v84, 7, v2
	s_nop 0
	global_load_dword v4, v3, s[72:73]
	v_mov_b32_e32 v85, v1
	v_lshlrev_b32_e32 v20, 3, v50
	global_load_dword v3, v3, s[74:75]
	s_waitcnt lgkmcnt(0)
	s_barrier
	v_and_b32_e32 v93, 15, v50
	v_and_b32_e32 v51, 63, v50
	v_ashrrev_i32_e32 v48, 2, v50
	v_bfi_b32 v99, -16, v48, v50
	v_add_u32_e32 v98, 64, v99
	v_readlane_b32 s76, v236, 28
	v_readlane_b32 s77, v236, 29
	v_readlane_b32 s78, v236, 30
	v_readlane_b32 s79, v236, 31
	v_readlane_b32 s80, v236, 32
	v_readlane_b32 s81, v236, 33
	v_readlane_b32 s82, v236, 34
	v_readlane_b32 s83, v236, 35
	v_readlane_b32 s84, v236, 36
	v_readlane_b32 s85, v236, 37
	v_readlane_b32 s86, v236, 38
	v_readlane_b32 s87, v236, 39
	s_waitcnt vmcnt(0)
	v_mul_f32_e32 v5, 0xbfb8aa3b, v4
	v_fma_f32 v6, v4, s55, -v5
	v_rndne_f32_e32 v7, v5
	v_fmac_f32_e32 v6, 0xb2a5705f, v4
	v_sub_f32_e32 v5, v5, v7
	v_add_f32_e32 v5, v5, v6
	v_exp_f32_e32 v5, v5
	v_cvt_i32_f32_e32 v6, v7
	v_cmp_nlt_f32_e32 vcc, s56, v4
	v_ldexp_f32 v5, v5, v6
	s_nop 0
	v_cndmask_b32_e32 v5, 0, v5, vcc
	v_cmp_ngt_f32_e32 vcc, s57, v4
	s_nop 1
	v_cndmask_b32_e32 v18, v160, v5, vcc
	v_add_f32_e32 v6, 1.0, v18
	v_add_f32_e32 v4, -1.0, v6
	v_sub_f32_e32 v5, v4, v6
	v_add_f32_e32 v5, 1.0, v5
	v_sub_f32_e32 v4, v18, v4
	v_add_f32_e32 v7, v4, v5
	v_frexp_mant_f32_e32 v4, v6
	v_cmp_gt_f32_e32 vcc, s59, v4
	v_cvt_f64_f32_e32 v[4:5], v6
	v_frexp_exp_i32_f64_e32 v4, v[4:5]
	v_subbrev_co_u32_e32 v12, vcc, 0, v4, vcc
	v_sub_u32_e32 v4, 0, v12
	v_ldexp_f32 v5, v6, v4
	v_add_f32_e32 v6, -1.0, v5
	v_add_f32_e32 v8, 1.0, v5
	v_ldexp_f32 v4, v7, v4
	v_add_f32_e32 v7, 1.0, v6
	v_add_f32_e32 v9, -1.0, v8
	v_sub_f32_e32 v7, v5, v7
	v_sub_f32_e32 v5, v5, v9
	v_add_f32_e32 v7, v4, v7
	v_add_f32_e32 v4, v4, v5
	v_add_f32_e32 v13, v8, v4
	v_rcp_f32_e32 v15, v13
	v_sub_f32_e32 v5, v8, v13
	v_add_f32_e32 v14, v4, v5
	v_add_f32_e32 v5, v6, v7
	v_mul_f32_e32 v17, v5, v15
	v_sub_f32_e32 v4, v6, v5
	v_mul_f32_e32 v6, v13, v17
	v_fma_f32 v8, v17, v13, -v6
	v_fmac_f32_e32 v8, v17, v14
	v_add_f32_e32 v16, v7, v4
	v_add_f32_e32 v4, v6, v8
	v_sub_f32_e32 v7, v5, v4
	v_pk_add_f32 v[10:11], v[4:5], v[6:7] neg_lo:[0,1] neg_hi:[0,1]
	v_mov_b32_e32 v9, v4
	v_pk_add_f32 v[4:5], v[10:11], v[8:9] neg_lo:[0,1] neg_hi:[0,1]
	v_cmp_neq_f32_e32 vcc, s58, v18
	v_add_f32_e32 v5, v16, v5
	v_add_f32_e32 v4, v4, v5
	v_add_f32_e32 v5, v7, v4
	v_mul_f32_e32 v16, v15, v5
	v_mul_f32_e32 v6, v13, v16
	v_fma_f32 v8, v16, v13, -v6
	v_fmac_f32_e32 v8, v16, v14
	v_sub_f32_e32 v7, v7, v5
	v_add_f32_e32 v13, v4, v7
	v_add_f32_e32 v4, v6, v8
	v_sub_f32_e32 v7, v5, v4
	v_pk_add_f32 v[10:11], v[4:5], v[6:7] neg_lo:[0,1] neg_hi:[0,1]
	v_mov_b32_e32 v9, v4
	v_pk_add_f32 v[4:5], v[10:11], v[8:9] neg_lo:[0,1] neg_hi:[0,1]
	s_nop 0
	v_add_f32_e32 v5, v13, v5
	v_add_f32_e32 v4, v4, v5
	v_add_f32_e32 v5, v17, v16
	v_add_f32_e32 v4, v7, v4
	v_sub_f32_e32 v6, v5, v17
	v_mul_f32_e32 v4, v15, v4
	v_sub_f32_e32 v6, v16, v6
	v_add_f32_e32 v6, v6, v4
	v_add_f32_e32 v8, v5, v6
	v_mul_f32_e32 v9, v8, v8
	v_fmamk_f32 v4, v9, 0x3e9b6dac, v157
	v_fmaak_f32 v123, v9, v4, 0x3f2aaada
	v_cvt_f32_i32_e32 v4, v12
	v_sub_f32_e32 v5, v8, v5
	v_sub_f32_e32 v5, v6, v5
	v_ldexp_f32 v10, v5, 1
	v_mul_f32_e32 v5, v8, v9
	v_ldexp_f32 v7, v8, 1
	v_pk_mul_f32 v[8:9], v[4:5], v[122:123]
	s_nop 0
	v_fma_f32 v6, v4, s60, -v8
	v_fmac_f32_e32 v6, 0xb102e308, v4
	v_pk_add_f32 v[4:5], v[8:9], v[6:7]
	s_nop 0
	v_sub_f32_e32 v7, v5, v7
	v_sub_f32_e32 v7, v9, v7
	v_add_f32_e32 v11, v10, v7
	v_mov_b32_e32 v10, v8
	v_pk_add_f32 v[8:9], v[4:5], v[8:9] neg_lo:[0,1] neg_hi:[0,1]
	v_pk_add_f32 v[12:13], v[4:5], v[10:11]
	v_mov_b32_e32 v7, v4
	v_mov_b32_e32 v9, v13
	v_pk_add_f32 v[14:15], v[6:7], v[8:9] neg_lo:[0,1] neg_hi:[0,1]
	v_pk_add_f32 v[6:7], v[6:7], v[8:9]
	v_mov_b32_e32 v10, v11
	v_pk_add_f32 v[8:9], v[6:7], v[4:5] op_sel:[1,0] op_sel_hi:[0,1] neg_lo:[0,1] neg_hi:[0,1]
	v_pk_add_f32 v[16:17], v[12:13], v[8:9] op_sel_hi:[1,0] neg_lo:[0,1] neg_hi:[0,1]
	v_mov_b32_e32 v12, v13
	v_mov_b32_e32 v13, v7
	v_pk_mov_b32 v[8:9], v[4:5], v[8:9] op_sel:[1,0]
	v_mov_b32_e32 v11, v4
	v_pk_add_f32 v[8:9], v[12:13], v[8:9] neg_lo:[0,1] neg_hi:[0,1]
	v_mov_b32_e32 v16, v14
	v_pk_add_f32 v[4:5], v[10:11], v[8:9] neg_lo:[0,1] neg_hi:[0,1]
	v_mov_b32_e32 v15, v7
	v_pk_add_f32 v[8:9], v[16:17], v[4:5]
	s_nop 0
	v_pk_add_f32 v[10:11], v[8:9], v[8:9] op_sel:[0,1] op_sel_hi:[1,0]
	s_nop 0
	v_pk_add_f32 v[6:7], v[6:7], v[10:11] op_sel:[1,0] op_sel_hi:[0,1]
	v_mov_b32_e32 v9, v6
	v_pk_add_f32 v[12:13], v[8:9], v[14:15] neg_lo:[0,1] neg_hi:[0,1]
	v_mov_b32_e32 v5, v10
	v_sub_f32_e32 v7, v8, v12
	v_pk_add_f32 v[4:5], v[4:5], v[12:13] neg_lo:[0,1] neg_hi:[0,1]
	v_sub_f32_e32 v7, v14, v7
	v_add_f32_e32 v4, v4, v7
	v_add_f32_e32 v4, v4, v5
	v_add_f32_e32 v4, v6, v4
	v_cndmask_b32_e32 v4, v160, v4, vcc
	v_cmp_lt_f32_e64 vcc, |v18|, s61
	s_nop 1
	v_cndmask_b32_e32 v96, v4, v18, vcc
	v_mul_f32_e32 v4, 0xbfb8aa3b, v3
	v_fma_f32 v5, v3, s55, -v4
	v_rndne_f32_e32 v6, v4
	v_fmac_f32_e32 v5, 0xb2a5705f, v3
	v_sub_f32_e32 v4, v4, v6
	v_add_f32_e32 v4, v4, v5
	v_exp_f32_e32 v4, v4
	v_cvt_i32_f32_e32 v5, v6
	v_cmp_nlt_f32_e32 vcc, s56, v3
	v_ldexp_f32 v4, v4, v5
	s_nop 0
	v_cndmask_b32_e32 v4, 0, v4, vcc
	v_cmp_ngt_f32_e32 vcc, s57, v3
	s_nop 1
	v_cndmask_b32_e32 v3, v160, v4, vcc
	v_add_f32_e32 v6, 1.0, v3
	v_add_f32_e32 v4, -1.0, v6
	v_sub_f32_e32 v5, v4, v6
	v_add_f32_e32 v5, 1.0, v5
	v_sub_f32_e32 v4, v3, v4
	v_add_f32_e32 v7, v4, v5
	v_frexp_mant_f32_e32 v4, v6
	v_cmp_gt_f32_e32 vcc, s59, v4
	v_cvt_f64_f32_e32 v[4:5], v6
	v_frexp_exp_i32_f64_e32 v4, v[4:5]
	v_subbrev_co_u32_e32 v12, vcc, 0, v4, vcc
	v_sub_u32_e32 v4, 0, v12
	v_ldexp_f32 v5, v6, v4
	v_add_f32_e32 v6, -1.0, v5
	v_add_f32_e32 v8, 1.0, v5
	v_ldexp_f32 v4, v7, v4
	v_add_f32_e32 v7, 1.0, v6
	v_add_f32_e32 v9, -1.0, v8
	v_sub_f32_e32 v7, v5, v7
	v_sub_f32_e32 v5, v5, v9
	v_add_f32_e32 v7, v4, v7
	v_add_f32_e32 v4, v4, v5
	v_add_f32_e32 v13, v8, v4
	v_rcp_f32_e32 v15, v13
	v_sub_f32_e32 v5, v8, v13
	v_add_f32_e32 v14, v4, v5
	v_add_f32_e32 v5, v6, v7
	v_mul_f32_e32 v17, v5, v15
	v_sub_f32_e32 v4, v6, v5
	v_mul_f32_e32 v6, v13, v17
	v_fma_f32 v8, v17, v13, -v6
	v_fmac_f32_e32 v8, v17, v14
	v_add_f32_e32 v16, v7, v4
	v_add_f32_e32 v4, v6, v8
	v_sub_f32_e32 v7, v5, v4
	v_pk_add_f32 v[10:11], v[4:5], v[6:7] neg_lo:[0,1] neg_hi:[0,1]
	v_mov_b32_e32 v9, v4
	v_pk_add_f32 v[4:5], v[10:11], v[8:9] neg_lo:[0,1] neg_hi:[0,1]
	v_cmp_neq_f32_e32 vcc, s58, v3
	v_add_f32_e32 v5, v16, v5
	v_add_f32_e32 v4, v4, v5
	v_add_f32_e32 v5, v7, v4
	v_mul_f32_e32 v16, v15, v5
	v_mul_f32_e32 v6, v13, v16
	v_fma_f32 v8, v16, v13, -v6
	v_fmac_f32_e32 v8, v16, v14
	v_sub_f32_e32 v7, v7, v5
	v_add_f32_e32 v13, v4, v7
	v_add_f32_e32 v4, v6, v8
	v_sub_f32_e32 v7, v5, v4
	v_pk_add_f32 v[10:11], v[4:5], v[6:7] neg_lo:[0,1] neg_hi:[0,1]
	v_mov_b32_e32 v9, v4
	v_pk_add_f32 v[4:5], v[10:11], v[8:9] neg_lo:[0,1] neg_hi:[0,1]
	s_nop 0
	v_add_f32_e32 v5, v13, v5
	v_add_f32_e32 v4, v4, v5
	v_add_f32_e32 v5, v17, v16
	v_add_f32_e32 v4, v7, v4
	v_sub_f32_e32 v6, v5, v17
	v_mul_f32_e32 v4, v15, v4
	v_sub_f32_e32 v6, v16, v6
	v_add_f32_e32 v6, v6, v4
	v_add_f32_e32 v8, v5, v6
	v_mul_f32_e32 v9, v8, v8
	v_fmamk_f32 v4, v9, 0x3e9b6dac, v157
	v_fmaak_f32 v123, v9, v4, 0x3f2aaada
	v_cvt_f32_i32_e32 v4, v12
	v_sub_f32_e32 v5, v8, v5
	v_sub_f32_e32 v5, v6, v5
	v_ldexp_f32 v10, v5, 1
	v_mul_f32_e32 v5, v8, v9
	v_ldexp_f32 v7, v8, 1
	v_pk_mul_f32 v[8:9], v[4:5], v[122:123]
	s_nop 0
	v_fma_f32 v6, v4, s60, -v8
	v_fmac_f32_e32 v6, 0xb102e308, v4
	v_pk_add_f32 v[4:5], v[8:9], v[6:7]
	s_nop 0
	v_sub_f32_e32 v7, v5, v7
	v_sub_f32_e32 v7, v9, v7
	v_add_f32_e32 v11, v10, v7
	v_mov_b32_e32 v10, v8
	v_pk_add_f32 v[8:9], v[4:5], v[8:9] neg_lo:[0,1] neg_hi:[0,1]
	v_pk_add_f32 v[12:13], v[4:5], v[10:11]
	v_mov_b32_e32 v7, v4
	v_mov_b32_e32 v9, v13
	v_pk_add_f32 v[14:15], v[6:7], v[8:9] neg_lo:[0,1] neg_hi:[0,1]
	v_pk_add_f32 v[6:7], v[6:7], v[8:9]
	v_mov_b32_e32 v10, v11
	v_pk_add_f32 v[8:9], v[6:7], v[4:5] op_sel:[1,0] op_sel_hi:[0,1] neg_lo:[0,1] neg_hi:[0,1]
	v_pk_add_f32 v[16:17], v[12:13], v[8:9] op_sel_hi:[1,0] neg_lo:[0,1] neg_hi:[0,1]
	v_mov_b32_e32 v12, v13
	v_mov_b32_e32 v13, v7
	v_pk_mov_b32 v[8:9], v[4:5], v[8:9] op_sel:[1,0]
	v_mov_b32_e32 v11, v4
	v_pk_add_f32 v[8:9], v[12:13], v[8:9] neg_lo:[0,1] neg_hi:[0,1]
	v_mov_b32_e32 v16, v14
	v_pk_add_f32 v[4:5], v[10:11], v[8:9] neg_lo:[0,1] neg_hi:[0,1]
	v_mov_b32_e32 v15, v7
	v_pk_add_f32 v[8:9], v[16:17], v[4:5]
	s_nop 0
	v_pk_add_f32 v[10:11], v[8:9], v[8:9] op_sel:[0,1] op_sel_hi:[1,0]
	s_nop 0
	v_pk_add_f32 v[6:7], v[6:7], v[10:11] op_sel:[1,0] op_sel_hi:[0,1]
	v_mov_b32_e32 v9, v6
	v_pk_add_f32 v[12:13], v[8:9], v[14:15] neg_lo:[0,1] neg_hi:[0,1]
	v_mov_b32_e32 v5, v10
	v_sub_f32_e32 v7, v8, v12
	v_pk_add_f32 v[4:5], v[4:5], v[12:13] neg_lo:[0,1] neg_hi:[0,1]
	v_sub_f32_e32 v7, v14, v7
	v_add_f32_e32 v4, v4, v7
	v_add_f32_e32 v4, v4, v5
	v_add_f32_e32 v4, v6, v4
	v_cndmask_b32_e32 v4, v160, v4, vcc
	v_cmp_lt_f32_e64 vcc, |v3|, s61
	v_mov_b32_e32 v11, v1
	s_nop 0
	v_cndmask_b32_e32 v97, v4, v3, vcc
	v_lshlrev_b32_e32 v3, 4, v50
	v_mad_i64_i32 v[4:5], s[6:7], v21, s52, v[82:83]
	v_and_b32_e32 v10, 0x70, v3
	v_lshl_add_u64 v[2:3], v[4:5], 0, v[84:85]
	v_lshl_add_u64 v[6:7], v[2:3], 0, v[10:11]
	global_load_dwordx4 v[172:175], v[6:7], off
	v_add_u32_e32 v12, s92, v10
	v_mad_u64_u32 v[8:9], s[6:7], v21, s62, v[12:13]
	s_nop 0
	v_mov_b32_e32 v206, v8
	global_load_dwordx4 v[176:179], v[6:7], off offset:512
	s_nop 0
	v_mov_b32_e32 v207, v8
	v_add_u32_e32 v8, 0x100, v50
	v_ashrrev_i32_e32 v9, 3, v8
	v_mad_i64_i32 v[2:3], s[6:7], v9, s52, v[82:83]
	v_lshl_add_u64 v[2:3], v[2:3], 0, v[84:85]
	v_lshl_add_u64 v[6:7], v[2:3], 0, v[10:11]
	global_load_dwordx4 v[180:183], v[6:7], off
	v_mad_u64_u32 v[14:15], s[6:7], v9, s62, v[12:13]
	s_nop 0
	v_mov_b32_e32 v208, v14
	global_load_dwordx4 v[184:187], v[6:7], off offset:512
	v_add_u32_e32 v7, 0x200, v50
	v_add_u32_e32 v6, 0x300, v50
	s_nop 0
	v_mov_b32_e32 v209, v14
	v_ashrrev_i32_e32 v4, 3, v7
	v_mad_i64_i32 v[2:3], s[6:7], v4, s52, v[82:83]
	v_lshl_add_u64 v[2:3], v[2:3], 0, v[84:85]
	v_lshl_add_u64 v[14:15], v[2:3], 0, v[10:11]
	v_mad_u64_u32 v[16:17], s[6:7], v4, s62, v[12:13]
	global_load_dwordx4 v[188:191], v[14:15], off
	v_ashrrev_i32_e32 v7, 4, v7
	s_nop 0
	v_mov_b32_e32 v210, v16
	global_load_dwordx4 v[192:195], v[14:15], off offset:512
	s_nop 0
	v_mov_b32_e32 v211, v16
	v_ashrrev_i32_e32 v4, 3, v6
	v_mad_i64_i32 v[2:3], s[6:7], v4, s52, v[82:83]
	v_lshl_add_u64 v[2:3], v[2:3], 0, v[84:85]
	v_lshl_add_u64 v[10:11], v[2:3], 0, v[10:11]
	v_mad_u64_u32 v[12:13], s[6:7], v4, s62, v[12:13]
	global_load_dwordx4 v[196:199], v[10:11], off
	s_mov_b64 s[6:7], 0x2140
	s_nop 0
	v_mov_b32_e32 v212, v12
	global_load_dwordx4 v[200:203], v[10:11], off offset:512
	v_and_b32_e32 v10, 48, v20
	v_and_b32_e32 v20, -8, v21
	v_ashrrev_i32_e32 v21, 31, v20
	v_and_b32_e32 v11, 8, v50
	v_lshlrev_b64 v[14:15], 1, v[20:21]
	s_waitcnt vmcnt(0) lgkmcnt(0)
	ds_write_b128 v206, v[172:175]
	ds_write_b128 v207, v[176:179] offset:18432
	ds_write_b128 v208, v[180:183]
	ds_write_b128 v209, v[184:187] offset:18432
	ds_write_b128 v210, v[188:191]
	ds_write_b128 v211, v[192:195] offset:18432
	ds_write_b128 v212, v[196:199]
	ds_write_b128 v12, v[200:203] offset:18432
	v_lshlrev_b32_e32 v2, 1, v50
	v_and_b32_e32 v2, 0x7e, v2
	v_mul_u32_u24_e32 v2, 0xea0, v2
	v_lshlrev_b32_e32 v2, 1, v2
	v_mov_b32_e32 v3, v1
	v_lshlrev_b32_e32 v5, 2, v50
	v_lshl_add_u64 v[2:3], v[82:83], 0, v[2:3]
	v_and_b32_e32 v4, 0xc4, v5
	v_lshl_add_u64 v[18:19], v[2:3], 0, v[84:85]
	v_add_u32_e32 v4, s92, v4
	v_lshl_add_u64 v[2:3], v[18:19], 0, s[6:7]
	v_add3_u32 v4, v4, v10, v11
	v_lshl_add_u64 v[10:11], v[18:19], 0, v[14:15]
	global_load_dwordx4 v[10:13], v[10:11], off offset:1024
	v_lshl_add_u64 v[14:15], v[2:3], 0, v[14:15]
	global_load_dwordx4 v[14:17], v[14:15], off
	s_waitcnt vmcnt(0) lgkmcnt(0)
	v_and_b32_e32 v21, 0xffff, v10
	v_lshrrev_b32_e32 v10, 16, v10
	v_lshl_or_b32 v22, v14, 16, v21
	v_mad_u64_u32 v[20:21], s[6:7], v20, s64, v[4:5]
	v_and_or_b32 v10, v14, s54, v10
	v_add_u32_e32 v14, 0x9000, v20
	ds_write2_b32 v14, v22, v10 offset1:68
	v_and_b32_e32 v10, 0xffff, v11
	v_lshrrev_b32_e32 v11, 16, v11
	v_lshl_or_b32 v10, v15, 16, v10
	v_and_or_b32 v11, v15, s54, v11
	ds_write2_b32 v14, v10, v11 offset0:136 offset1:204
	v_and_b32_e32 v10, 0xffff, v12
	v_lshrrev_b32_e32 v11, 16, v12
	v_lshl_or_b32 v10, v16, 16, v10
	v_and_or_b32 v11, v16, s54, v11
	v_add_u32_e32 v12, 0x9400, v20
	v_and_b32_e32 v20, -8, v9
	ds_write2_b32 v12, v10, v11 offset0:16 offset1:84
	v_and_b32_e32 v10, 0xffff, v13
	v_lshrrev_b32_e32 v11, 16, v13
	v_ashrrev_i32_e32 v21, 31, v20
	v_lshl_or_b32 v10, v17, 16, v10
	v_and_or_b32 v11, v17, s54, v11
	v_lshlrev_b64 v[14:15], 1, v[20:21]
	ds_write2_b32 v12, v10, v11 offset0:152 offset1:220
	v_lshl_add_u64 v[10:11], v[18:19], 0, v[14:15]
	global_load_dwordx4 v[10:13], v[10:11], off offset:1024
	v_lshl_add_u64 v[2:3], v[2:3], 0, v[14:15]
	global_load_dwordx4 v[14:17], v[2:3], off
	s_waitcnt vmcnt(0) lgkmcnt(0)
	v_and_b32_e32 v2, 0xffff, v10
	v_lshl_or_b32 v9, v14, 16, v2
	v_mad_u64_u32 v[2:3], s[6:7], v20, s64, v[4:5]
	v_lshrrev_b32_e32 v3, 16, v10
	v_and_or_b32 v3, v14, s54, v3
	v_add_u32_e32 v4, 0x9000, v2
	ds_write2_b32 v4, v9, v3 offset1:68
	v_and_b32_e32 v3, 0xffff, v11
	v_lshrrev_b32_e32 v9, 16, v11
	v_lshl_or_b32 v3, v15, 16, v3
	v_and_or_b32 v9, v15, s54, v9
	ds_write2_b32 v4, v3, v9 offset0:136 offset1:204
	v_and_b32_e32 v3, 0xffff, v12
	v_lshrrev_b32_e32 v4, 16, v12
	v_lshl_or_b32 v3, v16, 16, v3
	v_and_or_b32 v4, v16, s54, v4
	v_add_u32_e32 v2, 0x9400, v2
	ds_write2_b32 v2, v3, v4 offset0:16 offset1:84
	v_and_b32_e32 v3, 0xffff, v13
	v_lshrrev_b32_e32 v4, 16, v13
	v_lshl_or_b32 v3, v17, 16, v3
	v_and_or_b32 v4, v17, s54, v4
	v_and_b32_e32 v9, 60, v5
	ds_write2_b32 v2, v3, v4 offset0:152 offset1:220
	v_lshl_add_u64 v[2:3], v[0:1], 2, s[18:19]
	v_lshlrev_b32_e32 v0, 2, v9
	v_lshl_add_u64 v[2:3], v[2:3], 0, v[0:1]
	v_lshl_add_u32 v0, v9, 1, s92
	v_ashrrev_i32_e32 v9, 4, v50
	v_lshlrev_b32_e32 v10, 6, v9
	s_mov_b64 s[6:7], 0x4000
	v_ashrrev_i32_e32 v11, 31, v10
	v_lshl_add_u64 v[4:5], v[2:3], 0, s[6:7]
	v_lshlrev_b64 v[14:15], 2, v[10:11]
	v_lshl_add_u64 v[10:11], v[2:3], 0, v[14:15]
	v_lshl_add_u64 v[14:15], v[4:5], 0, v[14:15]
	global_load_dwordx4 v[10:13], v[10:11], off
	s_nop 0
	global_load_dwordx4 v[14:17], v[14:15], off
	s_waitcnt vmcnt(0) lgkmcnt(0)
	v_cvt_pk_bf16_f32 v10, v10, v11
	v_cvt_pk_bf16_f32 v11, v12, v13
	v_cvt_pk_bf16_f32 v14, v14, v15
	v_cvt_pk_bf16_f32 v15, v16, v17
	v_ashrrev_i32_e32 v16, 4, v8
	v_lshlrev_b32_e32 v8, 6, v16
	v_mad_u64_u32 v[12:13], s[6:7], v9, s62, v[0:1]
	v_ashrrev_i32_e32 v9, 31, v8
	ds_write2st64_b64 v12, v[10:11], v[14:15] offset0:106 offset1:124
	v_lshlrev_b64 v[12:13], 2, v[8:9]
	v_lshl_add_u64 v[8:9], v[2:3], 0, v[12:13]
	v_lshl_add_u64 v[12:13], v[4:5], 0, v[12:13]
	global_load_dwordx4 v[8:11], v[8:9], off
	s_nop 0
	global_load_dwordx4 v[12:15], v[12:13], off
	s_waitcnt vmcnt(0) lgkmcnt(0)
	v_cvt_pk_bf16_f32 v8, v8, v9
	v_cvt_pk_bf16_f32 v9, v10, v11
	v_mad_u64_u32 v[10:11], s[6:7], v16, s62, v[0:1]
	v_cvt_pk_bf16_f32 v12, v12, v13
	v_cvt_pk_bf16_f32 v13, v14, v15
	ds_write2st64_b64 v10, v[8:9], v[12:13] offset0:106 offset1:124
	v_lshlrev_b32_e32 v8, 6, v7
	v_ashrrev_i32_e32 v9, 31, v8
	v_lshlrev_b64 v[12:13], 2, v[8:9]
	v_lshl_add_u64 v[8:9], v[2:3], 0, v[12:13]
	v_lshl_add_u64 v[12:13], v[4:5], 0, v[12:13]
	global_load_dwordx4 v[8:11], v[8:9], off
	s_nop 0
	global_load_dwordx4 v[12:15], v[12:13], off
	s_waitcnt vmcnt(0) lgkmcnt(0)
	v_cvt_pk_bf16_f32 v8, v8, v9
	v_cvt_pk_bf16_f32 v9, v10, v11
	v_mad_u64_u32 v[10:11], s[6:7], v7, s62, v[0:1]
	v_cvt_pk_bf16_f32 v12, v12, v13
	v_cvt_pk_bf16_f32 v13, v14, v15
	ds_write2st64_b64 v10, v[8:9], v[12:13] offset0:106 offset1:124
	v_ashrrev_i32_e32 v12, 4, v6
	v_lshlrev_b32_e32 v6, 6, v12
	v_ashrrev_i32_e32 v7, 31, v6
	v_lshlrev_b64 v[10:11], 2, v[6:7]
	v_lshl_add_u64 v[2:3], v[2:3], 0, v[10:11]
	global_load_dwordx4 v[6:9], v[2:3], off
	v_lshl_add_u64 v[2:3], v[4:5], 0, v[10:11]
	global_load_dwordx4 v[2:5], v[2:3], off
	v_and_b32_e32 v14, 48, v50
	s_waitcnt vmcnt(0) lgkmcnt(0)
	v_cvt_pk_bf16_f32 v6, v6, v7
	v_cvt_pk_bf16_f32 v7, v8, v9
	v_mad_u64_u32 v[8:9], s[6:7], v12, s62, v[0:1]
	v_cvt_pk_bf16_f32 v2, v2, v3
	v_cvt_pk_bf16_f32 v3, v4, v5
	v_mul_u32_u24_e32 v0, 0x48, v93
	ds_write2st64_b64 v8, v[6:7], v[2:3] offset0:106 offset1:124
	v_lshlrev_b32_e32 v2, 1, v0
	v_add_u32_e32 v0, s92, v14
	v_and_b32_e32 v12, -16, v48
	v_add_u32_e32 v13, s92, v2
	v_add_u32_e32 v88, v0, v2
	v_or_b32_e32 v2, 48, v51
	v_mul_u32_u24_e32 v2, 0x48, v2
	v_mul_lo_u32 v12, v12, s62
	v_lshl_add_u32 v89, v2, 1, v0
	v_mov_b32_e32 v2, v1
	v_mov_b32_e32 v6, v1
	v_add3_u32 v90, v13, v14, v12
	s_waitcnt lgkmcnt(0)
	s_barrier
	ds_read_b128 v[12:15], v90
	ds_read_b128 v[16:19], v88 offset:54272
	ds_read_b128 v[20:23], v88 offset:56576
	ds_read_b128 v[24:27], v88 offset:58880
	ds_read_b128 v[28:31], v89 offset:54272
	v_mov_b32_e32 v3, v2
	v_mov_b32_e32 v4, v2
	v_mov_b32_e32 v5, v2
	v_add_u32_e32 v11, 0xf800, v88
	v_mov_b32_e32 v7, v6
	s_waitcnt lgkmcnt(3)
	v_mfma_f32_16x16x32_bf16 v[16:19], v[16:19], v[12:15], v[2:5]
	v_mov_b32_e32 v8, v6
	v_mov_b32_e32 v9, v6
	v_add_u32_e32 v10, 0xf840, v88
	s_waitcnt lgkmcnt(2)
	v_mfma_f32_16x16x32_bf16 v[20:23], v[20:23], v[12:15], v[2:5]
	v_or_b32_e32 v51, 0x70, v51
	v_mul_u32_u24_e32 v51, 0x48, v51
	v_lshl_add_u32 v92, v51, 1, v0
	s_waitcnt lgkmcnt(1)
	v_mfma_f32_16x16x32_bf16 v[24:27], v[24:27], v[12:15], v[2:5]
	v_lshrrev_b32_e32 v0, 2, v50
	v_mov_b32_e32 v50, v1
	v_and_b32_e32 v91, 12, v0
	s_waitcnt lgkmcnt(0)
	v_mfma_f32_16x16x32_bf16 v[2:5], v[28:31], v[12:15], v[2:5]
	ds_read_b128 v[28:31], v90 offset:64
	ds_read_b128 v[32:35], v88 offset:54336
	ds_read_b128 v[36:39], v88 offset:56640
	ds_read_b128 v[40:43], v88 offset:58944
	ds_read_b128 v[44:47], v89 offset:54336
	v_sub_u32_e32 v0, v99, v91
	v_sub_u32_e32 v86, 0, v0
	s_waitcnt lgkmcnt(3)
	v_mfma_f32_16x16x32_bf16 v[16:19], v[32:35], v[28:31], v[16:19]
	v_max_i32_e32 v0, v0, v86
	v_cvt_f32_u32_e32 v0, v0
	v_cmp_lt_i32_e32 vcc, v99, v91
	s_waitcnt lgkmcnt(2)
	v_mfma_f32_16x16x32_bf16 v[20:23], v[36:39], v[28:31], v[20:23]
	v_or_b32_e32 v94, 16, v91
	v_cndmask_b32_e32 v86, v96, v97, vcc
	v_mul_f32_e32 v0, v86, v0
	s_waitcnt lgkmcnt(1)
	v_mfma_f32_16x16x32_bf16 v[24:27], v[40:43], v[28:31], v[24:27]
	v_mul_f32_e32 v0, 0xbfb8aa3b, v0
	v_exp_f32_e32 v86, v0
	v_cmp_gt_i32_e32 vcc, v99, v91
	s_waitcnt lgkmcnt(0)
	v_mfma_f32_16x16x32_bf16 v[2:5], v[44:47], v[28:31], v[2:5]
	ds_read_b128 v[32:35], v88 offset:63488
	ds_read_b128 v[36:39], v11 offset:2304
	ds_read_b128 v[40:43], v11 offset:4608
	ds_read_b128 v[44:47], v89 offset:63488
	v_or_b32_e32 v95, 17, v91
	v_or_b32_e32 v120, 0x53, v91
	s_waitcnt lgkmcnt(3)
	v_mfma_f32_16x16x32_bf16 v[32:35], v[32:35], v[12:15], v[6:9]
	v_or_b32_e32 v121, 0x60, v91
	v_or_b32_e32 v123, 0x61, v91
	s_waitcnt lgkmcnt(2)
	v_mfma_f32_16x16x32_bf16 v[36:39], v[36:39], v[12:15], v[6:9]
	s_waitcnt lgkmcnt(1)
	v_mfma_f32_16x16x32_bf16 v[40:43], v[40:43], v[12:15], v[6:9]
	s_waitcnt lgkmcnt(0)
	v_mfma_f32_16x16x32_bf16 v[6:9], v[44:47], v[12:15], v[6:9]
	ds_read_b128 v[12:15], v88 offset:63552
	ds_read_b128 v[44:47], v10 offset:2304
	ds_read_b128 v[52:55], v10 offset:4608
	ds_read_b128 v[56:59], v89 offset:63552
	s_waitcnt lgkmcnt(3)
	v_mfma_f32_16x16x32_bf16 v[12:15], v[12:15], v[28:31], v[32:35]
	s_waitcnt lgkmcnt(2)
	v_mfma_f32_16x16x32_bf16 v[44:47], v[44:47], v[28:31], v[36:39]
	s_waitcnt lgkmcnt(1)
	v_mfma_f32_16x16x32_bf16 v[52:55], v[52:55], v[28:31], v[40:43]
	s_waitcnt lgkmcnt(0)
	v_mfma_f32_16x16x32_bf16 v[6:9], v[56:59], v[28:31], v[6:9]
	v_sub_u32_e32 v29, 0x80, v99
	v_add_u32_e32 v28, 1, v99
	v_cvt_f32_i32_e32 v29, v29
	v_cvt_f32_i32_e32 v28, v28
	v_mul_f32_e32 v29, v29, v97
	v_mul_f32_e32 v28, v28, v96
	v_mul_f32_e32 v29, 0xbfb8aa3b, v29
	v_mul_f32_e32 v28, 0xbfb8aa3b, v28
	v_exp_f32_e32 v30, v29
	v_exp_f32_e32 v28, v28
	v_pk_mul_f32 v[12:13], v[30:31], v[12:13] op_sel_hi:[0,1]
	v_pk_mul_f32 v[14:15], v[30:31], v[14:15] op_sel_hi:[0,1]
	v_pk_fma_f32 v[34:35], v[28:29], v[16:17], v[12:13] op_sel_hi:[0,1,1]
	v_pk_mul_f32 v[12:13], v[30:31], v[44:45] op_sel_hi:[0,1]
	v_pk_fma_f32 v[36:37], v[28:29], v[18:19], v[14:15] op_sel_hi:[0,1,1]
	v_pk_mul_f32 v[14:15], v[30:31], v[46:47] op_sel_hi:[0,1]
	v_pk_fma_f32 v[38:39], v[28:29], v[20:21], v[12:13] op_sel_hi:[0,1,1]
	v_pk_mul_f32 v[12:13], v[30:31], v[52:53] op_sel_hi:[0,1]
	v_pk_mul_f32 v[6:7], v[30:31], v[6:7] op_sel_hi:[0,1]
	v_pk_fma_f32 v[40:41], v[28:29], v[22:23], v[14:15] op_sel_hi:[0,1,1]
	v_pk_mul_f32 v[14:15], v[30:31], v[54:55] op_sel_hi:[0,1]
	v_pk_fma_f32 v[42:43], v[28:29], v[24:25], v[12:13] op_sel_hi:[0,1,1]
	v_pk_mul_f32 v[8:9], v[30:31], v[8:9] op_sel_hi:[0,1]
	v_pk_fma_f32 v[46:47], v[28:29], v[2:3], v[6:7] op_sel_hi:[0,1,1]
	v_mov_b32_e32 v2, v1
	v_mov_b32_e32 v12, v1
	v_pk_fma_f32 v[44:45], v[28:29], v[26:27], v[14:15] op_sel_hi:[0,1,1]
	v_pk_fma_f32 v[48:49], v[28:29], v[4:5], v[8:9] op_sel_hi:[0,1,1]
	ds_read_b128 v[22:25], v90 offset:9216
	ds_read_b128 v[6:9], v88 offset:54272
	ds_read_b128 v[16:19], v88 offset:56576
	ds_read_b128 v[26:29], v88 offset:58880
	ds_read_b128 v[30:33], v89 offset:54272
	v_mov_b32_e32 v3, v2
	v_mov_b32_e32 v4, v2
	v_mov_b32_e32 v5, v2
	v_mov_b32_e32 v13, v12
	v_mov_b32_e32 v14, v12
	s_waitcnt lgkmcnt(3)
	v_mfma_f32_16x16x32_bf16 v[6:9], v[6:9], v[22:25], v[2:5]
	v_mov_b32_e32 v15, v12
	s_waitcnt lgkmcnt(2)
	v_mfma_f32_16x16x32_bf16 v[16:19], v[16:19], v[22:25], v[2:5]
	s_waitcnt lgkmcnt(1)
	v_mfma_f32_16x16x32_bf16 v[26:29], v[26:29], v[22:25], v[2:5]
	s_waitcnt lgkmcnt(0)
	v_mfma_f32_16x16x32_bf16 v[30:33], v[30:33], v[22:25], v[2:5]
	ds_read_b128 v[52:55], v90 offset:9280
	s_nop 1
	ds_read_b128 v[2:5], v88 offset:54336
	ds_read_b128 v[56:59], v88 offset:56640
	ds_read_b128 v[60:63], v88 offset:58944
	ds_read_b128 v[64:67], v89 offset:54336
	s_waitcnt lgkmcnt(3)
	v_mfma_f32_16x16x32_bf16 v[2:5], v[2:5], v[52:55], v[6:9]
	s_waitcnt lgkmcnt(2)
	v_mfma_f32_16x16x32_bf16 v[6:9], v[56:59], v[52:55], v[16:19]
	s_waitcnt lgkmcnt(1)
	v_mfma_f32_16x16x32_bf16 v[18:21], v[60:63], v[52:55], v[26:29]
	s_waitcnt lgkmcnt(0)
	v_mfma_f32_16x16x32_bf16 v[26:29], v[64:67], v[52:55], v[30:33]
	s_nop 2
	ds_read_b128 v[30:33], v88 offset:63488
	ds_read_b128 v[56:59], v11 offset:2304
	ds_read_b128 v[60:63], v11 offset:4608
	ds_read_b128 v[64:67], v89 offset:63488
	s_waitcnt lgkmcnt(3)
	v_mfma_f32_16x16x32_bf16 v[30:33], v[30:33], v[22:25], v[12:15]
	s_waitcnt lgkmcnt(2)
	v_mfma_f32_16x16x32_bf16 v[56:59], v[56:59], v[22:25], v[12:15]
	s_waitcnt lgkmcnt(1)
	v_mfma_f32_16x16x32_bf16 v[60:63], v[60:63], v[22:25], v[12:15]
	s_waitcnt lgkmcnt(0)
	v_mfma_f32_16x16x32_bf16 v[64:67], v[64:67], v[22:25], v[12:15]
	s_nop 2
	ds_read_b128 v[12:15], v88 offset:63552
	ds_read_b128 v[22:25], v10 offset:2304
	ds_read_b128 v[68:71], v10 offset:4608
	ds_read_b128 v[72:75], v89 offset:63552
	s_waitcnt lgkmcnt(3)
	v_mfma_f32_16x16x32_bf16 v[10:13], v[12:15], v[52:55], v[30:33]
	v_mov_b32_e32 v51, v50
	s_waitcnt lgkmcnt(2)
	v_mfma_f32_16x16x32_bf16 v[14:17], v[22:25], v[52:55], v[56:59]
	s_waitcnt lgkmcnt(1)
	v_mfma_f32_16x16x32_bf16 v[22:25], v[68:71], v[52:55], v[60:63]
	s_waitcnt lgkmcnt(0)
	v_mfma_f32_16x16x32_bf16 v[30:33], v[72:75], v[52:55], v[64:67]
	ds_read_b128 v[54:57], v90
	ds_read_b128 v[58:61], v88 offset:18432
	s_nop 0
	ds_read_b128 v[62:65], v88 offset:20736
	ds_read_b128 v[66:69], v88 offset:23040
	ds_read_b128 v[70:73], v89 offset:18432
	ds_read_b128 v[74:77], v88 offset:27648
	ds_read_b128 v[78:81], v88 offset:29952
	ds_read_b128 v[100:103], v88 offset:32256
	ds_read_b128 v[104:107], v92 offset:18432
	v_mov_b32_e32 v52, v50
	v_mov_b32_e32 v53, v50
	s_waitcnt lgkmcnt(7)
	s_nop 0
	v_mfma_f32_16x16x32_bf16 v[58:61], v[58:61], v[54:57], v[50:53]
	s_waitcnt lgkmcnt(6)
	v_mfma_f32_16x16x32_bf16 v[62:65], v[62:65], v[54:57], v[50:53]
	s_waitcnt lgkmcnt(5)
	v_mfma_f32_16x16x32_bf16 v[66:69], v[66:69], v[54:57], v[50:53]
	s_waitcnt lgkmcnt(4)
	v_mfma_f32_16x16x32_bf16 v[108:111], v[70:73], v[54:57], v[50:53]
	s_waitcnt lgkmcnt(3)
	v_mfma_f32_16x16x32_bf16 v[112:115], v[74:77], v[54:57], v[50:53]
	s_waitcnt lgkmcnt(2)
	v_mfma_f32_16x16x32_bf16 v[116:119], v[78:81], v[54:57], v[50:53]
	s_waitcnt lgkmcnt(1)
	v_mfma_f32_16x16x32_bf16 v[100:103], v[100:103], v[54:57], v[50:53]
	s_waitcnt lgkmcnt(0)
	v_mfma_f32_16x16x32_bf16 v[50:53], v[104:107], v[54:57], v[50:53]
	ds_read_b128 v[104:107], v90 offset:64
	ds_read_b128 v[54:57], v88 offset:18496
	ds_read_b128 v[70:73], v88 offset:20800
	ds_read_b128 v[124:127], v88 offset:23104
	ds_read_b128 v[128:131], v89 offset:18496
	ds_read_b128 v[132:135], v88 offset:27712
	ds_read_b128 v[136:139], v88 offset:30016
	ds_read_b128 v[140:143], v88 offset:32320
	ds_read_b128 v[144:147], v92 offset:18496
	s_waitcnt lgkmcnt(7)
	v_mfma_f32_16x16x32_bf16 v[78:81], v[54:57], v[104:107], v[58:61]
	s_waitcnt lgkmcnt(1)
	v_mfma_f32_16x16x32_bf16 v[54:57], v[140:143], v[104:107], v[100:103]
	s_nop 2
	v_or_b32_e32 v102, 1, v91
	v_sub_u32_e32 v0, v102, v99
	v_sub_u32_e32 v87, v99, v102
	v_cndmask_b32_e32 v0, v0, v87, vcc
	v_cvt_f32_i32_e32 v0, v0
	v_cndmask_b32_e32 v87, v97, v96, vcc
	v_mfma_f32_16x16x32_bf16 v[74:77], v[70:73], v[104:107], v[62:65]
	v_or_b32_e32 v103, 3, v91
	v_mul_f32_e32 v0, v87, v0
	v_mul_f32_e32 v0, 0xbfb8aa3b, v0
	v_exp_f32_e32 v87, v0
	v_mfma_f32_16x16x32_bf16 v[70:73], v[124:127], v[104:107], v[66:69]
	v_or_b32_e32 v100, 18, v91
	v_or_b32_e32 v101, 19, v91
	v_pk_mul_f32 v[78:79], v[86:87], v[78:79]
	v_mfma_f32_16x16x32_bf16 v[66:69], v[128:131], v[104:107], v[108:111]
	v_or_b32_e32 v124, 0x62, v91
	v_or_b32_e32 v125, 0x63, v91
	v_lshl_add_u32 v130, v93, 7, v88
	v_mfma_f32_16x16x32_bf16 v[62:65], v[132:135], v[104:107], v[112:115]
	v_or_b32_e32 v108, 35, v91
	v_or_b32_e32 v109, 48, v91
	v_or_b32_e32 v110, 49, v91
	v_mfma_f32_16x16x32_bf16 v[58:61], v[136:139], v[104:107], v[116:119]
	v_or_b32_e32 v111, 50, v91
	v_or_b32_e32 v112, 51, v91
	v_or_b32_e32 v113, 64, v91
	s_waitcnt lgkmcnt(0)
	v_mfma_f32_16x16x32_bf16 v[50:53], v[144:147], v[104:107], v[50:53]
	v_or_b32_e32 v104, 2, v91
	v_sub_u32_e32 v0, v99, v104
	v_sub_u32_e32 v86, 0, v0
	v_max_i32_e32 v0, v0, v86
	v_cvt_f32_u32_e32 v0, v0
	v_cmp_lt_i32_e32 vcc, v99, v104
	v_or_b32_e32 v105, 32, v91
	v_or_b32_e32 v106, 33, v91
	v_cndmask_b32_e32 v86, v96, v97, vcc
	v_mul_f32_e32 v0, v86, v0
	v_mul_f32_e32 v0, 0xbfb8aa3b, v0
	v_exp_f32_e32 v86, v0
	v_sub_u32_e32 v0, v99, v103
	v_sub_u32_e32 v87, 0, v0
	v_max_i32_e32 v0, v0, v87
	v_cvt_f32_u32_e32 v0, v0
	v_cmp_lt_i32_e32 vcc, v99, v103
	v_or_b32_e32 v107, 34, v91
	v_or_b32_e32 v114, 0x41, v91
	v_cndmask_b32_e32 v87, v96, v97, vcc
	v_mul_f32_e32 v0, v87, v0
	v_mul_f32_e32 v0, 0xbfb8aa3b, v0
	v_exp_f32_e32 v87, v0
	v_sub_u32_e32 v0, v99, v94
	v_cmp_lt_i32_e32 vcc, v99, v94
	v_or_b32_e32 v115, 0x42, v91
	v_pk_mul_f32 v[80:81], v[86:87], v[80:81]
	v_sub_u32_e32 v86, 0, v0
	v_max_i32_e32 v0, v0, v86
	v_cvt_f32_u32_e32 v0, v0
	v_cndmask_b32_e32 v86, v96, v97, vcc
	v_cmp_lt_i32_e32 vcc, v99, v95
	v_or_b32_e32 v116, 0x43, v91
	v_mul_f32_e32 v0, v86, v0
	v_mul_f32_e32 v0, 0xbfb8aa3b, v0
	v_exp_f32_e32 v86, v0
	v_sub_u32_e32 v0, v99, v95
	v_sub_u32_e32 v87, 0, v0
	v_max_i32_e32 v0, v0, v87
	v_cvt_f32_u32_e32 v0, v0
	v_cndmask_b32_e32 v87, v96, v97, vcc
	v_cmp_lt_i32_e32 vcc, v99, v100
	v_or_b32_e32 v117, 0x50, v91
	v_mul_f32_e32 v0, v87, v0
	v_mul_f32_e32 v0, 0xbfb8aa3b, v0
	v_exp_f32_e32 v87, v0
	v_sub_u32_e32 v0, v99, v100
	v_or_b32_e32 v118, 0x51, v91
	v_or_b32_e32 v119, 0x52, v91
	v_pk_mul_f32 v[74:75], v[86:87], v[74:75]
	v_sub_u32_e32 v86, 0, v0
	v_max_i32_e32 v0, v0, v86
	v_cvt_f32_u32_e32 v0, v0
	v_cndmask_b32_e32 v86, v96, v97, vcc
	v_cmp_lt_i32_e32 vcc, v99, v101
	v_cvt_pk_bf16_f32 v78, v78, v79
	v_mul_f32_e32 v0, v86, v0
	v_mul_f32_e32 v0, 0xbfb8aa3b, v0
	v_exp_f32_e32 v86, v0
	v_sub_u32_e32 v0, v99, v101
	v_sub_u32_e32 v87, 0, v0
	v_max_i32_e32 v0, v0, v87
	v_cvt_f32_u32_e32 v0, v0
	v_cndmask_b32_e32 v87, v96, v97, vcc
	v_cmp_lt_i32_e32 vcc, v99, v105
	v_cvt_pk_bf16_f32 v79, v80, v81
	v_mul_f32_e32 v0, v87, v0
	v_mul_f32_e32 v0, 0xbfb8aa3b, v0
	v_exp_f32_e32 v87, v0
	v_sub_u32_e32 v0, v99, v105
	v_cvt_pk_bf16_f32 v80, v74, v75
	v_or_b32_e32 v126, 0x70, v91
	v_pk_mul_f32 v[76:77], v[86:87], v[76:77]
	v_sub_u32_e32 v86, 0, v0
	v_max_i32_e32 v0, v0, v86
	v_cvt_f32_u32_e32 v0, v0
	v_cndmask_b32_e32 v86, v96, v97, vcc
	v_cmp_lt_i32_e32 vcc, v99, v106
	v_cvt_pk_bf16_f32 v81, v76, v77
	v_mul_f32_e32 v0, v86, v0
	v_mul_f32_e32 v0, 0xbfb8aa3b, v0
	v_exp_f32_e32 v86, v0
	v_sub_u32_e32 v0, v99, v106
	v_sub_u32_e32 v87, 0, v0
	v_max_i32_e32 v0, v0, v87
	v_cvt_f32_u32_e32 v0, v0
	v_cndmask_b32_e32 v87, v96, v97, vcc
	v_cmp_lt_i32_e32 vcc, v99, v107
	ds_read_b128 v[74:77], v130 offset:36864
	v_mul_f32_e32 v0, v87, v0
	v_mul_f32_e32 v0, 0xbfb8aa3b, v0
	v_exp_f32_e32 v87, v0
	v_sub_u32_e32 v0, v99, v107
	v_or_b32_e32 v127, 0x71, v91
	v_or_b32_e32 v128, 0x72, v91
	v_pk_mul_f32 v[70:71], v[86:87], v[70:71]
	v_sub_u32_e32 v86, 0, v0
	v_max_i32_e32 v0, v0, v86
	v_cvt_f32_u32_e32 v0, v0
	v_cndmask_b32_e32 v86, v96, v97, vcc
	v_cmp_lt_i32_e32 vcc, v99, v108
	v_cvt_pk_bf16_f32 v70, v70, v71
	v_mul_f32_e32 v0, v86, v0
	v_mul_f32_e32 v0, 0xbfb8aa3b, v0
	v_exp_f32_e32 v86, v0
	v_sub_u32_e32 v0, v99, v108
	v_sub_u32_e32 v87, 0, v0
	v_max_i32_e32 v0, v0, v87
	v_cvt_f32_u32_e32 v0, v0
	v_cndmask_b32_e32 v87, v96, v97, vcc
	v_cmp_lt_i32_e32 vcc, v99, v109
	v_or_b32_e32 v129, 0x73, v91
	v_mul_f32_e32 v0, v87, v0
	v_mul_f32_e32 v0, 0xbfb8aa3b, v0
	v_exp_f32_e32 v87, v0
	v_sub_u32_e32 v0, v99, v109
	v_pk_mul_f32 v[72:73], v[86:87], v[72:73]
	v_sub_u32_e32 v86, 0, v0
	v_max_i32_e32 v0, v0, v86
	v_cvt_f32_u32_e32 v0, v0
	v_cndmask_b32_e32 v86, v96, v97, vcc
	v_cmp_lt_i32_e32 vcc, v99, v110
	v_cvt_pk_bf16_f32 v71, v72, v73
	v_mul_f32_e32 v0, v86, v0
	v_mul_f32_e32 v0, 0xbfb8aa3b, v0
	v_exp_f32_e32 v86, v0
	v_sub_u32_e32 v0, v99, v110
	v_sub_u32_e32 v87, 0, v0
	v_max_i32_e32 v0, v0, v87
	v_cvt_f32_u32_e32 v0, v0
	v_cndmask_b32_e32 v87, v96, v97, vcc
	v_cmp_lt_i32_e32 vcc, v99, v111
	v_mul_f32_e32 v0, v87, v0
	v_mul_f32_e32 v0, 0xbfb8aa3b, v0
	v_exp_f32_e32 v87, v0
	v_sub_u32_e32 v0, v99, v111
	v_pk_mul_f32 v[66:67], v[86:87], v[66:67]
	v_sub_u32_e32 v86, 0, v0
	v_max_i32_e32 v0, v0, v86
	v_cvt_f32_u32_e32 v0, v0
	v_cndmask_b32_e32 v86, v96, v97, vcc
	v_cmp_lt_i32_e32 vcc, v99, v112
	v_cvt_pk_bf16_f32 v72, v66, v67
	v_mul_f32_e32 v0, v86, v0
	v_mul_f32_e32 v0, 0xbfb8aa3b, v0
	v_exp_f32_e32 v86, v0
	v_sub_u32_e32 v0, v99, v112
	v_sub_u32_e32 v87, 0, v0
	v_max_i32_e32 v0, v0, v87
	v_cvt_f32_u32_e32 v0, v0
	v_cndmask_b32_e32 v87, v96, v97, vcc
	v_cmp_lt_i32_e32 vcc, v99, v113
	v_mul_f32_e32 v0, v87, v0
	v_mul_f32_e32 v0, 0xbfb8aa3b, v0
	v_exp_f32_e32 v87, v0
	v_sub_u32_e32 v0, v99, v113
	v_pk_mul_f32 v[68:69], v[86:87], v[68:69]
	v_sub_u32_e32 v86, 0, v0
	v_max_i32_e32 v0, v0, v86
	v_cvt_f32_u32_e32 v0, v0
	v_cndmask_b32_e32 v86, v96, v97, vcc
	v_cmp_lt_i32_e32 vcc, v99, v114
	v_cvt_pk_bf16_f32 v73, v68, v69
	v_mul_f32_e32 v0, v86, v0
	v_mul_f32_e32 v0, 0xbfb8aa3b, v0
	v_exp_f32_e32 v86, v0
	v_sub_u32_e32 v0, v99, v114
	v_sub_u32_e32 v87, 0, v0
	v_max_i32_e32 v0, v0, v87
	v_cvt_f32_u32_e32 v0, v0
	v_cndmask_b32_e32 v87, v96, v97, vcc
	v_cmp_lt_i32_e32 vcc, v99, v115
	ds_read_b128 v[66:69], v130 offset:36928
	v_mul_f32_e32 v0, v87, v0
	v_mul_f32_e32 v0, 0xbfb8aa3b, v0
	v_exp_f32_e32 v87, v0
	v_sub_u32_e32 v0, v99, v115
	s_waitcnt lgkmcnt(1)
	v_mfma_f32_16x16x32_bf16 v[34:37], v[74:77], v[78:81], v[34:37]
	ds_read_b128 v[74:77], v130 offset:41216
	v_pk_mul_f32 v[62:63], v[86:87], v[62:63]
	v_sub_u32_e32 v86, 0, v0
	v_max_i32_e32 v0, v0, v86
	v_cvt_f32_u32_e32 v0, v0
	v_cndmask_b32_e32 v86, v96, v97, vcc
	v_cmp_lt_i32_e32 vcc, v99, v116
	v_cvt_pk_bf16_f32 v62, v62, v63
	v_mul_f32_e32 v0, v86, v0
	v_mul_f32_e32 v0, 0xbfb8aa3b, v0
	v_exp_f32_e32 v86, v0
	v_sub_u32_e32 v0, v99, v116
	v_sub_u32_e32 v87, 0, v0
	v_max_i32_e32 v0, v0, v87
	v_cvt_f32_u32_e32 v0, v0
	v_cndmask_b32_e32 v87, v96, v97, vcc
	v_cmp_lt_i32_e32 vcc, v99, v117
	s_waitcnt lgkmcnt(1)
	v_mfma_f32_16x16x32_bf16 v[34:37], v[66:69], v[70:73], v[34:37]
	v_mul_f32_e32 v0, v87, v0
	v_mul_f32_e32 v0, 0xbfb8aa3b, v0
	v_exp_f32_e32 v87, v0
	v_sub_u32_e32 v0, v99, v117
	ds_read_b128 v[66:69], v130 offset:41280
	v_pk_mul_f32 v[64:65], v[86:87], v[64:65]
	v_sub_u32_e32 v86, 0, v0
	v_max_i32_e32 v0, v0, v86
	v_cvt_f32_u32_e32 v0, v0
	v_cndmask_b32_e32 v86, v96, v97, vcc
	v_cmp_lt_i32_e32 vcc, v99, v118
	v_cvt_pk_bf16_f32 v63, v64, v65
	v_mul_f32_e32 v0, v86, v0
	v_mul_f32_e32 v0, 0xbfb8aa3b, v0
	v_exp_f32_e32 v86, v0
	v_sub_u32_e32 v0, v99, v118
	v_sub_u32_e32 v87, 0, v0
	v_max_i32_e32 v0, v0, v87
	v_cvt_f32_u32_e32 v0, v0
	v_cndmask_b32_e32 v87, v96, v97, vcc
	v_cmp_lt_i32_e32 vcc, v99, v119
	v_mul_f32_e32 v0, v87, v0
	v_mul_f32_e32 v0, 0xbfb8aa3b, v0
	v_exp_f32_e32 v87, v0
	v_sub_u32_e32 v0, v99, v119
	v_pk_mul_f32 v[58:59], v[86:87], v[58:59]
	v_sub_u32_e32 v86, 0, v0
	v_max_i32_e32 v0, v0, v86
	v_cvt_f32_u32_e32 v0, v0
	v_cndmask_b32_e32 v86, v96, v97, vcc
	v_cmp_lt_i32_e32 vcc, v99, v120
	v_cvt_pk_bf16_f32 v64, v58, v59
	v_mul_f32_e32 v0, v86, v0
	v_mul_f32_e32 v0, 0xbfb8aa3b, v0
	v_exp_f32_e32 v86, v0
	v_sub_u32_e32 v0, v99, v120
	v_sub_u32_e32 v87, 0, v0
	v_max_i32_e32 v0, v0, v87
	v_cvt_f32_u32_e32 v0, v0
	v_cndmask_b32_e32 v87, v96, v97, vcc
	v_cmp_lt_i32_e32 vcc, v99, v121
	v_mul_f32_e32 v0, v87, v0
	v_mul_f32_e32 v0, 0xbfb8aa3b, v0
	v_exp_f32_e32 v87, v0
	v_sub_u32_e32 v0, v99, v121
	v_pk_mul_f32 v[60:61], v[86:87], v[60:61]
	v_sub_u32_e32 v86, 0, v0
	v_max_i32_e32 v0, v0, v86
	v_cvt_f32_u32_e32 v0, v0
	v_cndmask_b32_e32 v86, v96, v97, vcc
	v_cmp_lt_i32_e32 vcc, v99, v123
	v_cvt_pk_bf16_f32 v65, v60, v61
	v_mul_f32_e32 v0, v86, v0
	v_mul_f32_e32 v0, 0xbfb8aa3b, v0
	v_exp_f32_e32 v86, v0
	v_sub_u32_e32 v0, v99, v123
	v_sub_u32_e32 v87, 0, v0
	v_max_i32_e32 v0, v0, v87
	v_cvt_f32_u32_e32 v0, v0
	v_cndmask_b32_e32 v87, v96, v97, vcc
	v_cmp_lt_i32_e32 vcc, v99, v124
	ds_read_b128 v[58:61], v130 offset:36992
	v_mul_f32_e32 v0, v87, v0
	v_mul_f32_e32 v0, 0xbfb8aa3b, v0
	v_exp_f32_e32 v87, v0
	v_sub_u32_e32 v0, v99, v124
	s_waitcnt lgkmcnt(2)
	v_mfma_f32_16x16x32_bf16 v[38:41], v[74:77], v[78:81], v[38:41]
	ds_read_b128 v[74:77], v130 offset:45568
	v_pk_mul_f32 v[54:55], v[86:87], v[54:55]
	v_sub_u32_e32 v86, 0, v0
	v_max_i32_e32 v0, v0, v86
	v_cvt_f32_u32_e32 v0, v0
	v_cndmask_b32_e32 v86, v96, v97, vcc
	v_cmp_lt_i32_e32 vcc, v99, v125
	s_waitcnt lgkmcnt(1)
	v_mfma_f32_16x16x32_bf16 v[34:37], v[58:61], v[62:65], v[34:37]
	v_mul_f32_e32 v0, v86, v0
	v_mul_f32_e32 v0, 0xbfb8aa3b, v0
	v_exp_f32_e32 v86, v0
	v_sub_u32_e32 v0, v99, v125
	v_sub_u32_e32 v87, 0, v0
	v_max_i32_e32 v0, v0, v87
	v_cvt_f32_u32_e32 v0, v0
	v_cndmask_b32_e32 v87, v96, v97, vcc
	v_cmp_lt_i32_e32 vcc, v99, v126
	ds_read_b128 v[58:61], v130 offset:41344
	v_mul_f32_e32 v0, v87, v0
	v_mul_f32_e32 v0, 0xbfb8aa3b, v0
	v_exp_f32_e32 v87, v0
	v_sub_u32_e32 v0, v99, v126
	v_mfma_f32_16x16x32_bf16 v[38:41], v[66:69], v[70:73], v[38:41]
	ds_read_b128 v[66:69], v130 offset:45632
	v_pk_mul_f32 v[56:57], v[86:87], v[56:57]
	v_sub_u32_e32 v86, 0, v0
	v_max_i32_e32 v0, v0, v86
	v_cvt_f32_u32_e32 v0, v0
	v_cndmask_b32_e32 v86, v96, v97, vcc
	v_cmp_lt_i32_e32 vcc, v99, v127
	s_waitcnt lgkmcnt(2)
	v_mfma_f32_16x16x32_bf16 v[42:45], v[74:77], v[78:81], v[42:45]
	v_mul_f32_e32 v0, v86, v0
	v_mul_f32_e32 v0, 0xbfb8aa3b, v0
	v_exp_f32_e32 v86, v0
	v_sub_u32_e32 v0, v99, v127
	v_sub_u32_e32 v87, 0, v0
	v_max_i32_e32 v0, v0, v87
	v_cvt_f32_u32_e32 v0, v0
	v_cndmask_b32_e32 v87, v96, v97, vcc
	ds_read_b128 v[74:77], v130 offset:49920
	s_waitcnt lgkmcnt(2)
	v_mfma_f32_16x16x32_bf16 v[38:41], v[58:61], v[62:65], v[38:41]
	v_mul_f32_e32 v0, v87, v0
	v_mul_f32_e32 v0, 0xbfb8aa3b, v0
	v_exp_f32_e32 v87, v0
	ds_read_b128 v[58:61], v130 offset:45696
	v_sub_u32_e32 v0, v99, v128
	s_waitcnt lgkmcnt(2)
	v_mfma_f32_16x16x32_bf16 v[42:45], v[66:69], v[70:73], v[42:45]
	v_mul_f32_e64 v50, v86, v50
	v_mul_f32_e64 v51, v87, v51
	v_sub_u32_e32 v86, 0, v0
	v_max_i32_e32 v0, v0, v86
	ds_read_b128 v[66:69], v130 offset:49984
	v_cvt_f32_u32_e32 v0, v0
	v_cmp_lt_i32_e32 vcc, v99, v128
	s_waitcnt lgkmcnt(1)
	v_mfma_f32_16x16x32_bf16 v[58:61], v[58:61], v[62:65], v[42:45]
	v_cndmask_b32_e32 v86, v96, v97, vcc
	v_mul_f32_e32 v0, v86, v0
	s_nop 0
	ds_read_b128 v[42:45], v130 offset:50048
	v_mfma_f32_16x16x32_bf16 v[46:49], v[74:77], v[78:81], v[46:49]
	v_mul_f32_e32 v0, 0xbfb8aa3b, v0
	v_exp_f32_e32 v86, v0
	v_sub_u32_e32 v0, v99, v129
	v_sub_u32_e32 v87, 0, v0
	v_max_i32_e32 v0, v0, v87
	s_waitcnt lgkmcnt(1)
	v_mfma_f32_16x16x32_bf16 v[46:49], v[66:69], v[70:73], v[46:49]
	v_cvt_f32_u32_e32 v0, v0
	v_cmp_lt_i32_e32 vcc, v99, v129
	s_waitcnt lgkmcnt(0)
	v_mfma_f32_16x16x32_bf16 v[62:65], v[42:45], v[62:65], v[46:49]
	v_cndmask_b32_e32 v87, v96, v97, vcc
	ds_read_b128 v[42:45], v130 offset:37056
	v_mul_f32_e32 v0, v87, v0
	v_mul_f32_e32 v0, 0xbfb8aa3b, v0
	v_exp_f32_e32 v87, v0
	s_nop 0
	v_pk_mul_f32 v[86:87], v[86:87], v[52:53]
	v_cvt_pk_bf16_f32 v52, v54, v55
	v_cvt_pk_bf16_f32 v53, v56, v57
	v_cvt_pk_bf16_f32 v54, v50, v51
	v_cvt_pk_bf16_f32 v55, v86, v87
	s_waitcnt lgkmcnt(0)
	s_nop 0
	v_mfma_f32_16x16x32_bf16 v[46:49], v[42:45], v[52:55], v[34:37]
	s_nop 2
	ds_read_b128 v[34:37], v130 offset:41408
	s_waitcnt lgkmcnt(0)
	v_mfma_f32_16x16x32_bf16 v[42:45], v[34:37], v[52:55], v[38:41]
	ds_read_b128 v[34:37], v130 offset:45760
	s_nop 0
	v_mul_f32_e32 v0, v47, v47
	v_fmac_f32_e32 v0, v46, v46
	s_waitcnt lgkmcnt(0)
	v_mfma_f32_16x16x32_bf16 v[38:41], v[34:37], v[52:55], v[58:61]
	ds_read_b128 v[34:37], v130 offset:50112
	v_fmac_f32_e32 v0, v48, v48
	v_fmac_f32_e32 v0, v49, v49
	v_fmac_f32_e32 v0, v42, v42
	v_fmac_f32_e32 v0, v43, v43
	v_fmac_f32_e32 v0, v44, v44
	s_waitcnt lgkmcnt(0)
	v_mfma_f32_16x16x32_bf16 v[34:37], v[34:37], v[52:55], v[62:65]
	v_fmac_f32_e32 v0, v45, v45
	v_pk_mul_f32 v[52:53], v[38:39], v[38:39]
	v_pk_mul_f32 v[50:51], v[40:41], v[40:41]
	v_add_f32_e32 v0, v52, v0
	v_add_f32_e32 v0, v53, v0
	v_add_f32_e32 v0, v50, v0
	v_add_f32_e32 v0, v51, v0
	s_nop 0
	v_pk_mul_f32 v[52:53], v[34:35], v[34:35]
	v_pk_mul_f32 v[50:51], v[36:37], v[36:37]
	v_add_f32_e32 v0, v52, v0
	v_add_f32_e32 v0, v53, v0
	v_add_f32_e32 v0, v50, v0
	v_add_f32_e32 v0, v51, v0
	v_and_b32_e32 v51, 64, v170
	v_xor_b32_e32 v50, 16, v170
	v_add_u32_e32 v51, 64, v51
	v_cmp_lt_i32_e32 vcc, v50, v51
	v_mad_i64_i32 v[52:53], s[6:7], v99, s52, v[82:83]
	s_nop 0
	v_cndmask_b32_e32 v50, v170, v50, vcc
	v_lshlrev_b32_e32 v131, 2, v50
	ds_bpermute_b32 v50, v131, v0
	v_lshl_add_u64 v[52:53], v[52:53], 0, v[84:85]
	s_waitcnt lgkmcnt(0)
	v_add_f32_e32 v0, v0, v50
	v_xor_b32_e32 v50, 32, v170
	v_cmp_lt_i32_e32 vcc, v50, v51
	s_nop 1
	v_cndmask_b32_e32 v50, v170, v50, vcc
	v_lshlrev_b32_e32 v132, 2, v50
	ds_bpermute_b32 v50, v132, v0
	s_waitcnt lgkmcnt(0)
	v_add_f32_e32 v0, v0, v50
	v_fmamk_f32 v0, v0, 0x3c800000, v158
	v_cmp_gt_f32_e32 vcc, s66, v0
	v_mul_f32_e32 v50, 0x4b800000, v0
	s_nop 0
	v_cndmask_b32_e32 v0, v0, v50, vcc
	v_rsq_f32_e32 v0, v0
	s_nop 0
	v_mul_f32_e32 v50, 0x45800000, v0
	v_cndmask_b32_e32 v50, v0, v50, vcc
	v_lshlrev_b32_e32 v0, 1, v91
	v_lshl_add_u64 v[52:53], v[52:53], 0, v[0:1]
	global_load_dwordx2 v[54:55], v[52:53], off offset:1536
	v_cmp_lt_i32_e32 vcc, v98, v91
	s_waitcnt vmcnt(0) lgkmcnt(0)
	v_lshlrev_b32_e32 v56, 16, v54
	v_mul_f32_e32 v51, 0xbfb8aa3b, v56
	v_exp_f32_e32 v51, v51
	v_and_b32_e32 v57, 0xffff0000, v54
	v_lshlrev_b32_e32 v54, 16, v55
	v_and_b32_e32 v55, 0xffff0000, v55
	v_add_f32_e32 v51, 1.0, v51
	v_rcp_f32_e32 v58, v51
	v_mul_f32_e32 v51, 0xbfb8aa3b, v57
	v_exp_f32_e32 v51, v51
	s_nop 0
	v_add_f32_e32 v51, 1.0, v51
	v_rcp_f32_e32 v59, v51
	s_nop 0
	v_pk_mul_f32 v[56:57], v[58:59], v[56:57]
	s_nop 0
	v_pk_mul_f32 v[56:57], v[56:57], v[50:51] op_sel_hi:[1,0]
	v_mul_f32_e32 v51, 0xbfb8aa3b, v54
	v_exp_f32_e32 v51, v51
	v_pk_mul_f32 v[46:47], v[46:47], v[56:57]
	v_add_f32_e32 v51, 1.0, v51
	v_rcp_f32_e32 v56, v51
	v_mul_f32_e32 v51, 0xbfb8aa3b, v55
	v_exp_f32_e32 v51, v51
	v_cvt_pk_bf16_f32 v46, v46, v47
	v_add_f32_e32 v51, 1.0, v51
	v_rcp_f32_e32 v57, v51
	s_nop 0
	v_pk_mul_f32 v[54:55], v[56:57], v[54:55]
	s_nop 0
	v_pk_mul_f32 v[54:55], v[54:55], v[50:51] op_sel_hi:[1,0]
	s_nop 0
	v_pk_mul_f32 v[48:49], v[48:49], v[54:55]
	s_nop 0
	v_cvt_pk_bf16_f32 v47, v48, v49
	global_store_dwordx2 v[52:53], v[46:47], off offset:1536
	global_load_dwordx2 v[46:47], v[52:53], off offset:1568
	s_waitcnt vmcnt(0) lgkmcnt(0)
	v_lshlrev_b32_e32 v48, 16, v46
	v_mul_f32_e32 v51, 0xbfb8aa3b, v48
	v_exp_f32_e32 v51, v51
	v_and_b32_e32 v49, 0xffff0000, v46
	v_lshlrev_b32_e32 v46, 16, v47
	v_and_b32_e32 v47, 0xffff0000, v47
	v_add_f32_e32 v51, 1.0, v51
	v_rcp_f32_e32 v54, v51
	v_mul_f32_e32 v51, 0xbfb8aa3b, v49
	v_exp_f32_e32 v51, v51
	s_nop 0
	v_add_f32_e32 v51, 1.0, v51
	v_rcp_f32_e32 v55, v51
	s_nop 0
	v_pk_mul_f32 v[48:49], v[54:55], v[48:49]
	s_nop 0
	v_pk_mul_f32 v[48:49], v[48:49], v[50:51] op_sel_hi:[1,0]
	s_nop 0
	v_pk_mul_f32 v[42:43], v[42:43], v[48:49]
	v_mul_f32_e32 v48, 0xbfb8aa3b, v46
	v_mul_f32_e32 v49, 0xbfb8aa3b, v47
	v_exp_f32_e32 v48, v48
	v_exp_f32_e32 v49, v49
	v_cvt_pk_bf16_f32 v42, v42, v43
	v_add_f32_e32 v48, 1.0, v48
	v_add_f32_e32 v49, 1.0, v49
	v_rcp_f32_e32 v48, v48
	v_rcp_f32_e32 v49, v49
	s_nop 0
	v_pk_mul_f32 v[46:47], v[48:49], v[46:47]
	s_nop 0
	v_pk_mul_f32 v[46:47], v[46:47], v[50:51] op_sel_hi:[1,0]
	s_nop 0
	v_pk_mul_f32 v[44:45], v[44:45], v[46:47]
	s_nop 0
	v_cvt_pk_bf16_f32 v43, v44, v45
	global_store_dwordx2 v[52:53], v[42:43], off offset:1568
	global_load_dwordx2 v[42:43], v[52:53], off offset:1600
	s_waitcnt vmcnt(0) lgkmcnt(0)
	v_lshlrev_b32_e32 v44, 16, v42
	v_and_b32_e32 v45, 0xffff0000, v42
	v_mul_f32_e32 v46, 0xbfb8aa3b, v44
	v_mul_f32_e32 v47, 0xbfb8aa3b, v45
	v_exp_f32_e32 v46, v46
	v_exp_f32_e32 v47, v47
	v_lshlrev_b32_e32 v42, 16, v43
	v_and_b32_e32 v43, 0xffff0000, v43
	v_add_f32_e32 v46, 1.0, v46
	v_add_f32_e32 v47, 1.0, v47
	v_rcp_f32_e32 v46, v46
	v_rcp_f32_e32 v47, v47
	s_nop 0
	v_pk_mul_f32 v[44:45], v[46:47], v[44:45]
	s_nop 0
	v_pk_mul_f32 v[44:45], v[44:45], v[50:51] op_sel_hi:[1,0]
	s_nop 0
	v_pk_mul_f32 v[38:39], v[38:39], v[44:45]
	v_mul_f32_e32 v44, 0xbfb8aa3b, v42
	v_mul_f32_e32 v45, 0xbfb8aa3b, v43
	v_exp_f32_e32 v44, v44
	v_exp_f32_e32 v45, v45
	v_cvt_pk_bf16_f32 v38, v38, v39
	v_add_f32_e32 v44, 1.0, v44
	v_add_f32_e32 v45, 1.0, v45
	v_rcp_f32_e32 v44, v44
	v_rcp_f32_e32 v45, v45
	s_nop 0
	v_pk_mul_f32 v[42:43], v[44:45], v[42:43]
	s_nop 0
	v_pk_mul_f32 v[42:43], v[50:51], v[42:43] op_sel_hi:[0,1]
	v_pk_mul_f32 v[40:41], v[40:41], v[42:43]
	s_nop 0
	v_cvt_pk_bf16_f32 v39, v40, v41
	global_store_dwordx2 v[52:53], v[38:39], off offset:1600
	global_load_dwordx2 v[38:39], v[52:53], off offset:1632
	s_waitcnt vmcnt(0) lgkmcnt(0)
	v_lshlrev_b32_e32 v40, 16, v38
	v_and_b32_e32 v41, 0xffff0000, v38
	v_mul_f32_e32 v42, 0xbfb8aa3b, v40
	v_mul_f32_e32 v43, 0xbfb8aa3b, v41
	v_exp_f32_e32 v42, v42
	v_exp_f32_e32 v43, v43
	v_lshlrev_b32_e32 v38, 16, v39
	v_and_b32_e32 v39, 0xffff0000, v39
	v_add_f32_e32 v42, 1.0, v42
	v_add_f32_e32 v43, 1.0, v43
	v_rcp_f32_e32 v42, v42
	v_rcp_f32_e32 v43, v43
	s_nop 0
	v_pk_mul_f32 v[40:41], v[42:43], v[40:41]
	s_nop 0
	v_pk_mul_f32 v[40:41], v[50:51], v[40:41] op_sel_hi:[0,1]
	v_pk_mul_f32 v[34:35], v[34:35], v[40:41]
	v_mul_f32_e32 v40, 0xbfb8aa3b, v38
	v_mul_f32_e32 v41, 0xbfb8aa3b, v39
	v_exp_f32_e32 v40, v40
	v_exp_f32_e32 v41, v41
	v_cvt_pk_bf16_f32 v34, v34, v35
	v_add_f32_e32 v40, 1.0, v40
	v_add_f32_e32 v41, 1.0, v41
	v_rcp_f32_e32 v40, v40
	v_rcp_f32_e32 v41, v41
	s_nop 0
	v_pk_mul_f32 v[38:39], v[40:41], v[38:39]
	s_nop 0
	v_pk_mul_f32 v[38:39], v[50:51], v[38:39] op_sel_hi:[0,1]
	v_pk_mul_f32 v[36:37], v[36:37], v[38:39]
	s_nop 0
	v_cvt_pk_bf16_f32 v35, v36, v37
	global_store_dwordx2 v[52:53], v[34:35], off offset:1632
	v_mov_b32_e32 v34, v1
	ds_read_b128 v[38:41], v90 offset:9216
	ds_read_b128 v[42:45], v88 offset:18432
	ds_read_b128 v[46:49], v88 offset:20736
	ds_read_b128 v[50:53], v88 offset:23040
	ds_read_b128 v[54:57], v89 offset:18432
	ds_read_b128 v[58:61], v88 offset:27648
	ds_read_b128 v[62:65], v88 offset:29952
	ds_read_b128 v[66:69], v88 offset:32256
	ds_read_b128 v[70:73], v92 offset:18432
	v_mov_b32_e32 v35, v34
	v_mov_b32_e32 v36, v34
	v_mov_b32_e32 v37, v34
	s_waitcnt lgkmcnt(0)
	s_nop 0
	v_mfma_f32_16x16x32_bf16 v[42:45], v[42:45], v[38:41], v[34:37]
	v_mfma_f32_16x16x32_bf16 v[46:49], v[46:49], v[38:41], v[34:37]
	v_mfma_f32_16x16x32_bf16 v[50:53], v[50:53], v[38:41], v[34:37]
	v_mfma_f32_16x16x32_bf16 v[74:77], v[54:57], v[38:41], v[34:37]
	v_mfma_f32_16x16x32_bf16 v[78:81], v[58:61], v[38:41], v[34:37]
	v_mfma_f32_16x16x32_bf16 v[134:137], v[62:65], v[38:41], v[34:37]
	v_mfma_f32_16x16x32_bf16 v[66:69], v[66:69], v[38:41], v[34:37]
	v_mfma_f32_16x16x32_bf16 v[34:37], v[70:73], v[38:41], v[34:37]
	ds_read_b128 v[70:73], v90 offset:9280
	ds_read_b128 v[38:41], v88 offset:18496
	ds_read_b128 v[54:57], v88 offset:20800
	ds_read_b128 v[138:141], v88 offset:23104
	ds_read_b128 v[142:145], v89 offset:18496
	ds_read_b128 v[146:149], v88 offset:27712
	ds_read_b128 v[150:153], v88 offset:30016
	ds_read_b128 v[86:89], v88 offset:32320
	ds_read_b128 v[166:169], v92 offset:18496
	s_waitcnt lgkmcnt(0)
	v_mfma_f32_16x16x32_bf16 v[62:65], v[38:41], v[70:73], v[42:45]
	v_mfma_f32_16x16x32_bf16 v[38:41], v[86:89], v[70:73], v[66:69]
	s_nop 2
	v_sub_u32_e32 v66, v98, v91
	v_sub_u32_e32 v67, 0, v66
	v_max_i32_e32 v66, v66, v67
	v_cvt_f32_u32_e32 v66, v66
	v_cndmask_b32_e32 v67, v96, v97, vcc
	v_cmp_gt_i32_e32 vcc, v98, v91
	v_sub_u32_e32 v68, v98, v102
	v_mul_f32_e32 v66, v67, v66
	v_sub_u32_e32 v67, v102, v98
	v_cndmask_b32_e32 v67, v67, v68, vcc
	v_cvt_f32_i32_e32 v67, v67
	v_cndmask_b32_e32 v68, v97, v96, vcc
	v_cmp_lt_i32_e32 vcc, v98, v104
	v_mfma_f32_16x16x32_bf16 v[58:61], v[54:57], v[70:73], v[46:49]
	v_mul_f32_e32 v67, v68, v67
	v_sub_u32_e32 v68, v98, v104
	v_sub_u32_e32 v69, 0, v68
	v_max_i32_e32 v68, v68, v69
	v_cvt_f32_u32_e32 v68, v68
	v_cndmask_b32_e32 v69, v96, v97, vcc
	v_mfma_f32_16x16x32_bf16 v[54:57], v[138:141], v[70:73], v[50:53]
	v_cmp_lt_i32_e32 vcc, v98, v103
	v_mul_f32_e32 v68, v69, v68
	v_sub_u32_e32 v69, v98, v103
	v_mfma_f32_16x16x32_bf16 v[50:53], v[142:145], v[70:73], v[74:77]
	v_mul_f32_e32 v66, 0xbfb8aa3b, v66
	v_mul_f32_e32 v67, 0xbfb8aa3b, v67
	v_exp_f32_e32 v66, v66
	v_mfma_f32_16x16x32_bf16 v[46:49], v[146:149], v[70:73], v[78:81]
	v_exp_f32_e32 v67, v67
	v_mul_f32_e32 v68, 0xbfb8aa3b, v68
	v_exp_f32_e32 v68, v68
	v_mfma_f32_16x16x32_bf16 v[42:45], v[150:153], v[70:73], v[134:137]
	v_mul_f32_e64 v62, v66, v62
	v_mul_f32_e64 v63, v67, v63
	v_sub_u32_e32 v67, 64, v99
	v_add_u32_e32 v66, 0x41, v99
	v_mfma_f32_16x16x32_bf16 v[34:37], v[166:169], v[70:73], v[34:37]
	v_sub_u32_e32 v70, 0, v69
	v_max_i32_e32 v69, v69, v70
	v_cvt_f32_u32_e32 v69, v69
	v_cndmask_b32_e32 v70, v96, v97, vcc
	v_cmp_lt_i32_e32 vcc, v98, v94
	v_cvt_f32_i32_e32 v67, v67
	v_mul_f32_e32 v69, v70, v69
	v_sub_u32_e32 v70, v98, v94
	v_sub_u32_e32 v71, 0, v70
	v_max_i32_e32 v70, v70, v71
	v_cvt_f32_u32_e32 v70, v70
	v_cndmask_b32_e32 v71, v96, v97, vcc
	v_cmp_lt_i32_e32 vcc, v98, v95
	v_mul_f32_e32 v69, 0xbfb8aa3b, v69
	v_mul_f32_e32 v70, v71, v70
	v_sub_u32_e32 v71, v98, v95
	v_sub_u32_e32 v72, 0, v71
	v_max_i32_e32 v71, v71, v72
	v_cvt_f32_u32_e32 v71, v71
	v_cndmask_b32_e32 v72, v96, v97, vcc
	v_cmp_lt_i32_e32 vcc, v98, v100
	v_cvt_f32_i32_e32 v66, v66
	v_mul_f32_e32 v71, v72, v71
	v_sub_u32_e32 v72, v98, v100
	v_sub_u32_e32 v73, 0, v72
	v_max_i32_e32 v72, v72, v73
	v_cvt_f32_u32_e32 v72, v72
	v_cndmask_b32_e32 v73, v96, v97, vcc
	v_cmp_lt_i32_e32 vcc, v98, v101
	v_exp_f32_e32 v69, v69
	v_mul_f32_e32 v72, v73, v72
	v_sub_u32_e32 v73, v98, v101
	v_sub_u32_e32 v74, 0, v73
	v_max_i32_e32 v73, v73, v74
	v_cvt_f32_u32_e32 v73, v73
	v_cndmask_b32_e32 v74, v96, v97, vcc
	v_cmp_lt_i32_e32 vcc, v98, v105
	v_mul_f32_e32 v67, v67, v97
	v_mul_f32_e32 v73, v74, v73
	v_sub_u32_e32 v74, v98, v105
	v_sub_u32_e32 v75, 0, v74
	v_max_i32_e32 v74, v74, v75
	v_cvt_f32_u32_e32 v74, v74
	v_cndmask_b32_e32 v75, v96, v97, vcc
	v_cmp_lt_i32_e32 vcc, v98, v106
	v_mul_f32_e32 v66, v66, v96
	v_mul_f32_e32 v74, v75, v74
	v_sub_u32_e32 v75, v98, v106
	v_sub_u32_e32 v76, 0, v75
	v_max_i32_e32 v75, v75, v76
	v_cvt_f32_u32_e32 v75, v75
	v_cndmask_b32_e32 v76, v96, v97, vcc
	v_cmp_lt_i32_e32 vcc, v98, v107
	v_mul_f32_e32 v67, 0xbfb8aa3b, v67
	v_mul_f32_e32 v75, v76, v75
	v_sub_u32_e32 v76, v98, v107
	v_sub_u32_e32 v77, 0, v76
	v_max_i32_e32 v76, v76, v77
	v_cvt_f32_u32_e32 v76, v76
	v_cndmask_b32_e32 v77, v96, v97, vcc
	v_cmp_lt_i32_e32 vcc, v98, v108
	v_pk_mul_f32 v[64:65], v[68:69], v[64:65]
	v_mul_f32_e32 v76, v77, v76
	v_sub_u32_e32 v77, v98, v108
	v_sub_u32_e32 v78, 0, v77
	v_max_i32_e32 v77, v77, v78
	v_cvt_f32_u32_e32 v77, v77
	v_cndmask_b32_e32 v78, v96, v97, vcc
	v_cmp_lt_i32_e32 vcc, v98, v109
	v_mul_f32_e32 v66, 0xbfb8aa3b, v66
	v_mul_f32_e32 v77, v78, v77
	v_sub_u32_e32 v78, v98, v109
	v_sub_u32_e32 v79, 0, v78
	v_max_i32_e32 v78, v78, v79
	v_cvt_f32_u32_e32 v78, v78
	v_cndmask_b32_e32 v79, v96, v97, vcc
	v_cmp_lt_i32_e32 vcc, v98, v110
	v_exp_f32_e32 v68, v67
	v_mul_f32_e32 v78, v79, v78
	v_sub_u32_e32 v79, v98, v110
	v_sub_u32_e32 v80, 0, v79
	v_max_i32_e32 v79, v79, v80
	v_cvt_f32_u32_e32 v79, v79
	v_cndmask_b32_e32 v80, v96, v97, vcc
	v_cmp_lt_i32_e32 vcc, v98, v111
	v_exp_f32_e32 v66, v66
	v_mul_f32_e32 v79, v80, v79
	v_sub_u32_e32 v80, v98, v111
	v_sub_u32_e32 v81, 0, v80
	v_max_i32_e32 v80, v80, v81
	v_cvt_f32_u32_e32 v80, v80
	v_cndmask_b32_e32 v81, v96, v97, vcc
	v_cmp_lt_i32_e32 vcc, v98, v112
	v_pk_mul_f32 v[22:23], v[68:69], v[22:23] op_sel_hi:[0,1]
	v_mul_f32_e32 v80, v81, v80
	v_sub_u32_e32 v81, v98, v112
	v_sub_u32_e32 v86, 0, v81
	v_max_i32_e32 v81, v81, v86
	v_cvt_f32_u32_e32 v81, v81
	v_cndmask_b32_e32 v86, v96, v97, vcc
	v_pk_mul_f32 v[24:25], v[68:69], v[24:25] op_sel_hi:[0,1]
	v_pk_fma_f32 v[20:21], v[66:67], v[20:21], v[24:25] op_sel_hi:[0,1,1]
	v_mul_f32_e32 v81, v86, v81
	v_sub_u32_e32 v86, v98, v113
	v_sub_u32_e32 v87, 0, v86
	v_max_i32_e32 v86, v86, v87
	v_cvt_f32_u32_e32 v86, v86
	v_pk_fma_f32 v[18:19], v[66:67], v[18:19], v[22:23] op_sel_hi:[0,1,1]
	ds_read_b128 v[22:25], v130 offset:36864
	v_mul_f32_e32 v70, 0xbfb8aa3b, v70
	v_mul_f32_e32 v71, 0xbfb8aa3b, v71
	v_mul_f32_e32 v72, 0xbfb8aa3b, v72
	v_mul_f32_e32 v73, 0xbfb8aa3b, v73
	v_cmp_lt_i32_e32 vcc, v98, v113
	v_exp_f32_e32 v70, v70
	v_exp_f32_e32 v71, v71
	v_exp_f32_e32 v72, v72
	v_exp_f32_e32 v73, v73
	v_cndmask_b32_e32 v87, v96, v97, vcc
	v_mul_f32_e32 v86, v87, v86
	v_sub_u32_e32 v87, v98, v114
	v_sub_u32_e32 v88, 0, v87
	v_max_i32_e32 v87, v87, v88
	v_cvt_f32_u32_e32 v87, v87
	v_pk_mul_f32 v[58:59], v[70:71], v[58:59]
	v_pk_mul_f32 v[60:61], v[72:73], v[60:61]
	v_pk_mul_f32 v[14:15], v[68:69], v[14:15] op_sel_hi:[0,1]
	v_pk_mul_f32 v[16:17], v[68:69], v[16:17] op_sel_hi:[0,1]
	v_pk_mul_f32 v[10:11], v[68:69], v[10:11] op_sel_hi:[0,1]
	v_pk_mul_f32 v[12:13], v[68:69], v[12:13] op_sel_hi:[0,1]
	v_pk_fma_f32 v[8:9], v[66:67], v[8:9], v[16:17] op_sel_hi:[0,1,1]
	v_pk_fma_f32 v[6:7], v[66:67], v[6:7], v[14:15] op_sel_hi:[0,1,1]
	v_pk_fma_f32 v[12:13], v[66:67], v[4:5], v[12:13] op_sel_hi:[0,1,1]
	v_pk_fma_f32 v[10:11], v[66:67], v[2:3], v[10:11] op_sel_hi:[0,1,1]
	v_cvt_pk_bf16_f32 v14, v62, v63
	v_cvt_pk_bf16_f32 v15, v64, v65
	v_cvt_pk_bf16_f32 v16, v58, v59
	v_cvt_pk_bf16_f32 v17, v60, v61
	v_cmp_lt_i32_e32 vcc, v98, v114
	v_pk_mul_f32 v[30:31], v[68:69], v[30:31] op_sel_hi:[0,1]
	s_waitcnt lgkmcnt(0)
	v_mfma_f32_16x16x32_bf16 v[10:13], v[22:25], v[14:17], v[10:13]
	ds_read_b128 v[22:25], v130 offset:41216
	v_cndmask_b32_e32 v88, v96, v97, vcc
	v_mul_f32_e32 v87, v88, v87
	v_sub_u32_e32 v88, v98, v115
	v_sub_u32_e32 v89, 0, v88
	v_max_i32_e32 v88, v88, v89
	v_cvt_f32_u32_e32 v88, v88
	v_cmp_lt_i32_e32 vcc, v98, v115
	s_waitcnt lgkmcnt(0)
	v_mfma_f32_16x16x32_bf16 v[4:7], v[22:25], v[14:17], v[6:9]
	v_cndmask_b32_e32 v89, v96, v97, vcc
	v_mul_f32_e32 v88, v89, v88
	v_sub_u32_e32 v89, v98, v116
	ds_read_b128 v[22:25], v130 offset:45568
	v_sub_u32_e32 v90, 0, v89
	v_max_i32_e32 v89, v89, v90
	v_cvt_f32_u32_e32 v89, v89
	v_cmp_lt_i32_e32 vcc, v98, v116
	s_waitcnt lgkmcnt(0)
	v_mfma_f32_16x16x32_bf16 v[18:21], v[22:25], v[14:17], v[18:21]
	v_cndmask_b32_e32 v90, v96, v97, vcc
	v_mul_f32_e32 v89, v90, v89
	v_sub_u32_e32 v90, v98, v117
	v_sub_u32_e32 v91, 0, v90
	v_max_i32_e32 v90, v90, v91
	ds_read_b128 v[22:25], v130 offset:49920
	v_cvt_f32_u32_e32 v90, v90
	v_cmp_lt_i32_e32 vcc, v98, v117
	v_pk_mul_f32 v[32:33], v[68:69], v[32:33] op_sel_hi:[0,1]
	v_pk_fma_f32 v[28:29], v[66:67], v[28:29], v[32:33] op_sel_hi:[0,1,1]
	v_cndmask_b32_e32 v91, v96, v97, vcc
	v_mul_f32_e32 v90, v91, v90
	v_sub_u32_e32 v91, v98, v118
	v_sub_u32_e32 v92, 0, v91
	v_max_i32_e32 v91, v91, v92
	v_cvt_f32_u32_e32 v91, v91
	v_pk_fma_f32 v[26:27], v[66:67], v[26:27], v[30:31] op_sel_hi:[0,1,1]
	v_cmp_lt_i32_e32 vcc, v98, v118
	v_mul_f32_e32 v74, 0xbfb8aa3b, v74
	s_waitcnt lgkmcnt(0)
	v_mfma_f32_16x16x32_bf16 v[14:17], v[22:25], v[14:17], v[26:29]
	v_mul_f32_e32 v75, 0xbfb8aa3b, v75
	v_mul_f32_e32 v76, 0xbfb8aa3b, v76
	v_mul_f32_e32 v77, 0xbfb8aa3b, v77
	ds_read_b128 v[26:29], v130 offset:36928
	v_mul_f32_e32 v78, 0xbfb8aa3b, v78
	v_mul_f32_e32 v79, 0xbfb8aa3b, v79
	v_mul_f32_e32 v80, 0xbfb8aa3b, v80
	v_mul_f32_e32 v81, 0xbfb8aa3b, v81
	v_cndmask_b32_e32 v92, v96, v97, vcc
	v_exp_f32_e32 v74, v74
	v_exp_f32_e32 v75, v75
	v_exp_f32_e32 v76, v76
	v_exp_f32_e32 v77, v77
	v_exp_f32_e32 v78, v78
	v_exp_f32_e32 v79, v79
	v_exp_f32_e32 v80, v80
	v_exp_f32_e32 v81, v81
	v_mul_f32_e32 v91, v92, v91
	v_sub_u32_e32 v92, v98, v119
	v_sub_u32_e32 v93, 0, v92
	v_max_i32_e32 v92, v92, v93
	v_cvt_f32_u32_e32 v92, v92
	v_pk_mul_f32 v[54:55], v[74:75], v[54:55]
	v_pk_mul_f32 v[56:57], v[76:77], v[56:57]
	v_pk_mul_f32 v[50:51], v[78:79], v[50:51]
	v_pk_mul_f32 v[52:53], v[80:81], v[52:53]
	v_cmp_lt_i32_e32 vcc, v98, v119
	v_cvt_pk_bf16_f32 v22, v54, v55
	v_cvt_pk_bf16_f32 v23, v56, v57
	v_cvt_pk_bf16_f32 v24, v50, v51
	v_cvt_pk_bf16_f32 v25, v52, v53
	v_cndmask_b32_e32 v93, v96, v97, vcc
	v_mul_f32_e32 v92, v93, v92
	s_waitcnt lgkmcnt(0)
	v_mfma_f32_16x16x32_bf16 v[8:11], v[26:29], v[22:25], v[10:13]
	ds_read_b128 v[26:29], v130 offset:41280
	v_sub_u32_e32 v93, v98, v120
	v_sub_u32_e32 v94, 0, v93
	v_max_i32_e32 v93, v93, v94
	v_cvt_f32_u32_e32 v93, v93
	v_cmp_lt_i32_e32 vcc, v98, v120
	s_waitcnt lgkmcnt(0)
	v_mfma_f32_16x16x32_bf16 v[4:7], v[26:29], v[22:25], v[4:7]
	v_cndmask_b32_e32 v94, v96, v97, vcc
	v_mul_f32_e32 v93, v94, v93
	v_sub_u32_e32 v94, v98, v121
	v_sub_u32_e32 v95, 0, v94
	ds_read_b128 v[26:29], v130 offset:45632
	v_max_i32_e32 v94, v94, v95
	v_cvt_f32_u32_e32 v94, v94
	v_cmp_lt_i32_e32 vcc, v98, v121
	s_waitcnt lgkmcnt(0)
	v_mfma_f32_16x16x32_bf16 v[18:21], v[26:29], v[22:25], v[18:21]
	v_cndmask_b32_e32 v95, v96, v97, vcc
	v_mul_f32_e32 v94, v95, v94
	v_sub_u32_e32 v95, v98, v123
	v_sub_u32_e32 v100, 0, v95
	v_max_i32_e32 v95, v95, v100
	v_cvt_f32_u32_e32 v95, v95
	ds_read_b128 v[26:29], v130 offset:49984
	v_cmp_lt_i32_e32 vcc, v98, v123
	s_waitcnt lgkmcnt(0)
	v_mfma_f32_16x16x32_bf16 v[12:15], v[26:29], v[22:25], v[14:17]
	v_cndmask_b32_e32 v100, v96, v97, vcc
	v_mul_f32_e32 v95, v100, v95
	v_sub_u32_e32 v100, v98, v124
	v_sub_u32_e32 v101, 0, v100
	v_max_i32_e32 v100, v100, v101
	v_cvt_f32_u32_e32 v100, v100
	v_cmp_lt_i32_e32 vcc, v98, v124
	ds_read_b128 v[26:29], v130 offset:36992
	v_mul_f32_e32 v86, 0xbfb8aa3b, v86
	v_cndmask_b32_e32 v101, v96, v97, vcc
	v_mul_f32_e32 v87, 0xbfb8aa3b, v87
	v_mul_f32_e32 v88, 0xbfb8aa3b, v88
	v_mul_f32_e32 v89, 0xbfb8aa3b, v89
	v_mul_f32_e32 v90, 0xbfb8aa3b, v90
	v_mul_f32_e32 v91, 0xbfb8aa3b, v91
	v_mul_f32_e32 v92, 0xbfb8aa3b, v92
	v_mul_f32_e32 v93, 0xbfb8aa3b, v93
	v_mul_f32_e32 v100, v101, v100
	v_sub_u32_e32 v101, v98, v125
	v_exp_f32_e32 v86, v86
	v_exp_f32_e32 v87, v87
	v_exp_f32_e32 v88, v88
	v_exp_f32_e32 v89, v89
	v_exp_f32_e32 v90, v90
	v_exp_f32_e32 v91, v91
	v_exp_f32_e32 v92, v92
	v_exp_f32_e32 v93, v93
	v_sub_u32_e32 v102, 0, v101
	v_max_i32_e32 v101, v101, v102
	v_cvt_f32_u32_e32 v101, v101
	v_cmp_lt_i32_e32 vcc, v98, v125
	v_pk_mul_f32 v[46:47], v[86:87], v[46:47]
	v_pk_mul_f32 v[48:49], v[88:89], v[48:49]
	v_pk_mul_f32 v[42:43], v[90:91], v[42:43]
	v_pk_mul_f32 v[44:45], v[92:93], v[44:45]
	v_cndmask_b32_e32 v102, v96, v97, vcc
	v_cvt_pk_bf16_f32 v22, v46, v47
	v_cvt_pk_bf16_f32 v23, v48, v49
	v_cvt_pk_bf16_f32 v24, v42, v43
	v_cvt_pk_bf16_f32 v25, v44, v45
	v_mul_f32_e32 v101, v102, v101
	v_sub_u32_e32 v102, v98, v126
	s_waitcnt lgkmcnt(0)
	v_mfma_f32_16x16x32_bf16 v[8:11], v[26:29], v[22:25], v[8:11]
	ds_read_b128 v[26:29], v130 offset:41344
	v_sub_u32_e32 v103, 0, v102
	v_max_i32_e32 v102, v102, v103
	v_cvt_f32_u32_e32 v102, v102
	v_cmp_lt_i32_e32 vcc, v98, v126
	s_waitcnt lgkmcnt(0)
	v_mfma_f32_16x16x32_bf16 v[4:7], v[26:29], v[22:25], v[4:7]
	v_cndmask_b32_e32 v103, v96, v97, vcc
	v_mul_f32_e32 v102, v103, v102
	v_sub_u32_e32 v103, v98, v127
	v_sub_u32_e32 v104, 0, v103
	v_max_i32_e32 v103, v103, v104
	ds_read_b128 v[26:29], v130 offset:45696
	v_cvt_f32_u32_e32 v103, v103
	v_cmp_lt_i32_e32 vcc, v98, v127
	s_waitcnt lgkmcnt(0)
	v_mfma_f32_16x16x32_bf16 v[18:21], v[26:29], v[22:25], v[18:21]
	v_cndmask_b32_e32 v104, v96, v97, vcc
	v_mul_f32_e32 v103, v104, v103
	v_sub_u32_e32 v104, v98, v128
	v_sub_u32_e32 v105, 0, v104
	v_max_i32_e32 v104, v104, v105
	v_cvt_f32_u32_e32 v104, v104
	ds_read_b128 v[26:29], v130 offset:50048
	v_cmp_lt_i32_e32 vcc, v98, v128
	s_waitcnt lgkmcnt(0)
	v_mfma_f32_16x16x32_bf16 v[22:25], v[26:29], v[22:25], v[12:15]
	v_cndmask_b32_e32 v105, v96, v97, vcc
	v_mul_f32_e32 v104, v105, v104
	v_sub_u32_e32 v105, v98, v129
	v_sub_u32_e32 v106, 0, v105
	v_max_i32_e32 v105, v105, v106
	v_cvt_f32_u32_e32 v105, v105
	v_cmp_lt_i32_e32 vcc, v98, v129
	ds_read_b128 v[12:15], v130 offset:37056
	v_mul_f32_e32 v94, 0xbfb8aa3b, v94
	v_cndmask_b32_e32 v106, v96, v97, vcc
	v_mul_f32_e32 v105, v106, v105
	v_mul_f32_e32 v95, 0xbfb8aa3b, v95
	v_mul_f32_e32 v100, 0xbfb8aa3b, v100
	v_mul_f32_e32 v101, 0xbfb8aa3b, v101
	v_mul_f32_e32 v102, 0xbfb8aa3b, v102
	v_mul_f32_e32 v103, 0xbfb8aa3b, v103
	v_mul_f32_e32 v104, 0xbfb8aa3b, v104
	v_mul_f32_e32 v105, 0xbfb8aa3b, v105
	v_exp_f32_e32 v94, v94
	v_exp_f32_e32 v95, v95
	v_exp_f32_e32 v100, v100
	v_exp_f32_e32 v101, v101
	v_exp_f32_e32 v102, v102
	v_exp_f32_e32 v103, v103
	v_exp_f32_e32 v104, v104
	v_exp_f32_e32 v105, v105
	v_pk_mul_f32 v[38:39], v[94:95], v[38:39]
	v_pk_mul_f32 v[34:35], v[102:103], v[34:35]
	v_pk_mul_f32 v[40:41], v[100:101], v[40:41]
	v_pk_mul_f32 v[2:3], v[104:105], v[36:37]
	v_cvt_pk_bf16_f32 v26, v38, v39
	v_cvt_pk_bf16_f32 v27, v40, v41
	v_cvt_pk_bf16_f32 v28, v34, v35
	v_cvt_pk_bf16_f32 v29, v2, v3
	s_waitcnt lgkmcnt(0)
	s_nop 0
	v_mfma_f32_16x16x32_bf16 v[14:17], v[12:15], v[26:29], v[8:11]
	s_nop 2
	ds_read_b128 v[8:11], v130 offset:41408
	s_waitcnt lgkmcnt(0)
	v_mfma_f32_16x16x32_bf16 v[10:13], v[8:11], v[26:29], v[4:7]
	s_nop 2
	ds_read_b128 v[2:5], v130 offset:45760
	s_waitcnt lgkmcnt(0)
	v_mfma_f32_16x16x32_bf16 v[6:9], v[2:5], v[26:29], v[18:21]
	ds_read_b128 v[2:5], v130 offset:50112
	s_nop 6
	v_pk_mul_f32 v[20:21], v[6:7], v[6:7]
	s_waitcnt lgkmcnt(0)
	v_mfma_f32_16x16x32_bf16 v[2:5], v[2:5], v[26:29], v[22:25]
	s_nop 2
	v_mul_f32_e32 v22, v15, v15
	v_fmac_f32_e32 v22, v14, v14
	v_fmac_f32_e32 v22, v16, v16
	v_fmac_f32_e32 v22, v17, v17
	v_fmac_f32_e32 v22, v10, v10
	v_fmac_f32_e32 v22, v11, v11
	v_fmac_f32_e32 v22, v12, v12
	v_fmac_f32_e32 v22, v13, v13
	v_add_f32_e32 v20, v20, v22
	v_pk_mul_f32 v[18:19], v[8:9], v[8:9]
	v_add_f32_e32 v20, v21, v20
	v_add_f32_e32 v18, v18, v20
	v_add_f32_e32 v22, v19, v18
	v_pk_mul_f32 v[20:21], v[2:3], v[2:3]
	v_pk_mul_f32 v[18:19], v[4:5], v[4:5]
	v_add_f32_e32 v20, v20, v22
	v_add_f32_e32 v20, v21, v20
	v_add_f32_e32 v18, v18, v20
	v_mad_i64_i32 v[20:21], s[6:7], v98, s52, v[82:83]
	v_lshl_add_u64 v[20:21], v[20:21], 0, v[84:85]
	v_lshl_add_u64 v[20:21], v[20:21], 0, v[0:1]
	global_load_dwordx2 v[22:23], v[20:21], off offset:1536
	v_add_f32_e32 v18, v19, v18
	ds_bpermute_b32 v19, v131, v18
	s_waitcnt lgkmcnt(0)
	v_add_f32_e32 v18, v18, v19
	ds_bpermute_b32 v19, v132, v18
	s_waitcnt lgkmcnt(0)
	v_add_f32_e32 v18, v18, v19
	v_fmamk_f32 v18, v18, 0x3c800000, v158
	v_cmp_gt_f32_e32 vcc, s66, v18
	v_mul_f32_e32 v19, 0x4b800000, v18
	s_waitcnt vmcnt(0)
	v_lshlrev_b32_e32 v24, 16, v22
	v_mul_f32_e32 v0, 0xbfb8aa3b, v24
	v_exp_f32_e32 v0, v0
	v_and_b32_e32 v25, 0xffff0000, v22
	v_cndmask_b32_e32 v18, v18, v19, vcc
	v_rsq_f32_e32 v18, v18
	v_add_f32_e32 v0, 1.0, v0
	v_rcp_f32_e32 v26, v0
	v_mul_f32_e32 v0, 0xbfb8aa3b, v25
	v_exp_f32_e32 v0, v0
	v_lshlrev_b32_e32 v22, 16, v23
	v_mul_f32_e32 v19, 0x45800000, v18
	v_cndmask_b32_e32 v18, v18, v19, vcc
	v_add_f32_e32 v0, 1.0, v0
	v_rcp_f32_e32 v27, v0
	v_mul_f32_e32 v0, 0xbfb8aa3b, v22
	v_exp_f32_e32 v0, v0
	v_and_b32_e32 v23, 0xffff0000, v23
	v_pk_mul_f32 v[24:25], v[26:27], v[24:25]
	v_add_f32_e32 v0, 1.0, v0
	v_pk_mul_f32 v[24:25], v[24:25], v[18:19] op_sel_hi:[1,0]
	s_nop 0
	v_pk_mul_f32 v[14:15], v[14:15], v[24:25]
	v_rcp_f32_e32 v24, v0
	v_mul_f32_e32 v0, 0xbfb8aa3b, v23
	v_exp_f32_e32 v0, v0
	v_cvt_pk_bf16_f32 v14, v14, v15
	v_add_f32_e32 v0, 1.0, v0
	v_rcp_f32_e32 v25, v0
	s_nop 0
	v_pk_mul_f32 v[22:23], v[24:25], v[22:23]
	s_nop 0
	v_pk_mul_f32 v[22:23], v[22:23], v[18:19] op_sel_hi:[1,0]
	s_nop 0
	v_pk_mul_f32 v[16:17], v[16:17], v[22:23]
	s_nop 0
	v_cvt_pk_bf16_f32 v15, v16, v17
	global_store_dwordx2 v[20:21], v[14:15], off offset:1536
	global_load_dwordx2 v[14:15], v[20:21], off offset:1568
	s_waitcnt vmcnt(0) lgkmcnt(0)
	v_lshlrev_b32_e32 v16, 16, v14
	v_mul_f32_e32 v0, 0xbfb8aa3b, v16
	v_exp_f32_e32 v0, v0
	v_and_b32_e32 v17, 0xffff0000, v14
	v_lshlrev_b32_e32 v14, 16, v15
	v_and_b32_e32 v15, 0xffff0000, v15
	v_add_f32_e32 v0, 1.0, v0
	v_rcp_f32_e32 v22, v0
	v_mul_f32_e32 v0, 0xbfb8aa3b, v17
	v_exp_f32_e32 v0, v0
	s_nop 0
	v_add_f32_e32 v0, 1.0, v0
	v_rcp_f32_e32 v23, v0
	v_mul_f32_e32 v0, 0xbfb8aa3b, v14
	v_exp_f32_e32 v0, v0
	v_pk_mul_f32 v[16:17], v[22:23], v[16:17]
	s_nop 0
	v_pk_mul_f32 v[16:17], v[16:17], v[18:19] op_sel_hi:[1,0]
	v_add_f32_e32 v0, 1.0, v0
	v_pk_mul_f32 v[10:11], v[10:11], v[16:17]
	v_rcp_f32_e32 v16, v0
	v_mul_f32_e32 v0, 0xbfb8aa3b, v15
	v_exp_f32_e32 v0, v0
	v_cvt_pk_bf16_f32 v10, v10, v11
	v_add_f32_e32 v0, 1.0, v0
	v_rcp_f32_e32 v17, v0
	s_nop 0
	v_pk_mul_f32 v[14:15], v[16:17], v[14:15]
	s_nop 0
	v_pk_mul_f32 v[14:15], v[14:15], v[18:19] op_sel_hi:[1,0]
	s_nop 0
	v_pk_mul_f32 v[12:13], v[12:13], v[14:15]
	s_nop 0
	v_cvt_pk_bf16_f32 v11, v12, v13
	global_store_dwordx2 v[20:21], v[10:11], off offset:1568
	global_load_dwordx2 v[10:11], v[20:21], off offset:1600
	s_waitcnt vmcnt(0) lgkmcnt(0)
	v_lshlrev_b32_e32 v12, 16, v10
	v_mul_f32_e32 v0, 0xbfb8aa3b, v12
	v_exp_f32_e32 v0, v0
	v_and_b32_e32 v13, 0xffff0000, v10
	v_lshlrev_b32_e32 v10, 16, v11
	v_and_b32_e32 v11, 0xffff0000, v11
	v_add_f32_e32 v0, 1.0, v0
	v_rcp_f32_e32 v14, v0
	v_mul_f32_e32 v0, 0xbfb8aa3b, v13
	v_exp_f32_e32 v0, v0
	s_nop 0
	v_add_f32_e32 v0, 1.0, v0
	v_rcp_f32_e32 v15, v0
	v_mul_f32_e32 v0, 0xbfb8aa3b, v10
	v_exp_f32_e32 v0, v0
	v_pk_mul_f32 v[12:13], v[14:15], v[12:13]
	s_nop 0
	v_pk_mul_f32 v[12:13], v[12:13], v[18:19] op_sel_hi:[1,0]
	v_add_f32_e32 v0, 1.0, v0
	v_pk_mul_f32 v[6:7], v[6:7], v[12:13]
	v_rcp_f32_e32 v12, v0
	v_mul_f32_e32 v0, 0xbfb8aa3b, v11
	v_exp_f32_e32 v0, v0
	v_cvt_pk_bf16_f32 v6, v6, v7
	v_add_f32_e32 v0, 1.0, v0
	v_rcp_f32_e32 v13, v0
	s_nop 0
	v_pk_mul_f32 v[10:11], v[12:13], v[10:11]
	s_nop 0
	v_pk_mul_f32 v[10:11], v[10:11], v[18:19] op_sel_hi:[1,0]
	s_nop 0
	v_pk_mul_f32 v[8:9], v[8:9], v[10:11]
	s_nop 0
	v_cvt_pk_bf16_f32 v7, v8, v9
	global_store_dwordx2 v[20:21], v[6:7], off offset:1600
	global_load_dwordx2 v[6:7], v[20:21], off offset:1632
	s_waitcnt vmcnt(0) lgkmcnt(0)
	v_lshlrev_b32_e32 v8, 16, v6
	v_mul_f32_e32 v0, 0xbfb8aa3b, v8
	v_exp_f32_e32 v0, v0
	v_and_b32_e32 v9, 0xffff0000, v6
	v_lshlrev_b32_e32 v6, 16, v7
	v_and_b32_e32 v7, 0xffff0000, v7
	v_add_f32_e32 v0, 1.0, v0
	v_rcp_f32_e32 v10, v0
	v_mul_f32_e32 v0, 0xbfb8aa3b, v9
	v_exp_f32_e32 v0, v0
	s_nop 0
	v_add_f32_e32 v0, 1.0, v0
	v_rcp_f32_e32 v11, v0
	v_mul_f32_e32 v0, 0xbfb8aa3b, v6
	v_exp_f32_e32 v0, v0
	v_pk_mul_f32 v[8:9], v[10:11], v[8:9]
	s_nop 0
	v_pk_mul_f32 v[8:9], v[18:19], v[8:9] op_sel_hi:[0,1]
	v_add_f32_e32 v0, 1.0, v0
	v_pk_mul_f32 v[2:3], v[2:3], v[8:9]
	v_rcp_f32_e32 v8, v0
	v_mul_f32_e32 v0, 0xbfb8aa3b, v7
	v_exp_f32_e32 v0, v0
	v_cvt_pk_bf16_f32 v2, v2, v3
	v_add_f32_e32 v0, 1.0, v0
	v_rcp_f32_e32 v9, v0
	s_nop 0
	v_pk_mul_f32 v[6:7], v[8:9], v[6:7]
	s_nop 0
	v_pk_mul_f32 v[6:7], v[18:19], v[6:7] op_sel_hi:[0,1]
	v_pk_mul_f32 v[4:5], v[4:5], v[6:7]
	s_nop 0
	v_cvt_pk_bf16_f32 v3, v4, v5
	global_store_dwordx2 v[20:21], v[2:3], off offset:1632

.LBB0_1939:
	s_andn2_saveexec_b64 s[2:3], s[2:3]
	s_cbranch_execz .LBB0_1941
	v_add_u32_e32 v3, 0xfffff0dc, v2
	v_lshlrev_b32_e32 v0, 5, v3
	v_and_b32_e32 v0, 0x1ff80, v0
	v_mul_u32_u24_e32 v0, 0xea0, v0
	v_lshlrev_b32_e32 v0, 1, v0
	s_mov_b64 s[52:53], s[76:77]
	v_and_b32_e32 v2, 3, v2
	v_lshl_add_u64 v[82:83], s[16:17], 0, v[0:1]
	v_lshlrev_b32_e32 v0, 13, v3
	v_mbcnt_lo_u32_b32 v3, -1, 0
	v_mbcnt_hi_u32_b32 v3, -1, v3
	s_mov_b64 s[54:55], s[78:79]
	s_mov_b64 s[58:59], s[82:83]
	s_mov_b64 s[60:61], s[84:85]
	v_readlane_b32 s72, v236, 24
	v_or_b32_e32 v50, s10, v3
	v_lshlrev_b32_e32 v3, 2, v2
	v_readlane_b32 s73, v236, 25
	s_mov_b32 s4, 0xbfb8aa3b
	v_readlane_b32 s74, v236, 26
	v_readlane_b32 s75, v236, 27
	s_mov_b32 s5, 0x42ce8ed0
	s_nop 0
	global_load_dword v4, v3, s[72:73] offset:16
	v_ashrrev_i32_e32 v21, 3, v50
	v_lshlrev_b32_e32 v84, 7, v2
	v_mov_b32_e32 v85, v1
	global_load_dword v3, v3, s[74:75] offset:16
	s_waitcnt lgkmcnt(0)
	s_barrier
	v_lshlrev_b32_e32 v20, 3, v50
	v_and_b32_e32 v93, 15, v50
	v_and_b32_e32 v51, 63, v50
	v_ashrrev_i32_e32 v48, 2, v50
	v_bfi_b32 v99, -16, v48, v50
	s_mov_b32 s8, 0x800000
	v_add_u32_e32 v98, 64, v99
	v_readlane_b32 s76, v236, 28
	v_readlane_b32 s77, v236, 29
	v_readlane_b32 s78, v236, 30
	v_readlane_b32 s79, v236, 31
	v_readlane_b32 s82, v236, 34
	v_readlane_b32 s83, v236, 35
	v_readlane_b32 s84, v236, 36
	v_readlane_b32 s85, v236, 37
	s_mov_b64 s[78:79], s[54:55]
	s_mov_b64 s[76:77], s[52:53]
	s_mov_b64 s[82:83], s[58:59]
	s_mov_b64 s[84:85], s[60:61]
	s_movk_i32 s52, 0x48
	v_readlane_b32 s80, v236, 32
	v_readlane_b32 s81, v236, 33
	v_readlane_b32 s86, v236, 38
	v_readlane_b32 s87, v236, 39
	s_waitcnt vmcnt(0)
	v_mul_f32_e32 v5, 0xbfb8aa3b, v4
	v_fma_f32 v6, v4, s4, -v5
	v_rndne_f32_e32 v7, v5
	v_fmac_f32_e32 v6, 0xb2a5705f, v4
	v_sub_f32_e32 v5, v5, v7
	v_add_f32_e32 v5, v5, v6
	v_exp_f32_e32 v5, v5
	v_cvt_i32_f32_e32 v6, v7
	v_cmp_nlt_f32_e32 vcc, s5, v4
	v_ldexp_f32 v5, v5, v6
	s_nop 0
	v_cndmask_b32_e32 v5, 0, v5, vcc
	v_cmp_ngt_f32_e32 vcc, s71, v4
	s_nop 1
	v_cndmask_b32_e32 v18, v160, v5, vcc
	v_add_f32_e32 v6, 1.0, v18
	v_add_f32_e32 v4, -1.0, v6
	v_sub_f32_e32 v5, v4, v6
	v_add_f32_e32 v5, 1.0, v5
	v_sub_f32_e32 v4, v18, v4
	v_add_f32_e32 v7, v4, v5
	v_frexp_mant_f32_e32 v4, v6
	v_cmp_gt_f32_e32 vcc, s21, v4
	v_cvt_f64_f32_e32 v[4:5], v6
	v_frexp_exp_i32_f64_e32 v4, v[4:5]
	v_subbrev_co_u32_e32 v12, vcc, 0, v4, vcc
	v_sub_u32_e32 v4, 0, v12
	v_ldexp_f32 v5, v6, v4
	v_add_f32_e32 v6, -1.0, v5
	v_add_f32_e32 v8, 1.0, v5
	v_ldexp_f32 v4, v7, v4
	v_add_f32_e32 v7, 1.0, v6
	v_add_f32_e32 v9, -1.0, v8
	v_sub_f32_e32 v7, v5, v7
	v_sub_f32_e32 v5, v5, v9
	v_add_f32_e32 v7, v4, v7
	v_add_f32_e32 v4, v4, v5
	v_add_f32_e32 v13, v8, v4
	v_rcp_f32_e32 v15, v13
	v_sub_f32_e32 v5, v8, v13
	v_add_f32_e32 v14, v4, v5
	v_add_f32_e32 v5, v6, v7
	v_mul_f32_e32 v17, v5, v15
	v_sub_f32_e32 v4, v6, v5
	v_mul_f32_e32 v6, v13, v17
	v_fma_f32 v8, v17, v13, -v6
	v_fmac_f32_e32 v8, v17, v14
	v_add_f32_e32 v16, v7, v4
	v_add_f32_e32 v4, v6, v8
	v_sub_f32_e32 v7, v5, v4
	v_pk_add_f32 v[10:11], v[4:5], v[6:7] neg_lo:[0,1] neg_hi:[0,1]
	v_mov_b32_e32 v9, v4
	v_pk_add_f32 v[4:5], v[10:11], v[8:9] neg_lo:[0,1] neg_hi:[0,1]
	v_cmp_neq_f32_e32 vcc, s93, v18
	v_add_f32_e32 v5, v16, v5
	v_add_f32_e32 v4, v4, v5
	v_add_f32_e32 v5, v7, v4
	v_mul_f32_e32 v16, v15, v5
	v_mul_f32_e32 v6, v13, v16
	v_fma_f32 v8, v16, v13, -v6
	v_fmac_f32_e32 v8, v16, v14
	v_sub_f32_e32 v7, v7, v5
	v_add_f32_e32 v13, v4, v7
	v_add_f32_e32 v4, v6, v8
	v_sub_f32_e32 v7, v5, v4
	v_pk_add_f32 v[10:11], v[4:5], v[6:7] neg_lo:[0,1] neg_hi:[0,1]
	v_mov_b32_e32 v9, v4
	v_pk_add_f32 v[4:5], v[10:11], v[8:9] neg_lo:[0,1] neg_hi:[0,1]
	s_nop 0
	v_add_f32_e32 v5, v13, v5
	v_add_f32_e32 v4, v4, v5
	v_add_f32_e32 v5, v17, v16
	v_add_f32_e32 v4, v7, v4
	v_sub_f32_e32 v6, v5, v17
	v_mul_f32_e32 v4, v15, v4
	v_sub_f32_e32 v6, v16, v6
	v_add_f32_e32 v6, v6, v4
	v_add_f32_e32 v8, v5, v6
	v_mul_f32_e32 v9, v8, v8
	v_fmamk_f32 v4, v9, 0x3e9b6dac, v157
	v_fmaak_f32 v123, v9, v4, 0x3f2aaada
	v_cvt_f32_i32_e32 v4, v12
	v_sub_f32_e32 v5, v8, v5
	v_sub_f32_e32 v5, v6, v5
	v_ldexp_f32 v10, v5, 1
	v_mul_f32_e32 v5, v8, v9
	v_ldexp_f32 v7, v8, 1
	v_pk_mul_f32 v[8:9], v[4:5], v[122:123]
	s_nop 0
	v_fma_f32 v6, v4, s56, -v8
	v_fmac_f32_e32 v6, 0xb102e308, v4
	v_pk_add_f32 v[4:5], v[8:9], v[6:7]
	s_nop 0
	v_sub_f32_e32 v7, v5, v7
	v_sub_f32_e32 v7, v9, v7
	v_add_f32_e32 v11, v10, v7
	v_mov_b32_e32 v10, v8
	v_pk_add_f32 v[8:9], v[4:5], v[8:9] neg_lo:[0,1] neg_hi:[0,1]
	v_pk_add_f32 v[12:13], v[4:5], v[10:11]
	v_mov_b32_e32 v7, v4
	v_mov_b32_e32 v9, v13
	v_pk_add_f32 v[14:15], v[6:7], v[8:9] neg_lo:[0,1] neg_hi:[0,1]
	v_pk_add_f32 v[6:7], v[6:7], v[8:9]
	v_mov_b32_e32 v10, v11
	v_pk_add_f32 v[8:9], v[6:7], v[4:5] op_sel:[1,0] op_sel_hi:[0,1] neg_lo:[0,1] neg_hi:[0,1]
	v_pk_add_f32 v[16:17], v[12:13], v[8:9] op_sel_hi:[1,0] neg_lo:[0,1] neg_hi:[0,1]
	v_mov_b32_e32 v12, v13
	v_mov_b32_e32 v13, v7
	v_pk_mov_b32 v[8:9], v[4:5], v[8:9] op_sel:[1,0]
	v_mov_b32_e32 v11, v4
	v_pk_add_f32 v[8:9], v[12:13], v[8:9] neg_lo:[0,1] neg_hi:[0,1]
	v_mov_b32_e32 v16, v14
	v_pk_add_f32 v[4:5], v[10:11], v[8:9] neg_lo:[0,1] neg_hi:[0,1]
	v_mov_b32_e32 v15, v7
	v_pk_add_f32 v[8:9], v[16:17], v[4:5]
	s_nop 0
	v_pk_add_f32 v[10:11], v[8:9], v[8:9] op_sel:[0,1] op_sel_hi:[1,0]
	s_nop 0
	v_pk_add_f32 v[6:7], v[6:7], v[10:11] op_sel:[1,0] op_sel_hi:[0,1]
	v_mov_b32_e32 v9, v6
	v_pk_add_f32 v[12:13], v[8:9], v[14:15] neg_lo:[0,1] neg_hi:[0,1]
	v_mov_b32_e32 v5, v10
	v_sub_f32_e32 v7, v8, v12
	v_pk_add_f32 v[4:5], v[4:5], v[12:13] neg_lo:[0,1] neg_hi:[0,1]
	v_sub_f32_e32 v7, v14, v7
	v_add_f32_e32 v4, v4, v7
	v_add_f32_e32 v4, v4, v5
	v_add_f32_e32 v4, v6, v4
	v_cndmask_b32_e32 v4, v160, v4, vcc
	v_cmp_lt_f32_e64 vcc, |v18|, s96
	s_nop 1
	v_cndmask_b32_e32 v96, v4, v18, vcc
	v_mul_f32_e32 v4, 0xbfb8aa3b, v3
	v_fma_f32 v5, v3, s4, -v4
	v_rndne_f32_e32 v6, v4
	v_fmac_f32_e32 v5, 0xb2a5705f, v3
	v_sub_f32_e32 v4, v4, v6
	v_add_f32_e32 v4, v4, v5
	v_exp_f32_e32 v4, v4
	v_cvt_i32_f32_e32 v5, v6
	v_cmp_nlt_f32_e32 vcc, s5, v3
	v_ldexp_f32 v4, v4, v5
	s_nop 0
	v_cndmask_b32_e32 v4, 0, v4, vcc
	v_cmp_ngt_f32_e32 vcc, s71, v3
	s_nop 1
	v_cndmask_b32_e32 v3, v160, v4, vcc
	v_add_f32_e32 v6, 1.0, v3
	v_add_f32_e32 v4, -1.0, v6
	v_sub_f32_e32 v5, v4, v6
	v_add_f32_e32 v5, 1.0, v5
	v_sub_f32_e32 v4, v3, v4
	v_add_f32_e32 v7, v4, v5
	v_frexp_mant_f32_e32 v4, v6
	v_cmp_gt_f32_e32 vcc, s21, v4
	v_cvt_f64_f32_e32 v[4:5], v6
	v_frexp_exp_i32_f64_e32 v4, v[4:5]
	v_subbrev_co_u32_e32 v12, vcc, 0, v4, vcc
	v_sub_u32_e32 v4, 0, v12
	v_ldexp_f32 v5, v6, v4
	v_add_f32_e32 v6, -1.0, v5
	v_add_f32_e32 v8, 1.0, v5
	v_ldexp_f32 v4, v7, v4
	v_add_f32_e32 v7, 1.0, v6
	v_add_f32_e32 v9, -1.0, v8
	v_sub_f32_e32 v7, v5, v7
	v_sub_f32_e32 v5, v5, v9
	v_add_f32_e32 v7, v4, v7
	v_add_f32_e32 v4, v4, v5
	v_add_f32_e32 v13, v8, v4
	v_rcp_f32_e32 v15, v13
	v_sub_f32_e32 v5, v8, v13
	v_add_f32_e32 v14, v4, v5
	v_add_f32_e32 v5, v6, v7
	v_mul_f32_e32 v17, v5, v15
	v_sub_f32_e32 v4, v6, v5
	v_mul_f32_e32 v6, v13, v17
	v_fma_f32 v8, v17, v13, -v6
	v_fmac_f32_e32 v8, v17, v14
	v_add_f32_e32 v16, v7, v4
	v_add_f32_e32 v4, v6, v8
	v_sub_f32_e32 v7, v5, v4
	v_pk_add_f32 v[10:11], v[4:5], v[6:7] neg_lo:[0,1] neg_hi:[0,1]
	v_mov_b32_e32 v9, v4
	v_pk_add_f32 v[4:5], v[10:11], v[8:9] neg_lo:[0,1] neg_hi:[0,1]
	v_cmp_neq_f32_e32 vcc, s93, v3
	v_add_f32_e32 v5, v16, v5
	v_add_f32_e32 v4, v4, v5
	v_add_f32_e32 v5, v7, v4
	v_mul_f32_e32 v16, v15, v5
	v_mul_f32_e32 v6, v13, v16
	v_fma_f32 v8, v16, v13, -v6
	v_fmac_f32_e32 v8, v16, v14
	v_sub_f32_e32 v7, v7, v5
	v_add_f32_e32 v13, v4, v7
	v_add_f32_e32 v4, v6, v8
	v_sub_f32_e32 v7, v5, v4
	v_pk_add_f32 v[10:11], v[4:5], v[6:7] neg_lo:[0,1] neg_hi:[0,1]
	v_mov_b32_e32 v9, v4
	v_pk_add_f32 v[4:5], v[10:11], v[8:9] neg_lo:[0,1] neg_hi:[0,1]
	s_nop 0
	v_add_f32_e32 v5, v13, v5
	v_add_f32_e32 v4, v4, v5
	v_add_f32_e32 v5, v17, v16
	v_add_f32_e32 v4, v7, v4
	v_sub_f32_e32 v6, v5, v17
	v_mul_f32_e32 v4, v15, v4
	v_sub_f32_e32 v6, v16, v6
	v_add_f32_e32 v6, v6, v4
	v_add_f32_e32 v8, v5, v6
	v_mul_f32_e32 v9, v8, v8
	v_fmamk_f32 v4, v9, 0x3e9b6dac, v157
	v_fmaak_f32 v123, v9, v4, 0x3f2aaada
	v_cvt_f32_i32_e32 v4, v12
	v_sub_f32_e32 v5, v8, v5
	v_sub_f32_e32 v5, v6, v5
	v_ldexp_f32 v10, v5, 1
	v_mul_f32_e32 v5, v8, v9
	v_ldexp_f32 v7, v8, 1
	v_pk_mul_f32 v[8:9], v[4:5], v[122:123]
	s_nop 0
	v_fma_f32 v6, v4, s56, -v8
	v_fmac_f32_e32 v6, 0xb102e308, v4
	v_pk_add_f32 v[4:5], v[8:9], v[6:7]
	s_nop 0
	v_sub_f32_e32 v7, v5, v7
	v_sub_f32_e32 v7, v9, v7
	v_add_f32_e32 v11, v10, v7
	v_mov_b32_e32 v10, v8
	v_pk_add_f32 v[8:9], v[4:5], v[8:9] neg_lo:[0,1] neg_hi:[0,1]
	v_pk_add_f32 v[12:13], v[4:5], v[10:11]
	v_mov_b32_e32 v7, v4
	v_mov_b32_e32 v9, v13
	v_pk_add_f32 v[14:15], v[6:7], v[8:9] neg_lo:[0,1] neg_hi:[0,1]
	v_pk_add_f32 v[6:7], v[6:7], v[8:9]
	v_mov_b32_e32 v10, v11
	v_pk_add_f32 v[8:9], v[6:7], v[4:5] op_sel:[1,0] op_sel_hi:[0,1] neg_lo:[0,1] neg_hi:[0,1]
	v_pk_add_f32 v[16:17], v[12:13], v[8:9] op_sel_hi:[1,0] neg_lo:[0,1] neg_hi:[0,1]
	v_mov_b32_e32 v12, v13
	v_mov_b32_e32 v13, v7
	v_pk_mov_b32 v[8:9], v[4:5], v[8:9] op_sel:[1,0]
	v_mov_b32_e32 v11, v4
	v_pk_add_f32 v[8:9], v[12:13], v[8:9] neg_lo:[0,1] neg_hi:[0,1]
	v_mov_b32_e32 v16, v14
	v_pk_add_f32 v[4:5], v[10:11], v[8:9] neg_lo:[0,1] neg_hi:[0,1]
	v_mov_b32_e32 v15, v7
	v_pk_add_f32 v[8:9], v[16:17], v[4:5]
	s_nop 0
	v_pk_add_f32 v[10:11], v[8:9], v[8:9] op_sel:[0,1] op_sel_hi:[1,0]
	s_nop 0
	v_pk_add_f32 v[6:7], v[6:7], v[10:11] op_sel:[1,0] op_sel_hi:[0,1]
	v_mov_b32_e32 v9, v6
	v_pk_add_f32 v[12:13], v[8:9], v[14:15] neg_lo:[0,1] neg_hi:[0,1]
	v_mov_b32_e32 v5, v10
	v_sub_f32_e32 v7, v8, v12
	v_pk_add_f32 v[4:5], v[4:5], v[12:13] neg_lo:[0,1] neg_hi:[0,1]
	v_sub_f32_e32 v7, v14, v7
	v_add_f32_e32 v4, v4, v7
	v_add_f32_e32 v4, v4, v5
	v_add_f32_e32 v4, v6, v4
	v_cndmask_b32_e32 v4, v160, v4, vcc
	v_cmp_lt_f32_e64 vcc, |v3|, s96
	v_mov_b32_e32 v11, v1
	s_nop 0
	v_cndmask_b32_e32 v97, v4, v3, vcc
	v_lshlrev_b32_e32 v3, 4, v50
	v_mad_i64_i32 v[4:5], s[4:5], v21, s33, v[82:83]
	v_and_b32_e32 v10, 0x70, v3
	v_lshl_add_u64 v[2:3], v[4:5], 0, v[84:85]
	v_lshl_add_u64 v[6:7], v[2:3], 0, v[10:11]
	global_load_dwordx4 v[172:175], v[6:7], off
	v_add_u32_e32 v12, s92, v10
	v_mad_u64_u32 v[8:9], s[4:5], v21, s97, v[12:13]
	s_nop 0
	v_mov_b32_e32 v206, v8
	global_load_dwordx4 v[176:179], v[6:7], off offset:512
	s_nop 0
	v_mov_b32_e32 v207, v8
	v_add_u32_e32 v8, 0x100, v50
	v_ashrrev_i32_e32 v9, 3, v8
	v_mad_i64_i32 v[2:3], s[4:5], v9, s33, v[82:83]
	v_lshl_add_u64 v[2:3], v[2:3], 0, v[84:85]
	v_lshl_add_u64 v[6:7], v[2:3], 0, v[10:11]
	global_load_dwordx4 v[180:183], v[6:7], off
	v_mad_u64_u32 v[14:15], s[4:5], v9, s97, v[12:13]
	s_nop 0
	v_mov_b32_e32 v208, v14
	global_load_dwordx4 v[184:187], v[6:7], off offset:512
	v_add_u32_e32 v7, 0x200, v50
	v_add_u32_e32 v6, 0x300, v50
	s_nop 0
	v_mov_b32_e32 v209, v14
	v_ashrrev_i32_e32 v4, 3, v7
	v_mad_i64_i32 v[2:3], s[4:5], v4, s33, v[82:83]
	v_lshl_add_u64 v[2:3], v[2:3], 0, v[84:85]
	v_lshl_add_u64 v[14:15], v[2:3], 0, v[10:11]
	v_mad_u64_u32 v[16:17], s[4:5], v4, s97, v[12:13]
	global_load_dwordx4 v[188:191], v[14:15], off
	v_ashrrev_i32_e32 v7, 4, v7
	s_nop 0
	v_mov_b32_e32 v210, v16
	global_load_dwordx4 v[192:195], v[14:15], off offset:512
	s_nop 0
	v_mov_b32_e32 v211, v16
	v_ashrrev_i32_e32 v4, 3, v6
	v_mad_i64_i32 v[2:3], s[4:5], v4, s33, v[82:83]
	v_lshl_add_u64 v[2:3], v[2:3], 0, v[84:85]
	v_lshl_add_u64 v[10:11], v[2:3], 0, v[10:11]
	v_mad_u64_u32 v[12:13], s[4:5], v4, s97, v[12:13]
	global_load_dwordx4 v[196:199], v[10:11], off
	s_mov_b64 s[4:5], 0x2140
	s_nop 0
	v_mov_b32_e32 v212, v12
	global_load_dwordx4 v[200:203], v[10:11], off offset:512
	v_and_b32_e32 v10, 48, v20
	v_and_b32_e32 v20, -8, v21
	v_ashrrev_i32_e32 v21, 31, v20
	v_and_b32_e32 v11, 8, v50
	v_lshlrev_b64 v[14:15], 1, v[20:21]
	s_waitcnt vmcnt(0) lgkmcnt(0)
	ds_write_b128 v206, v[172:175]
	ds_write_b128 v207, v[176:179] offset:18432
	ds_write_b128 v208, v[180:183]
	ds_write_b128 v209, v[184:187] offset:18432
	ds_write_b128 v210, v[188:191]
	ds_write_b128 v211, v[192:195] offset:18432
	ds_write_b128 v212, v[196:199]
	ds_write_b128 v12, v[200:203] offset:18432
	v_lshlrev_b32_e32 v2, 1, v50
	v_and_b32_e32 v2, 0x7e, v2
	v_mul_u32_u24_e32 v2, 0xea0, v2
	v_lshlrev_b32_e32 v2, 1, v2
	v_mov_b32_e32 v3, v1
	v_lshlrev_b32_e32 v5, 2, v50
	v_lshl_add_u64 v[2:3], v[82:83], 0, v[2:3]
	v_and_b32_e32 v4, 0xc4, v5
	v_lshl_add_u64 v[18:19], v[2:3], 0, v[84:85]
	v_add_u32_e32 v4, s92, v4
	v_lshl_add_u64 v[2:3], v[18:19], 0, s[4:5]
	v_add3_u32 v4, v4, v10, v11
	v_lshl_add_u64 v[10:11], v[18:19], 0, v[14:15]
	global_load_dwordx4 v[10:13], v[10:11], off offset:1024
	v_lshl_add_u64 v[14:15], v[2:3], 0, v[14:15]
	global_load_dwordx4 v[14:17], v[14:15], off
	s_waitcnt vmcnt(0) lgkmcnt(0)
	v_and_b32_e32 v21, 0xffff, v10
	v_lshrrev_b32_e32 v10, 16, v10
	v_lshl_or_b32 v22, v14, 16, v21
	v_mad_u64_u32 v[20:21], s[4:5], v20, s19, v[4:5]
	v_and_or_b32 v10, v14, s57, v10
	v_add_u32_e32 v14, 0x9000, v20
	ds_write2_b32 v14, v22, v10 offset1:68
	v_and_b32_e32 v10, 0xffff, v11
	v_lshrrev_b32_e32 v11, 16, v11
	v_lshl_or_b32 v10, v15, 16, v10
	v_and_or_b32 v11, v15, s57, v11
	ds_write2_b32 v14, v10, v11 offset0:136 offset1:204
	v_and_b32_e32 v10, 0xffff, v12
	v_lshrrev_b32_e32 v11, 16, v12
	v_lshl_or_b32 v10, v16, 16, v10
	v_and_or_b32 v11, v16, s57, v11
	v_add_u32_e32 v12, 0x9400, v20
	v_and_b32_e32 v20, -8, v9
	ds_write2_b32 v12, v10, v11 offset0:16 offset1:84
	v_and_b32_e32 v10, 0xffff, v13
	v_lshrrev_b32_e32 v11, 16, v13
	v_ashrrev_i32_e32 v21, 31, v20
	v_lshl_or_b32 v10, v17, 16, v10
	v_and_or_b32 v11, v17, s57, v11
	v_lshlrev_b64 v[14:15], 1, v[20:21]
	ds_write2_b32 v12, v10, v11 offset0:152 offset1:220
	v_lshl_add_u64 v[10:11], v[18:19], 0, v[14:15]
	global_load_dwordx4 v[10:13], v[10:11], off offset:1024
	v_lshl_add_u64 v[2:3], v[2:3], 0, v[14:15]
	global_load_dwordx4 v[14:17], v[2:3], off
	s_waitcnt vmcnt(0) lgkmcnt(0)
	v_and_b32_e32 v2, 0xffff, v10
	v_lshl_or_b32 v9, v14, 16, v2
	v_mad_u64_u32 v[2:3], s[4:5], v20, s19, v[4:5]
	v_lshrrev_b32_e32 v3, 16, v10
	v_and_or_b32 v3, v14, s57, v3
	v_add_u32_e32 v4, 0x9000, v2
	ds_write2_b32 v4, v9, v3 offset1:68
	v_and_b32_e32 v3, 0xffff, v11
	v_lshrrev_b32_e32 v9, 16, v11
	v_lshl_or_b32 v3, v15, 16, v3
	v_and_or_b32 v9, v15, s57, v9
	ds_write2_b32 v4, v3, v9 offset0:136 offset1:204
	v_and_b32_e32 v3, 0xffff, v12
	v_lshrrev_b32_e32 v4, 16, v12
	v_lshl_or_b32 v3, v16, 16, v3
	v_and_or_b32 v4, v16, s57, v4
	v_add_u32_e32 v2, 0x9400, v2
	ds_write2_b32 v2, v3, v4 offset0:16 offset1:84
	v_and_b32_e32 v3, 0xffff, v13
	v_lshrrev_b32_e32 v4, 16, v13
	v_lshl_or_b32 v3, v17, 16, v3
	v_and_or_b32 v4, v17, s57, v4
	v_and_b32_e32 v9, 60, v5
	ds_write2_b32 v2, v3, v4 offset0:152 offset1:220
	v_lshl_add_u64 v[2:3], v[0:1], 2, s[94:95]
	v_lshlrev_b32_e32 v0, 2, v9
	v_lshl_add_u64 v[2:3], v[2:3], 0, v[0:1]
	v_lshl_add_u32 v0, v9, 1, s92
	v_ashrrev_i32_e32 v9, 4, v50
	v_lshlrev_b32_e32 v10, 6, v9
	s_mov_b64 s[4:5], 0x4000
	v_ashrrev_i32_e32 v11, 31, v10
	v_lshl_add_u64 v[4:5], v[2:3], 0, s[4:5]
	v_lshlrev_b64 v[14:15], 2, v[10:11]
	v_lshl_add_u64 v[10:11], v[2:3], 0, v[14:15]
	v_lshl_add_u64 v[14:15], v[4:5], 0, v[14:15]
	global_load_dwordx4 v[10:13], v[10:11], off
	s_nop 0
	global_load_dwordx4 v[14:17], v[14:15], off
	s_waitcnt vmcnt(0) lgkmcnt(0)
	v_cvt_pk_bf16_f32 v10, v10, v11
	v_cvt_pk_bf16_f32 v11, v12, v13
	v_cvt_pk_bf16_f32 v14, v14, v15
	v_cvt_pk_bf16_f32 v15, v16, v17
	v_ashrrev_i32_e32 v16, 4, v8
	v_lshlrev_b32_e32 v8, 6, v16
	v_mad_u64_u32 v[12:13], s[4:5], v9, s97, v[0:1]
	v_ashrrev_i32_e32 v9, 31, v8
	ds_write2st64_b64 v12, v[10:11], v[14:15] offset0:106 offset1:124
	v_lshlrev_b64 v[12:13], 2, v[8:9]
	v_lshl_add_u64 v[8:9], v[2:3], 0, v[12:13]
	v_lshl_add_u64 v[12:13], v[4:5], 0, v[12:13]
	global_load_dwordx4 v[8:11], v[8:9], off
	s_nop 0
	global_load_dwordx4 v[12:15], v[12:13], off
	s_waitcnt vmcnt(0) lgkmcnt(0)
	v_cvt_pk_bf16_f32 v8, v8, v9
	v_cvt_pk_bf16_f32 v9, v10, v11
	v_mad_u64_u32 v[10:11], s[4:5], v16, s97, v[0:1]
	v_cvt_pk_bf16_f32 v12, v12, v13
	v_cvt_pk_bf16_f32 v13, v14, v15
	ds_write2st64_b64 v10, v[8:9], v[12:13] offset0:106 offset1:124
	v_lshlrev_b32_e32 v8, 6, v7
	v_ashrrev_i32_e32 v9, 31, v8
	v_lshlrev_b64 v[12:13], 2, v[8:9]
	v_lshl_add_u64 v[8:9], v[2:3], 0, v[12:13]
	v_lshl_add_u64 v[12:13], v[4:5], 0, v[12:13]
	global_load_dwordx4 v[8:11], v[8:9], off
	s_nop 0
	global_load_dwordx4 v[12:15], v[12:13], off
	s_waitcnt vmcnt(0) lgkmcnt(0)
	v_cvt_pk_bf16_f32 v8, v8, v9
	v_cvt_pk_bf16_f32 v9, v10, v11
	v_mad_u64_u32 v[10:11], s[4:5], v7, s97, v[0:1]
	v_cvt_pk_bf16_f32 v12, v12, v13
	v_cvt_pk_bf16_f32 v13, v14, v15
	ds_write2st64_b64 v10, v[8:9], v[12:13] offset0:106 offset1:124
	v_ashrrev_i32_e32 v12, 4, v6
	v_lshlrev_b32_e32 v6, 6, v12
	v_ashrrev_i32_e32 v7, 31, v6
	v_lshlrev_b64 v[10:11], 2, v[6:7]
	v_lshl_add_u64 v[2:3], v[2:3], 0, v[10:11]
	global_load_dwordx4 v[6:9], v[2:3], off
	v_lshl_add_u64 v[2:3], v[4:5], 0, v[10:11]
	global_load_dwordx4 v[2:5], v[2:3], off
	v_and_b32_e32 v14, 48, v50
	s_waitcnt vmcnt(0) lgkmcnt(0)
	v_cvt_pk_bf16_f32 v6, v6, v7
	v_cvt_pk_bf16_f32 v7, v8, v9
	v_mad_u64_u32 v[8:9], s[4:5], v12, s97, v[0:1]
	v_cvt_pk_bf16_f32 v2, v2, v3
	v_cvt_pk_bf16_f32 v3, v4, v5
	v_mul_u32_u24_e32 v0, 0x48, v93
	ds_write2st64_b64 v8, v[6:7], v[2:3] offset0:106 offset1:124
	v_lshlrev_b32_e32 v2, 1, v0
	v_add_u32_e32 v0, s92, v14
	v_and_b32_e32 v12, -16, v48
	v_add_u32_e32 v13, s92, v2
	v_add_u32_e32 v88, v0, v2
	v_or_b32_e32 v2, 48, v51
	v_mul_u32_u24_e32 v2, 0x48, v2
	v_mul_lo_u32 v12, v12, s97
	v_lshl_add_u32 v89, v2, 1, v0
	v_mov_b32_e32 v2, v1
	v_mov_b32_e32 v6, v1
	v_add3_u32 v90, v13, v14, v12
	s_waitcnt lgkmcnt(0)
	s_barrier
	ds_read_b128 v[12:15], v90
	ds_read_b128 v[16:19], v88 offset:54272
	ds_read_b128 v[20:23], v88 offset:56576
	ds_read_b128 v[24:27], v88 offset:58880
	ds_read_b128 v[28:31], v89 offset:54272
	v_mov_b32_e32 v3, v2
	v_mov_b32_e32 v4, v2
	v_mov_b32_e32 v5, v2
	v_add_u32_e32 v11, 0xf800, v88
	v_mov_b32_e32 v7, v6
	s_waitcnt lgkmcnt(3)
	v_mfma_f32_16x16x32_bf16 v[16:19], v[16:19], v[12:15], v[2:5]
	v_mov_b32_e32 v8, v6
	v_mov_b32_e32 v9, v6
	v_add_u32_e32 v10, 0xf840, v88
	s_waitcnt lgkmcnt(2)
	v_mfma_f32_16x16x32_bf16 v[20:23], v[20:23], v[12:15], v[2:5]
	v_or_b32_e32 v51, 0x70, v51
	v_mul_u32_u24_e32 v51, 0x48, v51
	v_lshl_add_u32 v92, v51, 1, v0
	s_waitcnt lgkmcnt(1)
	v_mfma_f32_16x16x32_bf16 v[24:27], v[24:27], v[12:15], v[2:5]
	v_lshrrev_b32_e32 v0, 2, v50
	v_mov_b32_e32 v50, v1
	v_and_b32_e32 v91, 12, v0
	s_waitcnt lgkmcnt(0)
	v_mfma_f32_16x16x32_bf16 v[2:5], v[28:31], v[12:15], v[2:5]
	ds_read_b128 v[28:31], v90 offset:64
	ds_read_b128 v[32:35], v88 offset:54336
	ds_read_b128 v[36:39], v88 offset:56640
	ds_read_b128 v[40:43], v88 offset:58944
	ds_read_b128 v[44:47], v89 offset:54336
	v_sub_u32_e32 v0, v99, v91
	v_sub_u32_e32 v86, 0, v0
	s_waitcnt lgkmcnt(3)
	v_mfma_f32_16x16x32_bf16 v[16:19], v[32:35], v[28:31], v[16:19]
	v_max_i32_e32 v0, v0, v86
	v_cvt_f32_u32_e32 v0, v0
	v_cmp_lt_i32_e32 vcc, v99, v91
	s_waitcnt lgkmcnt(2)
	v_mfma_f32_16x16x32_bf16 v[20:23], v[36:39], v[28:31], v[20:23]
	v_or_b32_e32 v94, 16, v91
	v_cndmask_b32_e32 v86, v96, v97, vcc
	v_mul_f32_e32 v0, v86, v0
	s_waitcnt lgkmcnt(1)
	v_mfma_f32_16x16x32_bf16 v[24:27], v[40:43], v[28:31], v[24:27]
	v_mul_f32_e32 v0, 0xbfb8aa3b, v0
	v_exp_f32_e32 v86, v0
	v_cmp_gt_i32_e32 vcc, v99, v91
	s_waitcnt lgkmcnt(0)
	v_mfma_f32_16x16x32_bf16 v[2:5], v[44:47], v[28:31], v[2:5]
	ds_read_b128 v[32:35], v88 offset:63488
	ds_read_b128 v[36:39], v11 offset:2304
	ds_read_b128 v[40:43], v11 offset:4608
	ds_read_b128 v[44:47], v89 offset:63488
	v_or_b32_e32 v95, 17, v91
	v_or_b32_e32 v120, 0x53, v91
	s_waitcnt lgkmcnt(3)
	v_mfma_f32_16x16x32_bf16 v[32:35], v[32:35], v[12:15], v[6:9]
	v_or_b32_e32 v121, 0x60, v91
	v_or_b32_e32 v123, 0x61, v91
	s_waitcnt lgkmcnt(2)
	v_mfma_f32_16x16x32_bf16 v[36:39], v[36:39], v[12:15], v[6:9]
	s_waitcnt lgkmcnt(1)
	v_mfma_f32_16x16x32_bf16 v[40:43], v[40:43], v[12:15], v[6:9]
	s_waitcnt lgkmcnt(0)
	v_mfma_f32_16x16x32_bf16 v[6:9], v[44:47], v[12:15], v[6:9]
	ds_read_b128 v[12:15], v88 offset:63552
	ds_read_b128 v[44:47], v10 offset:2304
	ds_read_b128 v[52:55], v10 offset:4608
	ds_read_b128 v[56:59], v89 offset:63552
	s_waitcnt lgkmcnt(3)
	v_mfma_f32_16x16x32_bf16 v[12:15], v[12:15], v[28:31], v[32:35]
	s_waitcnt lgkmcnt(2)
	v_mfma_f32_16x16x32_bf16 v[44:47], v[44:47], v[28:31], v[36:39]
	s_waitcnt lgkmcnt(1)
	v_mfma_f32_16x16x32_bf16 v[52:55], v[52:55], v[28:31], v[40:43]
	s_waitcnt lgkmcnt(0)
	v_mfma_f32_16x16x32_bf16 v[6:9], v[56:59], v[28:31], v[6:9]
	v_sub_u32_e32 v29, 0x80, v99
	v_add_u32_e32 v28, 1, v99
	v_cvt_f32_i32_e32 v29, v29
	v_cvt_f32_i32_e32 v28, v28
	v_mul_f32_e32 v29, v29, v97
	v_mul_f32_e32 v28, v28, v96
	v_mul_f32_e32 v29, 0xbfb8aa3b, v29
	v_mul_f32_e32 v28, 0xbfb8aa3b, v28
	v_exp_f32_e32 v30, v29
	v_exp_f32_e32 v28, v28
	v_pk_mul_f32 v[12:13], v[30:31], v[12:13] op_sel_hi:[0,1]
	v_pk_mul_f32 v[14:15], v[30:31], v[14:15] op_sel_hi:[0,1]
	v_pk_fma_f32 v[34:35], v[28:29], v[16:17], v[12:13] op_sel_hi:[0,1,1]
	v_pk_mul_f32 v[12:13], v[30:31], v[44:45] op_sel_hi:[0,1]
	v_pk_fma_f32 v[36:37], v[28:29], v[18:19], v[14:15] op_sel_hi:[0,1,1]
	v_pk_mul_f32 v[14:15], v[30:31], v[46:47] op_sel_hi:[0,1]
	v_pk_fma_f32 v[38:39], v[28:29], v[20:21], v[12:13] op_sel_hi:[0,1,1]
	v_pk_mul_f32 v[12:13], v[30:31], v[52:53] op_sel_hi:[0,1]
	v_pk_mul_f32 v[6:7], v[30:31], v[6:7] op_sel_hi:[0,1]
	v_pk_fma_f32 v[40:41], v[28:29], v[22:23], v[14:15] op_sel_hi:[0,1,1]
	v_pk_mul_f32 v[14:15], v[30:31], v[54:55] op_sel_hi:[0,1]
	v_pk_fma_f32 v[42:43], v[28:29], v[24:25], v[12:13] op_sel_hi:[0,1,1]
	v_pk_mul_f32 v[8:9], v[30:31], v[8:9] op_sel_hi:[0,1]
	v_pk_fma_f32 v[46:47], v[28:29], v[2:3], v[6:7] op_sel_hi:[0,1,1]
	v_mov_b32_e32 v2, v1
	v_mov_b32_e32 v12, v1
	v_pk_fma_f32 v[44:45], v[28:29], v[26:27], v[14:15] op_sel_hi:[0,1,1]
	v_pk_fma_f32 v[48:49], v[28:29], v[4:5], v[8:9] op_sel_hi:[0,1,1]
	ds_read_b128 v[22:25], v90 offset:9216
	ds_read_b128 v[6:9], v88 offset:54272
	ds_read_b128 v[16:19], v88 offset:56576
	ds_read_b128 v[26:29], v88 offset:58880
	ds_read_b128 v[30:33], v89 offset:54272
	v_mov_b32_e32 v3, v2
	v_mov_b32_e32 v4, v2
	v_mov_b32_e32 v5, v2
	v_mov_b32_e32 v13, v12
	v_mov_b32_e32 v14, v12
	s_waitcnt lgkmcnt(3)
	v_mfma_f32_16x16x32_bf16 v[6:9], v[6:9], v[22:25], v[2:5]
	v_mov_b32_e32 v15, v12
	s_waitcnt lgkmcnt(2)
	v_mfma_f32_16x16x32_bf16 v[16:19], v[16:19], v[22:25], v[2:5]
	s_waitcnt lgkmcnt(1)
	v_mfma_f32_16x16x32_bf16 v[26:29], v[26:29], v[22:25], v[2:5]
	s_waitcnt lgkmcnt(0)
	v_mfma_f32_16x16x32_bf16 v[30:33], v[30:33], v[22:25], v[2:5]
	ds_read_b128 v[52:55], v90 offset:9280
	s_nop 1
	ds_read_b128 v[2:5], v88 offset:54336
	ds_read_b128 v[56:59], v88 offset:56640
	ds_read_b128 v[60:63], v88 offset:58944
	ds_read_b128 v[64:67], v89 offset:54336
	s_waitcnt lgkmcnt(3)
	v_mfma_f32_16x16x32_bf16 v[2:5], v[2:5], v[52:55], v[6:9]
	s_waitcnt lgkmcnt(2)
	v_mfma_f32_16x16x32_bf16 v[6:9], v[56:59], v[52:55], v[16:19]
	s_waitcnt lgkmcnt(1)
	v_mfma_f32_16x16x32_bf16 v[18:21], v[60:63], v[52:55], v[26:29]
	s_waitcnt lgkmcnt(0)
	v_mfma_f32_16x16x32_bf16 v[26:29], v[64:67], v[52:55], v[30:33]
	s_nop 2
	ds_read_b128 v[30:33], v88 offset:63488
	ds_read_b128 v[56:59], v11 offset:2304
	ds_read_b128 v[60:63], v11 offset:4608
	ds_read_b128 v[64:67], v89 offset:63488
	s_waitcnt lgkmcnt(3)
	v_mfma_f32_16x16x32_bf16 v[30:33], v[30:33], v[22:25], v[12:15]
	s_waitcnt lgkmcnt(2)
	v_mfma_f32_16x16x32_bf16 v[56:59], v[56:59], v[22:25], v[12:15]
	s_waitcnt lgkmcnt(1)
	v_mfma_f32_16x16x32_bf16 v[60:63], v[60:63], v[22:25], v[12:15]
	s_waitcnt lgkmcnt(0)
	v_mfma_f32_16x16x32_bf16 v[64:67], v[64:67], v[22:25], v[12:15]
	s_nop 2
	ds_read_b128 v[12:15], v88 offset:63552
	ds_read_b128 v[22:25], v10 offset:2304
	ds_read_b128 v[68:71], v10 offset:4608
	ds_read_b128 v[72:75], v89 offset:63552
	s_waitcnt lgkmcnt(3)
	v_mfma_f32_16x16x32_bf16 v[10:13], v[12:15], v[52:55], v[30:33]
	v_mov_b32_e32 v51, v50
	s_waitcnt lgkmcnt(2)
	v_mfma_f32_16x16x32_bf16 v[14:17], v[22:25], v[52:55], v[56:59]
	s_waitcnt lgkmcnt(1)
	v_mfma_f32_16x16x32_bf16 v[22:25], v[68:71], v[52:55], v[60:63]
	s_waitcnt lgkmcnt(0)
	v_mfma_f32_16x16x32_bf16 v[30:33], v[72:75], v[52:55], v[64:67]
	ds_read_b128 v[54:57], v90
	ds_read_b128 v[58:61], v88 offset:18432
	s_nop 0
	ds_read_b128 v[62:65], v88 offset:20736
	ds_read_b128 v[66:69], v88 offset:23040
	ds_read_b128 v[70:73], v89 offset:18432
	ds_read_b128 v[74:77], v88 offset:27648
	ds_read_b128 v[78:81], v88 offset:29952
	ds_read_b128 v[100:103], v88 offset:32256
	ds_read_b128 v[104:107], v92 offset:18432
	v_mov_b32_e32 v52, v50
	v_mov_b32_e32 v53, v50
	s_waitcnt lgkmcnt(7)
	s_nop 0
	v_mfma_f32_16x16x32_bf16 v[58:61], v[58:61], v[54:57], v[50:53]
	s_waitcnt lgkmcnt(6)
	v_mfma_f32_16x16x32_bf16 v[62:65], v[62:65], v[54:57], v[50:53]
	s_waitcnt lgkmcnt(5)
	v_mfma_f32_16x16x32_bf16 v[66:69], v[66:69], v[54:57], v[50:53]
	s_waitcnt lgkmcnt(4)
	v_mfma_f32_16x16x32_bf16 v[108:111], v[70:73], v[54:57], v[50:53]
	s_waitcnt lgkmcnt(3)
	v_mfma_f32_16x16x32_bf16 v[112:115], v[74:77], v[54:57], v[50:53]
	s_waitcnt lgkmcnt(2)
	v_mfma_f32_16x16x32_bf16 v[116:119], v[78:81], v[54:57], v[50:53]
	s_waitcnt lgkmcnt(1)
	v_mfma_f32_16x16x32_bf16 v[100:103], v[100:103], v[54:57], v[50:53]
	s_waitcnt lgkmcnt(0)
	v_mfma_f32_16x16x32_bf16 v[50:53], v[104:107], v[54:57], v[50:53]
	ds_read_b128 v[104:107], v90 offset:64
	ds_read_b128 v[54:57], v88 offset:18496
	ds_read_b128 v[70:73], v88 offset:20800
	ds_read_b128 v[124:127], v88 offset:23104
	ds_read_b128 v[128:131], v89 offset:18496
	ds_read_b128 v[132:135], v88 offset:27712
	ds_read_b128 v[136:139], v88 offset:30016
	ds_read_b128 v[140:143], v88 offset:32320
	ds_read_b128 v[144:147], v92 offset:18496
	s_waitcnt lgkmcnt(7)
	v_mfma_f32_16x16x32_bf16 v[78:81], v[54:57], v[104:107], v[58:61]
	s_waitcnt lgkmcnt(1)
	v_mfma_f32_16x16x32_bf16 v[54:57], v[140:143], v[104:107], v[100:103]
	s_nop 2
	v_or_b32_e32 v102, 1, v91
	v_sub_u32_e32 v0, v102, v99
	v_sub_u32_e32 v87, v99, v102
	v_cndmask_b32_e32 v0, v0, v87, vcc
	v_cvt_f32_i32_e32 v0, v0
	v_cndmask_b32_e32 v87, v97, v96, vcc
	v_mfma_f32_16x16x32_bf16 v[74:77], v[70:73], v[104:107], v[62:65]
	v_or_b32_e32 v103, 3, v91
	v_mul_f32_e32 v0, v87, v0
	v_mul_f32_e32 v0, 0xbfb8aa3b, v0
	v_exp_f32_e32 v87, v0
	v_mfma_f32_16x16x32_bf16 v[70:73], v[124:127], v[104:107], v[66:69]
	v_or_b32_e32 v100, 18, v91
	v_or_b32_e32 v101, 19, v91
	v_pk_mul_f32 v[78:79], v[86:87], v[78:79]
	v_mfma_f32_16x16x32_bf16 v[66:69], v[128:131], v[104:107], v[108:111]
	v_or_b32_e32 v124, 0x62, v91
	v_or_b32_e32 v125, 0x63, v91
	v_lshl_add_u32 v130, v93, 7, v88
	v_mfma_f32_16x16x32_bf16 v[62:65], v[132:135], v[104:107], v[112:115]
	v_or_b32_e32 v108, 35, v91
	v_or_b32_e32 v109, 48, v91
	v_or_b32_e32 v110, 49, v91
	v_mfma_f32_16x16x32_bf16 v[58:61], v[136:139], v[104:107], v[116:119]
	v_or_b32_e32 v111, 50, v91
	v_or_b32_e32 v112, 51, v91
	v_or_b32_e32 v113, 64, v91
	s_waitcnt lgkmcnt(0)
	v_mfma_f32_16x16x32_bf16 v[50:53], v[144:147], v[104:107], v[50:53]
	v_or_b32_e32 v104, 2, v91
	v_sub_u32_e32 v0, v99, v104
	v_sub_u32_e32 v86, 0, v0
	v_max_i32_e32 v0, v0, v86
	v_cvt_f32_u32_e32 v0, v0
	v_cmp_lt_i32_e32 vcc, v99, v104
	v_or_b32_e32 v105, 32, v91
	v_or_b32_e32 v106, 33, v91
	v_cndmask_b32_e32 v86, v96, v97, vcc
	v_mul_f32_e32 v0, v86, v0
	v_mul_f32_e32 v0, 0xbfb8aa3b, v0
	v_exp_f32_e32 v86, v0
	v_sub_u32_e32 v0, v99, v103
	v_sub_u32_e32 v87, 0, v0
	v_max_i32_e32 v0, v0, v87
	v_cvt_f32_u32_e32 v0, v0
	v_cmp_lt_i32_e32 vcc, v99, v103
	v_or_b32_e32 v107, 34, v91
	v_or_b32_e32 v114, 0x41, v91
	v_cndmask_b32_e32 v87, v96, v97, vcc
	v_mul_f32_e32 v0, v87, v0
	v_mul_f32_e32 v0, 0xbfb8aa3b, v0
	v_exp_f32_e32 v87, v0
	v_sub_u32_e32 v0, v99, v94
	v_cmp_lt_i32_e32 vcc, v99, v94
	v_or_b32_e32 v115, 0x42, v91
	v_pk_mul_f32 v[80:81], v[86:87], v[80:81]
	v_sub_u32_e32 v86, 0, v0
	v_max_i32_e32 v0, v0, v86
	v_cvt_f32_u32_e32 v0, v0
	v_cndmask_b32_e32 v86, v96, v97, vcc
	v_cmp_lt_i32_e32 vcc, v99, v95
	v_or_b32_e32 v116, 0x43, v91
	v_mul_f32_e32 v0, v86, v0
	v_mul_f32_e32 v0, 0xbfb8aa3b, v0
	v_exp_f32_e32 v86, v0
	v_sub_u32_e32 v0, v99, v95
	v_sub_u32_e32 v87, 0, v0
	v_max_i32_e32 v0, v0, v87
	v_cvt_f32_u32_e32 v0, v0
	v_cndmask_b32_e32 v87, v96, v97, vcc
	v_cmp_lt_i32_e32 vcc, v99, v100
	v_or_b32_e32 v117, 0x50, v91
	v_mul_f32_e32 v0, v87, v0
	v_mul_f32_e32 v0, 0xbfb8aa3b, v0
	v_exp_f32_e32 v87, v0
	v_sub_u32_e32 v0, v99, v100
	v_or_b32_e32 v118, 0x51, v91
	v_or_b32_e32 v119, 0x52, v91
	v_pk_mul_f32 v[74:75], v[86:87], v[74:75]
	v_sub_u32_e32 v86, 0, v0
	v_max_i32_e32 v0, v0, v86
	v_cvt_f32_u32_e32 v0, v0
	v_cndmask_b32_e32 v86, v96, v97, vcc
	v_cmp_lt_i32_e32 vcc, v99, v101
	v_cvt_pk_bf16_f32 v78, v78, v79
	v_mul_f32_e32 v0, v86, v0
	v_mul_f32_e32 v0, 0xbfb8aa3b, v0
	v_exp_f32_e32 v86, v0
	v_sub_u32_e32 v0, v99, v101
	v_sub_u32_e32 v87, 0, v0
	v_max_i32_e32 v0, v0, v87
	v_cvt_f32_u32_e32 v0, v0
	v_cndmask_b32_e32 v87, v96, v97, vcc
	v_cmp_lt_i32_e32 vcc, v99, v105
	v_cvt_pk_bf16_f32 v79, v80, v81
	v_mul_f32_e32 v0, v87, v0
	v_mul_f32_e32 v0, 0xbfb8aa3b, v0
	v_exp_f32_e32 v87, v0
	v_sub_u32_e32 v0, v99, v105
	v_cvt_pk_bf16_f32 v80, v74, v75
	v_or_b32_e32 v126, 0x70, v91
	v_pk_mul_f32 v[76:77], v[86:87], v[76:77]
	v_sub_u32_e32 v86, 0, v0
	v_max_i32_e32 v0, v0, v86
	v_cvt_f32_u32_e32 v0, v0
	v_cndmask_b32_e32 v86, v96, v97, vcc
	v_cmp_lt_i32_e32 vcc, v99, v106
	v_cvt_pk_bf16_f32 v81, v76, v77
	v_mul_f32_e32 v0, v86, v0
	v_mul_f32_e32 v0, 0xbfb8aa3b, v0
	v_exp_f32_e32 v86, v0
	v_sub_u32_e32 v0, v99, v106
	v_sub_u32_e32 v87, 0, v0
	v_max_i32_e32 v0, v0, v87
	v_cvt_f32_u32_e32 v0, v0
	v_cndmask_b32_e32 v87, v96, v97, vcc
	v_cmp_lt_i32_e32 vcc, v99, v107
	ds_read_b128 v[74:77], v130 offset:36864
	v_mul_f32_e32 v0, v87, v0
	v_mul_f32_e32 v0, 0xbfb8aa3b, v0
	v_exp_f32_e32 v87, v0
	v_sub_u32_e32 v0, v99, v107
	v_or_b32_e32 v127, 0x71, v91
	v_or_b32_e32 v128, 0x72, v91
	v_pk_mul_f32 v[70:71], v[86:87], v[70:71]
	v_sub_u32_e32 v86, 0, v0
	v_max_i32_e32 v0, v0, v86
	v_cvt_f32_u32_e32 v0, v0
	v_cndmask_b32_e32 v86, v96, v97, vcc
	v_cmp_lt_i32_e32 vcc, v99, v108
	v_cvt_pk_bf16_f32 v70, v70, v71
	v_mul_f32_e32 v0, v86, v0
	v_mul_f32_e32 v0, 0xbfb8aa3b, v0
	v_exp_f32_e32 v86, v0
	v_sub_u32_e32 v0, v99, v108
	v_sub_u32_e32 v87, 0, v0
	v_max_i32_e32 v0, v0, v87
	v_cvt_f32_u32_e32 v0, v0
	v_cndmask_b32_e32 v87, v96, v97, vcc
	v_cmp_lt_i32_e32 vcc, v99, v109
	v_or_b32_e32 v129, 0x73, v91
	v_mul_f32_e32 v0, v87, v0
	v_mul_f32_e32 v0, 0xbfb8aa3b, v0
	v_exp_f32_e32 v87, v0
	v_sub_u32_e32 v0, v99, v109
	v_pk_mul_f32 v[72:73], v[86:87], v[72:73]
	v_sub_u32_e32 v86, 0, v0
	v_max_i32_e32 v0, v0, v86
	v_cvt_f32_u32_e32 v0, v0
	v_cndmask_b32_e32 v86, v96, v97, vcc
	v_cmp_lt_i32_e32 vcc, v99, v110
	v_cvt_pk_bf16_f32 v71, v72, v73
	v_mul_f32_e32 v0, v86, v0
	v_mul_f32_e32 v0, 0xbfb8aa3b, v0
	v_exp_f32_e32 v86, v0
	v_sub_u32_e32 v0, v99, v110
	v_sub_u32_e32 v87, 0, v0
	v_max_i32_e32 v0, v0, v87
	v_cvt_f32_u32_e32 v0, v0
	v_cndmask_b32_e32 v87, v96, v97, vcc
	v_cmp_lt_i32_e32 vcc, v99, v111
	v_mul_f32_e32 v0, v87, v0
	v_mul_f32_e32 v0, 0xbfb8aa3b, v0
	v_exp_f32_e32 v87, v0
	v_sub_u32_e32 v0, v99, v111
	v_pk_mul_f32 v[66:67], v[86:87], v[66:67]
	v_sub_u32_e32 v86, 0, v0
	v_max_i32_e32 v0, v0, v86
	v_cvt_f32_u32_e32 v0, v0
	v_cndmask_b32_e32 v86, v96, v97, vcc
	v_cmp_lt_i32_e32 vcc, v99, v112
	v_cvt_pk_bf16_f32 v72, v66, v67
	v_mul_f32_e32 v0, v86, v0
	v_mul_f32_e32 v0, 0xbfb8aa3b, v0
	v_exp_f32_e32 v86, v0
	v_sub_u32_e32 v0, v99, v112
	v_sub_u32_e32 v87, 0, v0
	v_max_i32_e32 v0, v0, v87
	v_cvt_f32_u32_e32 v0, v0
	v_cndmask_b32_e32 v87, v96, v97, vcc
	v_cmp_lt_i32_e32 vcc, v99, v113
	v_mul_f32_e32 v0, v87, v0
	v_mul_f32_e32 v0, 0xbfb8aa3b, v0
	v_exp_f32_e32 v87, v0
	v_sub_u32_e32 v0, v99, v113
	v_pk_mul_f32 v[68:69], v[86:87], v[68:69]
	v_sub_u32_e32 v86, 0, v0
	v_max_i32_e32 v0, v0, v86
	v_cvt_f32_u32_e32 v0, v0
	v_cndmask_b32_e32 v86, v96, v97, vcc
	v_cmp_lt_i32_e32 vcc, v99, v114
	v_cvt_pk_bf16_f32 v73, v68, v69
	v_mul_f32_e32 v0, v86, v0
	v_mul_f32_e32 v0, 0xbfb8aa3b, v0
	v_exp_f32_e32 v86, v0
	v_sub_u32_e32 v0, v99, v114
	v_sub_u32_e32 v87, 0, v0
	v_max_i32_e32 v0, v0, v87
	v_cvt_f32_u32_e32 v0, v0
	v_cndmask_b32_e32 v87, v96, v97, vcc
	v_cmp_lt_i32_e32 vcc, v99, v115
	ds_read_b128 v[66:69], v130 offset:36928
	v_mul_f32_e32 v0, v87, v0
	v_mul_f32_e32 v0, 0xbfb8aa3b, v0
	v_exp_f32_e32 v87, v0
	v_sub_u32_e32 v0, v99, v115
	s_waitcnt lgkmcnt(1)
	v_mfma_f32_16x16x32_bf16 v[34:37], v[74:77], v[78:81], v[34:37]
	ds_read_b128 v[74:77], v130 offset:41216
	v_pk_mul_f32 v[62:63], v[86:87], v[62:63]
	v_sub_u32_e32 v86, 0, v0
	v_max_i32_e32 v0, v0, v86
	v_cvt_f32_u32_e32 v0, v0
	v_cndmask_b32_e32 v86, v96, v97, vcc
	v_cmp_lt_i32_e32 vcc, v99, v116
	v_cvt_pk_bf16_f32 v62, v62, v63
	v_mul_f32_e32 v0, v86, v0
	v_mul_f32_e32 v0, 0xbfb8aa3b, v0
	v_exp_f32_e32 v86, v0
	v_sub_u32_e32 v0, v99, v116
	v_sub_u32_e32 v87, 0, v0
	v_max_i32_e32 v0, v0, v87
	v_cvt_f32_u32_e32 v0, v0
	v_cndmask_b32_e32 v87, v96, v97, vcc
	v_cmp_lt_i32_e32 vcc, v99, v117
	s_waitcnt lgkmcnt(1)
	v_mfma_f32_16x16x32_bf16 v[34:37], v[66:69], v[70:73], v[34:37]
	v_mul_f32_e32 v0, v87, v0
	v_mul_f32_e32 v0, 0xbfb8aa3b, v0
	v_exp_f32_e32 v87, v0
	v_sub_u32_e32 v0, v99, v117
	ds_read_b128 v[66:69], v130 offset:41280
	v_pk_mul_f32 v[64:65], v[86:87], v[64:65]
	v_sub_u32_e32 v86, 0, v0
	v_max_i32_e32 v0, v0, v86
	v_cvt_f32_u32_e32 v0, v0
	v_cndmask_b32_e32 v86, v96, v97, vcc
	v_cmp_lt_i32_e32 vcc, v99, v118
	v_cvt_pk_bf16_f32 v63, v64, v65
	v_mul_f32_e32 v0, v86, v0
	v_mul_f32_e32 v0, 0xbfb8aa3b, v0
	v_exp_f32_e32 v86, v0
	v_sub_u32_e32 v0, v99, v118
	v_sub_u32_e32 v87, 0, v0
	v_max_i32_e32 v0, v0, v87
	v_cvt_f32_u32_e32 v0, v0
	v_cndmask_b32_e32 v87, v96, v97, vcc
	v_cmp_lt_i32_e32 vcc, v99, v119
	v_mul_f32_e32 v0, v87, v0
	v_mul_f32_e32 v0, 0xbfb8aa3b, v0
	v_exp_f32_e32 v87, v0
	v_sub_u32_e32 v0, v99, v119
	v_pk_mul_f32 v[58:59], v[86:87], v[58:59]
	v_sub_u32_e32 v86, 0, v0
	v_max_i32_e32 v0, v0, v86
	v_cvt_f32_u32_e32 v0, v0
	v_cndmask_b32_e32 v86, v96, v97, vcc
	v_cmp_lt_i32_e32 vcc, v99, v120
	v_cvt_pk_bf16_f32 v64, v58, v59
	v_mul_f32_e32 v0, v86, v0
	v_mul_f32_e32 v0, 0xbfb8aa3b, v0
	v_exp_f32_e32 v86, v0
	v_sub_u32_e32 v0, v99, v120
	v_sub_u32_e32 v87, 0, v0
	v_max_i32_e32 v0, v0, v87
	v_cvt_f32_u32_e32 v0, v0
	v_cndmask_b32_e32 v87, v96, v97, vcc
	v_cmp_lt_i32_e32 vcc, v99, v121
	v_mul_f32_e32 v0, v87, v0
	v_mul_f32_e32 v0, 0xbfb8aa3b, v0
	v_exp_f32_e32 v87, v0
	v_sub_u32_e32 v0, v99, v121
	v_pk_mul_f32 v[60:61], v[86:87], v[60:61]
	v_sub_u32_e32 v86, 0, v0
	v_max_i32_e32 v0, v0, v86
	v_cvt_f32_u32_e32 v0, v0
	v_cndmask_b32_e32 v86, v96, v97, vcc
	v_cmp_lt_i32_e32 vcc, v99, v123
	v_cvt_pk_bf16_f32 v65, v60, v61
	v_mul_f32_e32 v0, v86, v0
	v_mul_f32_e32 v0, 0xbfb8aa3b, v0
	v_exp_f32_e32 v86, v0
	v_sub_u32_e32 v0, v99, v123
	v_sub_u32_e32 v87, 0, v0
	v_max_i32_e32 v0, v0, v87
	v_cvt_f32_u32_e32 v0, v0
	v_cndmask_b32_e32 v87, v96, v97, vcc
	v_cmp_lt_i32_e32 vcc, v99, v124
	ds_read_b128 v[58:61], v130 offset:36992
	v_mul_f32_e32 v0, v87, v0
	v_mul_f32_e32 v0, 0xbfb8aa3b, v0
	v_exp_f32_e32 v87, v0
	v_sub_u32_e32 v0, v99, v124
	s_waitcnt lgkmcnt(2)
	v_mfma_f32_16x16x32_bf16 v[38:41], v[74:77], v[78:81], v[38:41]
	ds_read_b128 v[74:77], v130 offset:45568
	v_pk_mul_f32 v[54:55], v[86:87], v[54:55]
	v_sub_u32_e32 v86, 0, v0
	v_max_i32_e32 v0, v0, v86
	v_cvt_f32_u32_e32 v0, v0
	v_cndmask_b32_e32 v86, v96, v97, vcc
	v_cmp_lt_i32_e32 vcc, v99, v125
	s_waitcnt lgkmcnt(1)
	v_mfma_f32_16x16x32_bf16 v[34:37], v[58:61], v[62:65], v[34:37]
	v_mul_f32_e32 v0, v86, v0
	v_mul_f32_e32 v0, 0xbfb8aa3b, v0
	v_exp_f32_e32 v86, v0
	v_sub_u32_e32 v0, v99, v125
	v_sub_u32_e32 v87, 0, v0
	v_max_i32_e32 v0, v0, v87
	v_cvt_f32_u32_e32 v0, v0
	v_cndmask_b32_e32 v87, v96, v97, vcc
	v_cmp_lt_i32_e32 vcc, v99, v126
	ds_read_b128 v[58:61], v130 offset:41344
	v_mul_f32_e32 v0, v87, v0
	v_mul_f32_e32 v0, 0xbfb8aa3b, v0
	v_exp_f32_e32 v87, v0
	v_sub_u32_e32 v0, v99, v126
	v_mfma_f32_16x16x32_bf16 v[38:41], v[66:69], v[70:73], v[38:41]
	ds_read_b128 v[66:69], v130 offset:45632
	v_pk_mul_f32 v[56:57], v[86:87], v[56:57]
	v_sub_u32_e32 v86, 0, v0
	v_max_i32_e32 v0, v0, v86
	v_cvt_f32_u32_e32 v0, v0
	v_cndmask_b32_e32 v86, v96, v97, vcc
	v_cmp_lt_i32_e32 vcc, v99, v127
	s_waitcnt lgkmcnt(2)
	v_mfma_f32_16x16x32_bf16 v[42:45], v[74:77], v[78:81], v[42:45]
	v_mul_f32_e32 v0, v86, v0
	v_mul_f32_e32 v0, 0xbfb8aa3b, v0
	v_exp_f32_e32 v86, v0
	v_sub_u32_e32 v0, v99, v127
	v_sub_u32_e32 v87, 0, v0
	v_max_i32_e32 v0, v0, v87
	v_cvt_f32_u32_e32 v0, v0
	v_cndmask_b32_e32 v87, v96, v97, vcc
	ds_read_b128 v[74:77], v130 offset:49920
	s_waitcnt lgkmcnt(2)
	v_mfma_f32_16x16x32_bf16 v[38:41], v[58:61], v[62:65], v[38:41]
	v_mul_f32_e32 v0, v87, v0
	v_mul_f32_e32 v0, 0xbfb8aa3b, v0
	v_exp_f32_e32 v87, v0
	ds_read_b128 v[58:61], v130 offset:45696
	v_sub_u32_e32 v0, v99, v128
	s_waitcnt lgkmcnt(2)
	v_mfma_f32_16x16x32_bf16 v[42:45], v[66:69], v[70:73], v[42:45]
	v_mul_f32_e64 v50, v86, v50
	v_mul_f32_e64 v51, v87, v51
	v_sub_u32_e32 v86, 0, v0
	v_max_i32_e32 v0, v0, v86
	ds_read_b128 v[66:69], v130 offset:49984
	v_cvt_f32_u32_e32 v0, v0
	v_cmp_lt_i32_e32 vcc, v99, v128
	s_waitcnt lgkmcnt(1)
	v_mfma_f32_16x16x32_bf16 v[58:61], v[58:61], v[62:65], v[42:45]
	v_cndmask_b32_e32 v86, v96, v97, vcc
	v_mul_f32_e32 v0, v86, v0
	s_nop 0
	ds_read_b128 v[42:45], v130 offset:50048
	v_mfma_f32_16x16x32_bf16 v[46:49], v[74:77], v[78:81], v[46:49]
	v_mul_f32_e32 v0, 0xbfb8aa3b, v0
	v_exp_f32_e32 v86, v0
	v_sub_u32_e32 v0, v99, v129
	v_sub_u32_e32 v87, 0, v0
	v_max_i32_e32 v0, v0, v87
	s_waitcnt lgkmcnt(1)
	v_mfma_f32_16x16x32_bf16 v[46:49], v[66:69], v[70:73], v[46:49]
	v_cvt_f32_u32_e32 v0, v0
	v_cmp_lt_i32_e32 vcc, v99, v129
	s_waitcnt lgkmcnt(0)
	v_mfma_f32_16x16x32_bf16 v[62:65], v[42:45], v[62:65], v[46:49]
	v_cndmask_b32_e32 v87, v96, v97, vcc
	ds_read_b128 v[42:45], v130 offset:37056
	v_mul_f32_e32 v0, v87, v0
	v_mul_f32_e32 v0, 0xbfb8aa3b, v0
	v_exp_f32_e32 v87, v0
	s_nop 0
	v_pk_mul_f32 v[86:87], v[86:87], v[52:53]
	v_cvt_pk_bf16_f32 v52, v54, v55
	v_cvt_pk_bf16_f32 v53, v56, v57
	v_cvt_pk_bf16_f32 v54, v50, v51
	v_cvt_pk_bf16_f32 v55, v86, v87
	s_waitcnt lgkmcnt(0)
	s_nop 0
	v_mfma_f32_16x16x32_bf16 v[46:49], v[42:45], v[52:55], v[34:37]
	s_nop 2
	ds_read_b128 v[34:37], v130 offset:41408
	s_waitcnt lgkmcnt(0)
	v_mfma_f32_16x16x32_bf16 v[42:45], v[34:37], v[52:55], v[38:41]
	ds_read_b128 v[34:37], v130 offset:45760
	s_nop 0
	v_mul_f32_e32 v0, v47, v47
	v_fmac_f32_e32 v0, v46, v46
	s_waitcnt lgkmcnt(0)
	v_mfma_f32_16x16x32_bf16 v[38:41], v[34:37], v[52:55], v[58:61]
	ds_read_b128 v[34:37], v130 offset:50112
	v_fmac_f32_e32 v0, v48, v48
	v_fmac_f32_e32 v0, v49, v49
	v_fmac_f32_e32 v0, v42, v42
	v_fmac_f32_e32 v0, v43, v43
	v_fmac_f32_e32 v0, v44, v44
	s_waitcnt lgkmcnt(0)
	v_mfma_f32_16x16x32_bf16 v[34:37], v[34:37], v[52:55], v[62:65]
	v_fmac_f32_e32 v0, v45, v45
	v_pk_mul_f32 v[52:53], v[38:39], v[38:39]
	v_pk_mul_f32 v[50:51], v[40:41], v[40:41]
	v_add_f32_e32 v0, v52, v0
	v_add_f32_e32 v0, v53, v0
	v_add_f32_e32 v0, v50, v0
	v_add_f32_e32 v0, v51, v0
	s_nop 0
	v_pk_mul_f32 v[52:53], v[34:35], v[34:35]
	v_pk_mul_f32 v[50:51], v[36:37], v[36:37]
	v_add_f32_e32 v0, v52, v0
	v_add_f32_e32 v0, v53, v0
	v_add_f32_e32 v0, v50, v0
	v_add_f32_e32 v0, v51, v0
	v_and_b32_e32 v51, 64, v170
	v_xor_b32_e32 v50, 16, v170
	v_add_u32_e32 v51, 64, v51
	v_cmp_lt_i32_e32 vcc, v50, v51
	v_mad_i64_i32 v[52:53], s[4:5], v99, s33, v[82:83]
	s_nop 0
	v_cndmask_b32_e32 v50, v170, v50, vcc
	v_lshlrev_b32_e32 v131, 2, v50
	ds_bpermute_b32 v50, v131, v0
	v_lshl_add_u64 v[52:53], v[52:53], 0, v[84:85]
	s_waitcnt lgkmcnt(0)
	v_add_f32_e32 v0, v0, v50
	v_xor_b32_e32 v50, 32, v170
	v_cmp_lt_i32_e32 vcc, v50, v51
	s_nop 1
	v_cndmask_b32_e32 v50, v170, v50, vcc
	v_lshlrev_b32_e32 v132, 2, v50
	ds_bpermute_b32 v50, v132, v0
	s_waitcnt lgkmcnt(0)
	v_add_f32_e32 v0, v0, v50
	v_fmamk_f32 v0, v0, 0x3c800000, v158
	v_cmp_gt_f32_e32 vcc, s8, v0
	v_mul_f32_e32 v50, 0x4b800000, v0
	s_nop 0
	v_cndmask_b32_e32 v0, v0, v50, vcc
	v_rsq_f32_e32 v0, v0
	s_nop 0
	v_mul_f32_e32 v50, 0x45800000, v0
	v_cndmask_b32_e32 v50, v0, v50, vcc
	v_lshlrev_b32_e32 v0, 1, v91
	v_lshl_add_u64 v[52:53], v[52:53], 0, v[0:1]
	global_load_dwordx2 v[54:55], v[52:53], off offset:1536
	v_cmp_lt_i32_e32 vcc, v98, v91
	s_waitcnt vmcnt(0) lgkmcnt(0)
	v_lshlrev_b32_e32 v56, 16, v54
	v_mul_f32_e32 v51, 0xbfb8aa3b, v56
	v_exp_f32_e32 v51, v51
	v_and_b32_e32 v57, 0xffff0000, v54
	v_lshlrev_b32_e32 v54, 16, v55
	v_and_b32_e32 v55, 0xffff0000, v55
	v_add_f32_e32 v51, 1.0, v51
	v_rcp_f32_e32 v58, v51
	v_mul_f32_e32 v51, 0xbfb8aa3b, v57
	v_exp_f32_e32 v51, v51
	s_nop 0
	v_add_f32_e32 v51, 1.0, v51
	v_rcp_f32_e32 v59, v51
	s_nop 0
	v_pk_mul_f32 v[56:57], v[58:59], v[56:57]
	s_nop 0
	v_pk_mul_f32 v[56:57], v[56:57], v[50:51] op_sel_hi:[1,0]
	v_mul_f32_e32 v51, 0xbfb8aa3b, v54
	v_exp_f32_e32 v51, v51
	v_pk_mul_f32 v[46:47], v[46:47], v[56:57]
	v_add_f32_e32 v51, 1.0, v51
	v_rcp_f32_e32 v56, v51
	v_mul_f32_e32 v51, 0xbfb8aa3b, v55
	v_exp_f32_e32 v51, v51
	v_cvt_pk_bf16_f32 v46, v46, v47
	v_add_f32_e32 v51, 1.0, v51
	v_rcp_f32_e32 v57, v51
	s_nop 0
	v_pk_mul_f32 v[54:55], v[56:57], v[54:55]
	s_nop 0
	v_pk_mul_f32 v[54:55], v[54:55], v[50:51] op_sel_hi:[1,0]
	s_nop 0
	v_pk_mul_f32 v[48:49], v[48:49], v[54:55]
	s_nop 0
	v_cvt_pk_bf16_f32 v47, v48, v49
	global_store_dwordx2 v[52:53], v[46:47], off offset:1536
	global_load_dwordx2 v[46:47], v[52:53], off offset:1568
	s_waitcnt vmcnt(0) lgkmcnt(0)
	v_lshlrev_b32_e32 v48, 16, v46
	v_mul_f32_e32 v51, 0xbfb8aa3b, v48
	v_exp_f32_e32 v51, v51
	v_and_b32_e32 v49, 0xffff0000, v46
	v_lshlrev_b32_e32 v46, 16, v47
	v_and_b32_e32 v47, 0xffff0000, v47
	v_add_f32_e32 v51, 1.0, v51
	v_rcp_f32_e32 v54, v51
	v_mul_f32_e32 v51, 0xbfb8aa3b, v49
	v_exp_f32_e32 v51, v51
	s_nop 0
	v_add_f32_e32 v51, 1.0, v51
	v_rcp_f32_e32 v55, v51
	s_nop 0
	v_pk_mul_f32 v[48:49], v[54:55], v[48:49]
	s_nop 0
	v_pk_mul_f32 v[48:49], v[48:49], v[50:51] op_sel_hi:[1,0]
	s_nop 0
	v_pk_mul_f32 v[42:43], v[42:43], v[48:49]
	v_mul_f32_e32 v48, 0xbfb8aa3b, v46
	v_mul_f32_e32 v49, 0xbfb8aa3b, v47
	v_exp_f32_e32 v48, v48
	v_exp_f32_e32 v49, v49
	v_cvt_pk_bf16_f32 v42, v42, v43
	v_add_f32_e32 v48, 1.0, v48
	v_add_f32_e32 v49, 1.0, v49
	v_rcp_f32_e32 v48, v48
	v_rcp_f32_e32 v49, v49
	s_nop 0
	v_pk_mul_f32 v[46:47], v[48:49], v[46:47]
	s_nop 0
	v_pk_mul_f32 v[46:47], v[46:47], v[50:51] op_sel_hi:[1,0]
	s_nop 0
	v_pk_mul_f32 v[44:45], v[44:45], v[46:47]
	s_nop 0
	v_cvt_pk_bf16_f32 v43, v44, v45
	global_store_dwordx2 v[52:53], v[42:43], off offset:1568
	global_load_dwordx2 v[42:43], v[52:53], off offset:1600
	s_waitcnt vmcnt(0) lgkmcnt(0)
	v_lshlrev_b32_e32 v44, 16, v42
	v_and_b32_e32 v45, 0xffff0000, v42
	v_mul_f32_e32 v46, 0xbfb8aa3b, v44
	v_mul_f32_e32 v47, 0xbfb8aa3b, v45
	v_exp_f32_e32 v46, v46
	v_exp_f32_e32 v47, v47
	v_lshlrev_b32_e32 v42, 16, v43
	v_and_b32_e32 v43, 0xffff0000, v43
	v_add_f32_e32 v46, 1.0, v46
	v_add_f32_e32 v47, 1.0, v47
	v_rcp_f32_e32 v46, v46
	v_rcp_f32_e32 v47, v47
	s_nop 0
	v_pk_mul_f32 v[44:45], v[46:47], v[44:45]
	s_nop 0
	v_pk_mul_f32 v[44:45], v[44:45], v[50:51] op_sel_hi:[1,0]
	s_nop 0
	v_pk_mul_f32 v[38:39], v[38:39], v[44:45]
	v_mul_f32_e32 v44, 0xbfb8aa3b, v42
	v_mul_f32_e32 v45, 0xbfb8aa3b, v43
	v_exp_f32_e32 v44, v44
	v_exp_f32_e32 v45, v45
	v_cvt_pk_bf16_f32 v38, v38, v39
	v_add_f32_e32 v44, 1.0, v44
	v_add_f32_e32 v45, 1.0, v45
	v_rcp_f32_e32 v44, v44
	v_rcp_f32_e32 v45, v45
	s_nop 0
	v_pk_mul_f32 v[42:43], v[44:45], v[42:43]
	s_nop 0
	v_pk_mul_f32 v[42:43], v[50:51], v[42:43] op_sel_hi:[0,1]
	v_pk_mul_f32 v[40:41], v[40:41], v[42:43]
	s_nop 0
	v_cvt_pk_bf16_f32 v39, v40, v41
	global_store_dwordx2 v[52:53], v[38:39], off offset:1600
	global_load_dwordx2 v[38:39], v[52:53], off offset:1632
	s_waitcnt vmcnt(0) lgkmcnt(0)
	v_lshlrev_b32_e32 v40, 16, v38
	v_and_b32_e32 v41, 0xffff0000, v38
	v_mul_f32_e32 v42, 0xbfb8aa3b, v40
	v_mul_f32_e32 v43, 0xbfb8aa3b, v41
	v_exp_f32_e32 v42, v42
	v_exp_f32_e32 v43, v43
	v_lshlrev_b32_e32 v38, 16, v39
	v_and_b32_e32 v39, 0xffff0000, v39
	v_add_f32_e32 v42, 1.0, v42
	v_add_f32_e32 v43, 1.0, v43
	v_rcp_f32_e32 v42, v42
	v_rcp_f32_e32 v43, v43
	s_nop 0
	v_pk_mul_f32 v[40:41], v[42:43], v[40:41]
	s_nop 0
	v_pk_mul_f32 v[40:41], v[50:51], v[40:41] op_sel_hi:[0,1]
	v_pk_mul_f32 v[34:35], v[34:35], v[40:41]
	v_mul_f32_e32 v40, 0xbfb8aa3b, v38
	v_mul_f32_e32 v41, 0xbfb8aa3b, v39
	v_exp_f32_e32 v40, v40
	v_exp_f32_e32 v41, v41
	v_cvt_pk_bf16_f32 v34, v34, v35
	v_add_f32_e32 v40, 1.0, v40
	v_add_f32_e32 v41, 1.0, v41
	v_rcp_f32_e32 v40, v40
	v_rcp_f32_e32 v41, v41
	s_nop 0
	v_pk_mul_f32 v[38:39], v[40:41], v[38:39]
	s_nop 0
	v_pk_mul_f32 v[38:39], v[50:51], v[38:39] op_sel_hi:[0,1]
	v_pk_mul_f32 v[36:37], v[36:37], v[38:39]
	s_nop 0
	v_cvt_pk_bf16_f32 v35, v36, v37
	global_store_dwordx2 v[52:53], v[34:35], off offset:1632
	v_mov_b32_e32 v34, v1
	ds_read_b128 v[38:41], v90 offset:9216
	ds_read_b128 v[42:45], v88 offset:18432
	ds_read_b128 v[46:49], v88 offset:20736
	ds_read_b128 v[50:53], v88 offset:23040
	ds_read_b128 v[54:57], v89 offset:18432
	ds_read_b128 v[58:61], v88 offset:27648
	ds_read_b128 v[62:65], v88 offset:29952
	ds_read_b128 v[66:69], v88 offset:32256
	ds_read_b128 v[70:73], v92 offset:18432
	v_mov_b32_e32 v35, v34
	v_mov_b32_e32 v36, v34
	v_mov_b32_e32 v37, v34
	s_waitcnt lgkmcnt(0)
	s_nop 0
	v_mfma_f32_16x16x32_bf16 v[42:45], v[42:45], v[38:41], v[34:37]
	v_mfma_f32_16x16x32_bf16 v[46:49], v[46:49], v[38:41], v[34:37]
	v_mfma_f32_16x16x32_bf16 v[50:53], v[50:53], v[38:41], v[34:37]
	v_mfma_f32_16x16x32_bf16 v[74:77], v[54:57], v[38:41], v[34:37]
	v_mfma_f32_16x16x32_bf16 v[78:81], v[58:61], v[38:41], v[34:37]
	v_mfma_f32_16x16x32_bf16 v[134:137], v[62:65], v[38:41], v[34:37]
	v_mfma_f32_16x16x32_bf16 v[66:69], v[66:69], v[38:41], v[34:37]
	v_mfma_f32_16x16x32_bf16 v[34:37], v[70:73], v[38:41], v[34:37]
	ds_read_b128 v[70:73], v90 offset:9280
	ds_read_b128 v[38:41], v88 offset:18496
	ds_read_b128 v[54:57], v88 offset:20800
	ds_read_b128 v[138:141], v88 offset:23104
	ds_read_b128 v[142:145], v89 offset:18496
	ds_read_b128 v[146:149], v88 offset:27712
	ds_read_b128 v[150:153], v88 offset:30016
	ds_read_b128 v[86:89], v88 offset:32320
	ds_read_b128 v[166:169], v92 offset:18496
	s_waitcnt lgkmcnt(0)
	v_mfma_f32_16x16x32_bf16 v[62:65], v[38:41], v[70:73], v[42:45]
	v_mfma_f32_16x16x32_bf16 v[38:41], v[86:89], v[70:73], v[66:69]
	s_nop 2
	v_sub_u32_e32 v66, v98, v91
	v_sub_u32_e32 v67, 0, v66
	v_max_i32_e32 v66, v66, v67
	v_cvt_f32_u32_e32 v66, v66
	v_cndmask_b32_e32 v67, v96, v97, vcc
	v_cmp_gt_i32_e32 vcc, v98, v91
	v_sub_u32_e32 v68, v98, v102
	v_mul_f32_e32 v66, v67, v66
	v_sub_u32_e32 v67, v102, v98
	v_cndmask_b32_e32 v67, v67, v68, vcc
	v_cvt_f32_i32_e32 v67, v67
	v_cndmask_b32_e32 v68, v97, v96, vcc
	v_cmp_lt_i32_e32 vcc, v98, v104
	v_mfma_f32_16x16x32_bf16 v[58:61], v[54:57], v[70:73], v[46:49]
	v_mul_f32_e32 v67, v68, v67
	v_sub_u32_e32 v68, v98, v104
	v_sub_u32_e32 v69, 0, v68
	v_max_i32_e32 v68, v68, v69
	v_cvt_f32_u32_e32 v68, v68
	v_cndmask_b32_e32 v69, v96, v97, vcc
	v_mfma_f32_16x16x32_bf16 v[54:57], v[138:141], v[70:73], v[50:53]
	v_cmp_lt_i32_e32 vcc, v98, v103
	v_mul_f32_e32 v68, v69, v68
	v_sub_u32_e32 v69, v98, v103
	v_mfma_f32_16x16x32_bf16 v[50:53], v[142:145], v[70:73], v[74:77]
	v_mul_f32_e32 v66, 0xbfb8aa3b, v66
	v_mul_f32_e32 v67, 0xbfb8aa3b, v67
	v_exp_f32_e32 v66, v66
	v_mfma_f32_16x16x32_bf16 v[46:49], v[146:149], v[70:73], v[78:81]
	v_exp_f32_e32 v67, v67
	v_mul_f32_e32 v68, 0xbfb8aa3b, v68
	v_exp_f32_e32 v68, v68
	v_mfma_f32_16x16x32_bf16 v[42:45], v[150:153], v[70:73], v[134:137]
	v_mul_f32_e64 v62, v66, v62
	v_mul_f32_e64 v63, v67, v63
	v_sub_u32_e32 v67, 64, v99
	v_add_u32_e32 v66, 0x41, v99
	v_mfma_f32_16x16x32_bf16 v[34:37], v[166:169], v[70:73], v[34:37]
	v_sub_u32_e32 v70, 0, v69
	v_max_i32_e32 v69, v69, v70
	v_cvt_f32_u32_e32 v69, v69
	v_cndmask_b32_e32 v70, v96, v97, vcc
	v_cmp_lt_i32_e32 vcc, v98, v94
	v_cvt_f32_i32_e32 v67, v67
	v_mul_f32_e32 v69, v70, v69
	v_sub_u32_e32 v70, v98, v94
	v_sub_u32_e32 v71, 0, v70
	v_max_i32_e32 v70, v70, v71
	v_cvt_f32_u32_e32 v70, v70
	v_cndmask_b32_e32 v71, v96, v97, vcc
	v_cmp_lt_i32_e32 vcc, v98, v95
	v_mul_f32_e32 v69, 0xbfb8aa3b, v69
	v_mul_f32_e32 v70, v71, v70
	v_sub_u32_e32 v71, v98, v95
	v_sub_u32_e32 v72, 0, v71
	v_max_i32_e32 v71, v71, v72
	v_cvt_f32_u32_e32 v71, v71
	v_cndmask_b32_e32 v72, v96, v97, vcc
	v_cmp_lt_i32_e32 vcc, v98, v100
	v_cvt_f32_i32_e32 v66, v66
	v_mul_f32_e32 v71, v72, v71
	v_sub_u32_e32 v72, v98, v100
	v_sub_u32_e32 v73, 0, v72
	v_max_i32_e32 v72, v72, v73
	v_cvt_f32_u32_e32 v72, v72
	v_cndmask_b32_e32 v73, v96, v97, vcc
	v_cmp_lt_i32_e32 vcc, v98, v101
	v_exp_f32_e32 v69, v69
	v_mul_f32_e32 v72, v73, v72
	v_sub_u32_e32 v73, v98, v101
	v_sub_u32_e32 v74, 0, v73
	v_max_i32_e32 v73, v73, v74
	v_cvt_f32_u32_e32 v73, v73
	v_cndmask_b32_e32 v74, v96, v97, vcc
	v_cmp_lt_i32_e32 vcc, v98, v105
	v_mul_f32_e32 v67, v67, v97
	v_mul_f32_e32 v73, v74, v73
	v_sub_u32_e32 v74, v98, v105
	v_sub_u32_e32 v75, 0, v74
	v_max_i32_e32 v74, v74, v75
	v_cvt_f32_u32_e32 v74, v74
	v_cndmask_b32_e32 v75, v96, v97, vcc
	v_cmp_lt_i32_e32 vcc, v98, v106
	v_mul_f32_e32 v66, v66, v96
	v_mul_f32_e32 v74, v75, v74
	v_sub_u32_e32 v75, v98, v106
	v_sub_u32_e32 v76, 0, v75
	v_max_i32_e32 v75, v75, v76
	v_cvt_f32_u32_e32 v75, v75
	v_cndmask_b32_e32 v76, v96, v97, vcc
	v_cmp_lt_i32_e32 vcc, v98, v107
	v_mul_f32_e32 v67, 0xbfb8aa3b, v67
	v_mul_f32_e32 v75, v76, v75
	v_sub_u32_e32 v76, v98, v107
	v_sub_u32_e32 v77, 0, v76
	v_max_i32_e32 v76, v76, v77
	v_cvt_f32_u32_e32 v76, v76
	v_cndmask_b32_e32 v77, v96, v97, vcc
	v_cmp_lt_i32_e32 vcc, v98, v108
	v_pk_mul_f32 v[64:65], v[68:69], v[64:65]
	v_mul_f32_e32 v76, v77, v76
	v_sub_u32_e32 v77, v98, v108
	v_sub_u32_e32 v78, 0, v77
	v_max_i32_e32 v77, v77, v78
	v_cvt_f32_u32_e32 v77, v77
	v_cndmask_b32_e32 v78, v96, v97, vcc
	v_cmp_lt_i32_e32 vcc, v98, v109
	v_mul_f32_e32 v66, 0xbfb8aa3b, v66
	v_mul_f32_e32 v77, v78, v77
	v_sub_u32_e32 v78, v98, v109
	v_sub_u32_e32 v79, 0, v78
	v_max_i32_e32 v78, v78, v79
	v_cvt_f32_u32_e32 v78, v78
	v_cndmask_b32_e32 v79, v96, v97, vcc
	v_cmp_lt_i32_e32 vcc, v98, v110
	v_exp_f32_e32 v68, v67
	v_mul_f32_e32 v78, v79, v78
	v_sub_u32_e32 v79, v98, v110
	v_sub_u32_e32 v80, 0, v79
	v_max_i32_e32 v79, v79, v80
	v_cvt_f32_u32_e32 v79, v79
	v_cndmask_b32_e32 v80, v96, v97, vcc
	v_cmp_lt_i32_e32 vcc, v98, v111
	v_exp_f32_e32 v66, v66
	v_mul_f32_e32 v79, v80, v79
	v_sub_u32_e32 v80, v98, v111
	v_sub_u32_e32 v81, 0, v80
	v_max_i32_e32 v80, v80, v81
	v_cvt_f32_u32_e32 v80, v80
	v_cndmask_b32_e32 v81, v96, v97, vcc
	v_cmp_lt_i32_e32 vcc, v98, v112
	v_pk_mul_f32 v[22:23], v[68:69], v[22:23] op_sel_hi:[0,1]
	v_mul_f32_e32 v80, v81, v80
	v_sub_u32_e32 v81, v98, v112
	v_sub_u32_e32 v86, 0, v81
	v_max_i32_e32 v81, v81, v86
	v_cvt_f32_u32_e32 v81, v81
	v_cndmask_b32_e32 v86, v96, v97, vcc
	v_pk_mul_f32 v[24:25], v[68:69], v[24:25] op_sel_hi:[0,1]
	v_pk_fma_f32 v[20:21], v[66:67], v[20:21], v[24:25] op_sel_hi:[0,1,1]
	v_mul_f32_e32 v81, v86, v81
	v_sub_u32_e32 v86, v98, v113
	v_sub_u32_e32 v87, 0, v86
	v_max_i32_e32 v86, v86, v87
	v_cvt_f32_u32_e32 v86, v86
	v_pk_fma_f32 v[18:19], v[66:67], v[18:19], v[22:23] op_sel_hi:[0,1,1]
	ds_read_b128 v[22:25], v130 offset:36864
	v_mul_f32_e32 v70, 0xbfb8aa3b, v70
	v_mul_f32_e32 v71, 0xbfb8aa3b, v71
	v_mul_f32_e32 v72, 0xbfb8aa3b, v72
	v_mul_f32_e32 v73, 0xbfb8aa3b, v73
	v_cmp_lt_i32_e32 vcc, v98, v113
	v_exp_f32_e32 v70, v70
	v_exp_f32_e32 v71, v71
	v_exp_f32_e32 v72, v72
	v_exp_f32_e32 v73, v73
	v_cndmask_b32_e32 v87, v96, v97, vcc
	v_mul_f32_e32 v86, v87, v86
	v_sub_u32_e32 v87, v98, v114
	v_sub_u32_e32 v88, 0, v87
	v_max_i32_e32 v87, v87, v88
	v_cvt_f32_u32_e32 v87, v87
	v_pk_mul_f32 v[58:59], v[70:71], v[58:59]
	v_pk_mul_f32 v[60:61], v[72:73], v[60:61]
	v_pk_mul_f32 v[14:15], v[68:69], v[14:15] op_sel_hi:[0,1]
	v_pk_mul_f32 v[16:17], v[68:69], v[16:17] op_sel_hi:[0,1]
	v_pk_mul_f32 v[10:11], v[68:69], v[10:11] op_sel_hi:[0,1]
	v_pk_mul_f32 v[12:13], v[68:69], v[12:13] op_sel_hi:[0,1]
	v_pk_fma_f32 v[8:9], v[66:67], v[8:9], v[16:17] op_sel_hi:[0,1,1]
	v_pk_fma_f32 v[6:7], v[66:67], v[6:7], v[14:15] op_sel_hi:[0,1,1]
	v_pk_fma_f32 v[12:13], v[66:67], v[4:5], v[12:13] op_sel_hi:[0,1,1]
	v_pk_fma_f32 v[10:11], v[66:67], v[2:3], v[10:11] op_sel_hi:[0,1,1]
	v_cvt_pk_bf16_f32 v14, v62, v63
	v_cvt_pk_bf16_f32 v15, v64, v65
	v_cvt_pk_bf16_f32 v16, v58, v59
	v_cvt_pk_bf16_f32 v17, v60, v61
	v_cmp_lt_i32_e32 vcc, v98, v114
	v_pk_mul_f32 v[30:31], v[68:69], v[30:31] op_sel_hi:[0,1]
	s_waitcnt lgkmcnt(0)
	v_mfma_f32_16x16x32_bf16 v[10:13], v[22:25], v[14:17], v[10:13]
	ds_read_b128 v[22:25], v130 offset:41216
	v_cndmask_b32_e32 v88, v96, v97, vcc
	v_mul_f32_e32 v87, v88, v87
	v_sub_u32_e32 v88, v98, v115
	v_sub_u32_e32 v89, 0, v88
	v_max_i32_e32 v88, v88, v89
	v_cvt_f32_u32_e32 v88, v88
	v_cmp_lt_i32_e32 vcc, v98, v115
	s_waitcnt lgkmcnt(0)
	v_mfma_f32_16x16x32_bf16 v[4:7], v[22:25], v[14:17], v[6:9]
	v_cndmask_b32_e32 v89, v96, v97, vcc
	v_mul_f32_e32 v88, v89, v88
	v_sub_u32_e32 v89, v98, v116
	ds_read_b128 v[22:25], v130 offset:45568
	v_sub_u32_e32 v90, 0, v89
	v_max_i32_e32 v89, v89, v90
	v_cvt_f32_u32_e32 v89, v89
	v_cmp_lt_i32_e32 vcc, v98, v116
	s_waitcnt lgkmcnt(0)
	v_mfma_f32_16x16x32_bf16 v[18:21], v[22:25], v[14:17], v[18:21]
	v_cndmask_b32_e32 v90, v96, v97, vcc
	v_mul_f32_e32 v89, v90, v89
	v_sub_u32_e32 v90, v98, v117
	v_sub_u32_e32 v91, 0, v90
	v_max_i32_e32 v90, v90, v91
	ds_read_b128 v[22:25], v130 offset:49920
	v_cvt_f32_u32_e32 v90, v90
	v_cmp_lt_i32_e32 vcc, v98, v117
	v_pk_mul_f32 v[32:33], v[68:69], v[32:33] op_sel_hi:[0,1]
	v_pk_fma_f32 v[28:29], v[66:67], v[28:29], v[32:33] op_sel_hi:[0,1,1]
	v_cndmask_b32_e32 v91, v96, v97, vcc
	v_mul_f32_e32 v90, v91, v90
	v_sub_u32_e32 v91, v98, v118
	v_sub_u32_e32 v92, 0, v91
	v_max_i32_e32 v91, v91, v92
	v_cvt_f32_u32_e32 v91, v91
	v_pk_fma_f32 v[26:27], v[66:67], v[26:27], v[30:31] op_sel_hi:[0,1,1]
	v_cmp_lt_i32_e32 vcc, v98, v118
	v_mul_f32_e32 v74, 0xbfb8aa3b, v74
	s_waitcnt lgkmcnt(0)
	v_mfma_f32_16x16x32_bf16 v[14:17], v[22:25], v[14:17], v[26:29]
	v_mul_f32_e32 v75, 0xbfb8aa3b, v75
	v_mul_f32_e32 v76, 0xbfb8aa3b, v76
	v_mul_f32_e32 v77, 0xbfb8aa3b, v77
	ds_read_b128 v[26:29], v130 offset:36928
	v_mul_f32_e32 v78, 0xbfb8aa3b, v78
	v_mul_f32_e32 v79, 0xbfb8aa3b, v79
	v_mul_f32_e32 v80, 0xbfb8aa3b, v80
	v_mul_f32_e32 v81, 0xbfb8aa3b, v81
	v_cndmask_b32_e32 v92, v96, v97, vcc
	v_exp_f32_e32 v74, v74
	v_exp_f32_e32 v75, v75
	v_exp_f32_e32 v76, v76
	v_exp_f32_e32 v77, v77
	v_exp_f32_e32 v78, v78
	v_exp_f32_e32 v79, v79
	v_exp_f32_e32 v80, v80
	v_exp_f32_e32 v81, v81
	v_mul_f32_e32 v91, v92, v91
	v_sub_u32_e32 v92, v98, v119
	v_sub_u32_e32 v93, 0, v92
	v_max_i32_e32 v92, v92, v93
	v_cvt_f32_u32_e32 v92, v92
	v_pk_mul_f32 v[54:55], v[74:75], v[54:55]
	v_pk_mul_f32 v[56:57], v[76:77], v[56:57]
	v_pk_mul_f32 v[50:51], v[78:79], v[50:51]
	v_pk_mul_f32 v[52:53], v[80:81], v[52:53]
	v_cmp_lt_i32_e32 vcc, v98, v119
	v_cvt_pk_bf16_f32 v22, v54, v55
	v_cvt_pk_bf16_f32 v23, v56, v57
	v_cvt_pk_bf16_f32 v24, v50, v51
	v_cvt_pk_bf16_f32 v25, v52, v53
	v_cndmask_b32_e32 v93, v96, v97, vcc
	v_mul_f32_e32 v92, v93, v92
	s_waitcnt lgkmcnt(0)
	v_mfma_f32_16x16x32_bf16 v[8:11], v[26:29], v[22:25], v[10:13]
	ds_read_b128 v[26:29], v130 offset:41280
	v_sub_u32_e32 v93, v98, v120
	v_sub_u32_e32 v94, 0, v93
	v_max_i32_e32 v93, v93, v94
	v_cvt_f32_u32_e32 v93, v93
	v_cmp_lt_i32_e32 vcc, v98, v120
	s_waitcnt lgkmcnt(0)
	v_mfma_f32_16x16x32_bf16 v[4:7], v[26:29], v[22:25], v[4:7]
	v_cndmask_b32_e32 v94, v96, v97, vcc
	v_mul_f32_e32 v93, v94, v93
	v_sub_u32_e32 v94, v98, v121
	v_sub_u32_e32 v95, 0, v94
	ds_read_b128 v[26:29], v130 offset:45632
	v_max_i32_e32 v94, v94, v95
	v_cvt_f32_u32_e32 v94, v94
	v_cmp_lt_i32_e32 vcc, v98, v121
	s_waitcnt lgkmcnt(0)
	v_mfma_f32_16x16x32_bf16 v[18:21], v[26:29], v[22:25], v[18:21]
	v_cndmask_b32_e32 v95, v96, v97, vcc
	v_mul_f32_e32 v94, v95, v94
	v_sub_u32_e32 v95, v98, v123
	v_sub_u32_e32 v100, 0, v95
	v_max_i32_e32 v95, v95, v100
	v_cvt_f32_u32_e32 v95, v95
	ds_read_b128 v[26:29], v130 offset:49984
	v_cmp_lt_i32_e32 vcc, v98, v123
	s_waitcnt lgkmcnt(0)
	v_mfma_f32_16x16x32_bf16 v[12:15], v[26:29], v[22:25], v[14:17]
	v_cndmask_b32_e32 v100, v96, v97, vcc
	v_mul_f32_e32 v95, v100, v95
	v_sub_u32_e32 v100, v98, v124
	v_sub_u32_e32 v101, 0, v100
	v_max_i32_e32 v100, v100, v101
	v_cvt_f32_u32_e32 v100, v100
	v_cmp_lt_i32_e32 vcc, v98, v124
	ds_read_b128 v[26:29], v130 offset:36992
	v_mul_f32_e32 v86, 0xbfb8aa3b, v86
	v_cndmask_b32_e32 v101, v96, v97, vcc
	v_mul_f32_e32 v87, 0xbfb8aa3b, v87
	v_mul_f32_e32 v88, 0xbfb8aa3b, v88
	v_mul_f32_e32 v89, 0xbfb8aa3b, v89
	v_mul_f32_e32 v90, 0xbfb8aa3b, v90
	v_mul_f32_e32 v91, 0xbfb8aa3b, v91
	v_mul_f32_e32 v92, 0xbfb8aa3b, v92
	v_mul_f32_e32 v93, 0xbfb8aa3b, v93
	v_mul_f32_e32 v100, v101, v100
	v_sub_u32_e32 v101, v98, v125
	v_exp_f32_e32 v86, v86
	v_exp_f32_e32 v87, v87
	v_exp_f32_e32 v88, v88
	v_exp_f32_e32 v89, v89
	v_exp_f32_e32 v90, v90
	v_exp_f32_e32 v91, v91
	v_exp_f32_e32 v92, v92
	v_exp_f32_e32 v93, v93
	v_sub_u32_e32 v102, 0, v101
	v_max_i32_e32 v101, v101, v102
	v_cvt_f32_u32_e32 v101, v101
	v_cmp_lt_i32_e32 vcc, v98, v125
	v_pk_mul_f32 v[46:47], v[86:87], v[46:47]
	v_pk_mul_f32 v[48:49], v[88:89], v[48:49]
	v_pk_mul_f32 v[42:43], v[90:91], v[42:43]
	v_pk_mul_f32 v[44:45], v[92:93], v[44:45]
	v_cndmask_b32_e32 v102, v96, v97, vcc
	v_cvt_pk_bf16_f32 v22, v46, v47
	v_cvt_pk_bf16_f32 v23, v48, v49
	v_cvt_pk_bf16_f32 v24, v42, v43
	v_cvt_pk_bf16_f32 v25, v44, v45
	v_mul_f32_e32 v101, v102, v101
	v_sub_u32_e32 v102, v98, v126
	s_waitcnt lgkmcnt(0)
	v_mfma_f32_16x16x32_bf16 v[8:11], v[26:29], v[22:25], v[8:11]
	ds_read_b128 v[26:29], v130 offset:41344
	v_sub_u32_e32 v103, 0, v102
	v_max_i32_e32 v102, v102, v103
	v_cvt_f32_u32_e32 v102, v102
	v_cmp_lt_i32_e32 vcc, v98, v126
	s_waitcnt lgkmcnt(0)
	v_mfma_f32_16x16x32_bf16 v[4:7], v[26:29], v[22:25], v[4:7]
	v_cndmask_b32_e32 v103, v96, v97, vcc
	v_mul_f32_e32 v102, v103, v102
	v_sub_u32_e32 v103, v98, v127
	v_sub_u32_e32 v104, 0, v103
	v_max_i32_e32 v103, v103, v104
	ds_read_b128 v[26:29], v130 offset:45696
	v_cvt_f32_u32_e32 v103, v103
	v_cmp_lt_i32_e32 vcc, v98, v127
	s_waitcnt lgkmcnt(0)
	v_mfma_f32_16x16x32_bf16 v[18:21], v[26:29], v[22:25], v[18:21]
	v_cndmask_b32_e32 v104, v96, v97, vcc
	v_mul_f32_e32 v103, v104, v103
	v_sub_u32_e32 v104, v98, v128
	v_sub_u32_e32 v105, 0, v104
	v_max_i32_e32 v104, v104, v105
	v_cvt_f32_u32_e32 v104, v104
	ds_read_b128 v[26:29], v130 offset:50048
	v_cmp_lt_i32_e32 vcc, v98, v128
	s_waitcnt lgkmcnt(0)
	v_mfma_f32_16x16x32_bf16 v[22:25], v[26:29], v[22:25], v[12:15]
	v_cndmask_b32_e32 v105, v96, v97, vcc
	v_mul_f32_e32 v104, v105, v104
	v_sub_u32_e32 v105, v98, v129
	v_sub_u32_e32 v106, 0, v105
	v_max_i32_e32 v105, v105, v106
	v_cvt_f32_u32_e32 v105, v105
	v_cmp_lt_i32_e32 vcc, v98, v129
	ds_read_b128 v[12:15], v130 offset:37056
	v_mul_f32_e32 v94, 0xbfb8aa3b, v94
	v_cndmask_b32_e32 v106, v96, v97, vcc
	v_mul_f32_e32 v105, v106, v105
	v_mul_f32_e32 v95, 0xbfb8aa3b, v95
	v_mul_f32_e32 v100, 0xbfb8aa3b, v100
	v_mul_f32_e32 v101, 0xbfb8aa3b, v101
	v_mul_f32_e32 v102, 0xbfb8aa3b, v102
	v_mul_f32_e32 v103, 0xbfb8aa3b, v103
	v_mul_f32_e32 v104, 0xbfb8aa3b, v104
	v_mul_f32_e32 v105, 0xbfb8aa3b, v105
	v_exp_f32_e32 v94, v94
	v_exp_f32_e32 v95, v95
	v_exp_f32_e32 v100, v100
	v_exp_f32_e32 v101, v101
	v_exp_f32_e32 v102, v102
	v_exp_f32_e32 v103, v103
	v_exp_f32_e32 v104, v104
	v_exp_f32_e32 v105, v105
	v_pk_mul_f32 v[38:39], v[94:95], v[38:39]
	v_pk_mul_f32 v[34:35], v[102:103], v[34:35]
	v_pk_mul_f32 v[40:41], v[100:101], v[40:41]
	v_pk_mul_f32 v[2:3], v[104:105], v[36:37]
	v_cvt_pk_bf16_f32 v26, v38, v39
	v_cvt_pk_bf16_f32 v27, v40, v41
	v_cvt_pk_bf16_f32 v28, v34, v35
	v_cvt_pk_bf16_f32 v29, v2, v3
	s_waitcnt lgkmcnt(0)
	s_nop 0
	v_mfma_f32_16x16x32_bf16 v[14:17], v[12:15], v[26:29], v[8:11]
	s_nop 2
	ds_read_b128 v[8:11], v130 offset:41408
	s_waitcnt lgkmcnt(0)
	v_mfma_f32_16x16x32_bf16 v[10:13], v[8:11], v[26:29], v[4:7]
	s_nop 2
	ds_read_b128 v[2:5], v130 offset:45760
	s_waitcnt lgkmcnt(0)
	v_mfma_f32_16x16x32_bf16 v[6:9], v[2:5], v[26:29], v[18:21]
	ds_read_b128 v[2:5], v130 offset:50112
	s_nop 6
	v_pk_mul_f32 v[20:21], v[6:7], v[6:7]
	s_waitcnt lgkmcnt(0)
	v_mfma_f32_16x16x32_bf16 v[2:5], v[2:5], v[26:29], v[22:25]
	s_nop 2
	v_mul_f32_e32 v22, v15, v15
	v_fmac_f32_e32 v22, v14, v14
	v_fmac_f32_e32 v22, v16, v16
	v_fmac_f32_e32 v22, v17, v17
	v_fmac_f32_e32 v22, v10, v10
	v_fmac_f32_e32 v22, v11, v11
	v_fmac_f32_e32 v22, v12, v12
	v_fmac_f32_e32 v22, v13, v13
	v_add_f32_e32 v20, v20, v22
	v_pk_mul_f32 v[18:19], v[8:9], v[8:9]
	v_add_f32_e32 v20, v21, v20
	v_add_f32_e32 v18, v18, v20
	v_add_f32_e32 v22, v19, v18
	v_pk_mul_f32 v[20:21], v[2:3], v[2:3]
	v_pk_mul_f32 v[18:19], v[4:5], v[4:5]
	v_add_f32_e32 v20, v20, v22
	v_add_f32_e32 v20, v21, v20
	v_add_f32_e32 v18, v18, v20
	v_mad_i64_i32 v[20:21], s[4:5], v98, s33, v[82:83]
	v_lshl_add_u64 v[20:21], v[20:21], 0, v[84:85]
	v_lshl_add_u64 v[20:21], v[20:21], 0, v[0:1]
	global_load_dwordx2 v[22:23], v[20:21], off offset:1536
	v_add_f32_e32 v18, v19, v18
	ds_bpermute_b32 v19, v131, v18
	s_waitcnt lgkmcnt(0)
	v_add_f32_e32 v18, v18, v19
	ds_bpermute_b32 v19, v132, v18
	s_waitcnt lgkmcnt(0)
	v_add_f32_e32 v18, v18, v19
	v_fmamk_f32 v18, v18, 0x3c800000, v158
	v_cmp_gt_f32_e32 vcc, s8, v18
	v_mul_f32_e32 v19, 0x4b800000, v18
	s_waitcnt vmcnt(0)
	v_lshlrev_b32_e32 v24, 16, v22
	v_mul_f32_e32 v0, 0xbfb8aa3b, v24
	v_exp_f32_e32 v0, v0
	v_and_b32_e32 v25, 0xffff0000, v22
	v_cndmask_b32_e32 v18, v18, v19, vcc
	v_rsq_f32_e32 v18, v18
	v_add_f32_e32 v0, 1.0, v0
	v_rcp_f32_e32 v26, v0
	v_mul_f32_e32 v0, 0xbfb8aa3b, v25
	v_exp_f32_e32 v0, v0
	v_lshlrev_b32_e32 v22, 16, v23
	v_mul_f32_e32 v19, 0x45800000, v18
	v_cndmask_b32_e32 v18, v18, v19, vcc
	v_add_f32_e32 v0, 1.0, v0
	v_rcp_f32_e32 v27, v0
	v_mul_f32_e32 v0, 0xbfb8aa3b, v22
	v_exp_f32_e32 v0, v0
	v_and_b32_e32 v23, 0xffff0000, v23
	v_pk_mul_f32 v[24:25], v[26:27], v[24:25]
	v_add_f32_e32 v0, 1.0, v0
	v_pk_mul_f32 v[24:25], v[24:25], v[18:19] op_sel_hi:[1,0]
	s_nop 0
	v_pk_mul_f32 v[14:15], v[14:15], v[24:25]
	v_rcp_f32_e32 v24, v0
	v_mul_f32_e32 v0, 0xbfb8aa3b, v23
	v_exp_f32_e32 v0, v0
	v_cvt_pk_bf16_f32 v14, v14, v15
	v_add_f32_e32 v0, 1.0, v0
	v_rcp_f32_e32 v25, v0
	s_nop 0
	v_pk_mul_f32 v[22:23], v[24:25], v[22:23]
	s_nop 0
	v_pk_mul_f32 v[22:23], v[22:23], v[18:19] op_sel_hi:[1,0]
	s_nop 0
	v_pk_mul_f32 v[16:17], v[16:17], v[22:23]
	s_nop 0
	v_cvt_pk_bf16_f32 v15, v16, v17
	global_store_dwordx2 v[20:21], v[14:15], off offset:1536
	global_load_dwordx2 v[14:15], v[20:21], off offset:1568
	s_waitcnt vmcnt(0) lgkmcnt(0)
	v_lshlrev_b32_e32 v16, 16, v14
	v_mul_f32_e32 v0, 0xbfb8aa3b, v16
	v_exp_f32_e32 v0, v0
	v_and_b32_e32 v17, 0xffff0000, v14
	v_lshlrev_b32_e32 v14, 16, v15
	v_and_b32_e32 v15, 0xffff0000, v15
	v_add_f32_e32 v0, 1.0, v0
	v_rcp_f32_e32 v22, v0
	v_mul_f32_e32 v0, 0xbfb8aa3b, v17
	v_exp_f32_e32 v0, v0
	s_nop 0
	v_add_f32_e32 v0, 1.0, v0
	v_rcp_f32_e32 v23, v0
	v_mul_f32_e32 v0, 0xbfb8aa3b, v14
	v_exp_f32_e32 v0, v0
	v_pk_mul_f32 v[16:17], v[22:23], v[16:17]
	s_nop 0
	v_pk_mul_f32 v[16:17], v[16:17], v[18:19] op_sel_hi:[1,0]
	v_add_f32_e32 v0, 1.0, v0
	v_pk_mul_f32 v[10:11], v[10:11], v[16:17]
	v_rcp_f32_e32 v16, v0
	v_mul_f32_e32 v0, 0xbfb8aa3b, v15
	v_exp_f32_e32 v0, v0
	v_cvt_pk_bf16_f32 v10, v10, v11
	v_add_f32_e32 v0, 1.0, v0
	v_rcp_f32_e32 v17, v0
	s_nop 0
	v_pk_mul_f32 v[14:15], v[16:17], v[14:15]
	s_nop 0
	v_pk_mul_f32 v[14:15], v[14:15], v[18:19] op_sel_hi:[1,0]
	s_nop 0
	v_pk_mul_f32 v[12:13], v[12:13], v[14:15]
	s_nop 0
	v_cvt_pk_bf16_f32 v11, v12, v13
	global_store_dwordx2 v[20:21], v[10:11], off offset:1568
	global_load_dwordx2 v[10:11], v[20:21], off offset:1600
	s_waitcnt vmcnt(0) lgkmcnt(0)
	v_lshlrev_b32_e32 v12, 16, v10
	v_mul_f32_e32 v0, 0xbfb8aa3b, v12
	v_exp_f32_e32 v0, v0
	v_and_b32_e32 v13, 0xffff0000, v10
	v_lshlrev_b32_e32 v10, 16, v11
	v_and_b32_e32 v11, 0xffff0000, v11
	v_add_f32_e32 v0, 1.0, v0
	v_rcp_f32_e32 v14, v0
	v_mul_f32_e32 v0, 0xbfb8aa3b, v13
	v_exp_f32_e32 v0, v0
	s_nop 0
	v_add_f32_e32 v0, 1.0, v0
	v_rcp_f32_e32 v15, v0
	v_mul_f32_e32 v0, 0xbfb8aa3b, v10
	v_exp_f32_e32 v0, v0
	v_pk_mul_f32 v[12:13], v[14:15], v[12:13]
	s_nop 0
	v_pk_mul_f32 v[12:13], v[12:13], v[18:19] op_sel_hi:[1,0]
	v_add_f32_e32 v0, 1.0, v0
	v_pk_mul_f32 v[6:7], v[6:7], v[12:13]
	v_rcp_f32_e32 v12, v0
	v_mul_f32_e32 v0, 0xbfb8aa3b, v11
	v_exp_f32_e32 v0, v0
	v_cvt_pk_bf16_f32 v6, v6, v7
	v_add_f32_e32 v0, 1.0, v0
	v_rcp_f32_e32 v13, v0
	s_nop 0
	v_pk_mul_f32 v[10:11], v[12:13], v[10:11]
	s_nop 0
	v_pk_mul_f32 v[10:11], v[10:11], v[18:19] op_sel_hi:[1,0]
	s_nop 0
	v_pk_mul_f32 v[8:9], v[8:9], v[10:11]
	s_nop 0
	v_cvt_pk_bf16_f32 v7, v8, v9
	global_store_dwordx2 v[20:21], v[6:7], off offset:1600
	global_load_dwordx2 v[6:7], v[20:21], off offset:1632
	s_waitcnt vmcnt(0) lgkmcnt(0)
	v_lshlrev_b32_e32 v8, 16, v6
	v_mul_f32_e32 v0, 0xbfb8aa3b, v8
	v_exp_f32_e32 v0, v0
	v_and_b32_e32 v9, 0xffff0000, v6
	v_lshlrev_b32_e32 v6, 16, v7
	v_and_b32_e32 v7, 0xffff0000, v7
	v_add_f32_e32 v0, 1.0, v0
	v_rcp_f32_e32 v10, v0
	v_mul_f32_e32 v0, 0xbfb8aa3b, v9
	v_exp_f32_e32 v0, v0
	s_nop 0
	v_add_f32_e32 v0, 1.0, v0
	v_rcp_f32_e32 v11, v0
	v_mul_f32_e32 v0, 0xbfb8aa3b, v6
	v_exp_f32_e32 v0, v0
	v_pk_mul_f32 v[8:9], v[10:11], v[8:9]
	s_nop 0
	v_pk_mul_f32 v[8:9], v[18:19], v[8:9] op_sel_hi:[0,1]
	v_add_f32_e32 v0, 1.0, v0
	v_pk_mul_f32 v[2:3], v[2:3], v[8:9]
	v_rcp_f32_e32 v8, v0
	v_mul_f32_e32 v0, 0xbfb8aa3b, v7
	v_exp_f32_e32 v0, v0
	v_cvt_pk_bf16_f32 v2, v2, v3
	v_add_f32_e32 v0, 1.0, v0
	v_rcp_f32_e32 v9, v0
	s_nop 0
	v_pk_mul_f32 v[6:7], v[8:9], v[6:7]
	s_nop 0
	v_pk_mul_f32 v[6:7], v[18:19], v[6:7] op_sel_hi:[0,1]
	v_pk_mul_f32 v[4:5], v[4:5], v[6:7]
	s_nop 0
	v_cvt_pk_bf16_f32 v3, v4, v5
	global_store_dwordx2 v[20:21], v[2:3], off offset:1632
